# attention loop: bookkeeping moved ahead of the per-tile barrier; retention output unit: decay and GroupNorm weight loads issued early so their round trips overlap
# baseline (speedup 1.0000x reference)
;   #define RESC() do{ if(resc){ asm volatile("s_waitcnt lgkmcnt(0)":::"memory"); \
;       _Pragma("unroll") for(int d_=0;d_<2;++d_) _Pragma("unroll") for(int r=0;r<16;++r)o[d_][r]*=wsf[crow(r,hi)]; } }while(0)
;   #define ROT() do{sl_prev=sl_cur;sl_cur=sl_next;sl_next=(sl_next==(NSLOT-1)*SLOTB)?0:sl_next+SLOTB;}while(0)
;   #define WAIT_STEADY() WAIT_BAR(3)
;   #define WAIT_STEADY() WAIT_BAR(2)
; template<int THRL,bool NOMAX> __device__ __forceinline__ void attn_unit(int b,int h,int qb,int t0,const bf16*Q,const bf16*__restrict__ KV,const bf16*__restrict__ GA,bf16*O,char*shm){
;     ...
;     STEP(pB0,pB1,pA0,pA1,t,true,true,true);     WAIT_STEADY(); RESC(); ROT();
;     STEP(pA0,pA1,pB0,pB1,t+1,true,true,true);   WAIT_STEADY(); RESC(); ROT();
.LBB0_479:
	v_add_u32_e32 v179, s16, v2
	ds_read_b64_tr_b16 v[198:199], v179 offset:24576
	ds_read_b64_tr_b16 v[200:201], v179 offset:25088
	v_add_f32_e32 v88, v68, v69
	v_add_f32_e32 v88, v70, v88
	v_add_f32_e32 v88, v71, v88
	v_add_f32_e32 v88, v72, v88
	v_add_f32_e32 v88, v73, v88
	v_cvt_pk_bf16_f32 v160, v68, v69
	v_cvt_pk_bf16_f32 v161, v70, v71
	v_mfma_f32_32x32x16_bf16 v[100:115], v[84:87], v[152:155], v[36:51]
	ds_read_b64_tr_b16 v[202:203], v179 offset:28672
	ds_read_b64_tr_b16 v[204:205], v179 offset:29184
	v_add_f32_e32 v68, v74, v88
	v_mfma_f32_32x32x16_bf16 v[84:99], v[168:171], v[152:155], v[36:51]
	v_add_f32_e32 v68, v75, v68
	v_add_f32_e32 v68, v76, v68
	v_add_f32_e32 v140, v77, v68
	v_cvt_pk_bf16_f32 v162, v72, v73
	v_cvt_pk_bf16_f32 v163, v74, v75
	ds_read_b64_tr_b16 v[68:69], v179 offset:25600
	ds_read_b64_tr_b16 v[70:71], v179 offset:26112
	v_add_f32_e32 v72, v78, v140
	v_add_f32_e32 v72, v79, v72
	v_add_f32_e32 v72, v80, v72
	v_add_f32_e32 v140, v81, v72
	v_cvt_pk_bf16_f32 v156, v76, v77
	v_cvt_pk_bf16_f32 v157, v78, v79
	v_mfma_f32_32x32x16_bf16 v[100:115], v[172:175], v[144:147], v[100:115]
	ds_read_b64_tr_b16 v[72:73], v179 offset:29696
	ds_read_b64_tr_b16 v[74:75], v179 offset:30208
	v_mfma_f32_32x32x16_bf16 v[84:99], v[164:167], v[144:147], v[84:99]
	v_add_f32_e32 v76, v82, v140
	v_add_f32_e32 v76, v83, v76
	v_add_f32_e32 v76, v52, v76
	v_add_f32_e32 v140, v53, v76
	v_cvt_pk_bf16_f32 v158, v80, v81
	v_cvt_pk_bf16_f32 v159, v82, v83
	ds_read_b64_tr_b16 v[76:77], v179 offset:26624
	ds_read_b64_tr_b16 v[78:79], v179 offset:27136
	v_add_f32_e32 v80, v54, v140
	v_add_f32_e32 v80, v55, v80
	v_add_f32_e32 v80, v56, v80
	v_add_f32_e32 v80, v57, v80
	v_cvt_pk_bf16_f32 v148, v52, v53
	v_cvt_pk_bf16_f32 v149, v54, v55
	v_mfma_f32_32x32x16_bf16 v[100:115], v[128:131], v[136:139], v[100:115]
	ds_read_b64_tr_b16 v[52:53], v179 offset:30720
	ds_read_b64_tr_b16 v[54:55], v179 offset:31232
	v_mfma_f32_32x32x16_bf16 v[84:99], v[124:127], v[136:139], v[84:99]
	v_add_f32_e32 v80, v58, v80
	v_add_f32_e32 v80, v59, v80
	v_add_f32_e32 v80, v60, v80
	v_add_f32_e32 v80, v61, v80
	v_cvt_pk_bf16_f32 v150, v56, v57
	v_cvt_pk_bf16_f32 v151, v58, v59
	ds_read_b64_tr_b16 v[56:57], v179 offset:27648
	ds_read_b64_tr_b16 v[58:59], v179 offset:28160
	v_add_f32_e32 v80, v62, v80
	v_add_f32_e32 v80, v63, v80
	v_add_f32_e32 v80, v64, v80
	v_add_f32_e32 v80, v65, v80
	v_cvt_pk_bf16_f32 v140, v60, v61
	v_cvt_pk_bf16_f32 v141, v62, v63
	v_mfma_f32_32x32x16_bf16 v[100:115], v[120:123], v[132:135], v[100:115]
	ds_read_b64_tr_b16 v[60:61], v179 offset:31744
	ds_read_b64_tr_b16 v[62:63], v179 offset:32256
	v_mfma_f32_32x32x16_bf16 v[84:99], v[116:119], v[132:135], v[84:99]
	v_add_f32_e32 v80, v66, v80
	v_add_f32_e32 v80, v67, v80
	v_add_f32_e32 v179, 0, v80
	v_cvt_pk_bf16_f32 v142, v64, v65
	v_cvt_pk_bf16_f32 v143, v66, v67
	s_add_i32 s16, s21, 0x4000
	s_and_b32 s16, s16, 0xfc000
	s_lshl_b32 s16, s16, 1
	v_lshl_add_u64 v[64:65], v[182:183], 0, s[16:17]
	s_add_i32 m0, s22, s9
	s_add_i32 s16, s20, 0xffff4000
	global_load_lds_dwordx4 v[64:65], off
	s_and_b32 s16, s16, 0xfc000
	s_lshl_b32 s16, s16, 1
	v_lshl_add_u64 v[64:65], v[180:181], 0, s[16:17]
	s_add_i32 m0, s15, s8
	s_nop 0
	global_load_lds_dwordx4 v[64:65], off
	s_waitcnt lgkmcnt(4)
	v_mfma_f32_32x32x16_bf16 v[4:19], v[160:163], v[198:201], v[4:19]
	v_exp_f32_e32 v100, v100
	v_exp_f32_e32 v101, v101
	v_exp_f32_e32 v102, v102
	v_exp_f32_e32 v103, v103
	v_mfma_f32_32x32x16_bf16 v[20:35], v[160:163], v[202:205], v[20:35]
	v_exp_f32_e32 v104, v104
	v_exp_f32_e32 v105, v105
	v_exp_f32_e32 v106, v106
	v_exp_f32_e32 v107, v107
	v_add_u32_e32 v80, s15, v189
	ds_read_b128 v[64:67], v80
	ds_read_b128 v[120:123], v80 offset:512
	v_mfma_f32_32x32x16_bf16 v[4:19], v[156:159], v[68:71], v[4:19]
	v_exp_f32_e32 v108, v108
	v_exp_f32_e32 v109, v109
	v_exp_f32_e32 v110, v110
	v_exp_f32_e32 v111, v111
	ds_read_b128 v[124:127], v80 offset:2048
	ds_read_b128 v[128:131], v80 offset:2560
	v_mfma_f32_32x32x16_bf16 v[20:35], v[156:159], v[72:75], v[20:35]
	v_exp_f32_e32 v112, v112
	v_exp_f32_e32 v113, v113
	v_exp_f32_e32 v114, v114
	v_exp_f32_e32 v115, v115
	ds_read_b128 v[164:167], v80 offset:4096
	ds_read_b128 v[168:171], v80 offset:4608
	v_mfma_f32_32x32x16_bf16 v[4:19], v[148:151], v[76:79], v[4:19]
	v_exp_f32_e32 v84, v84
	v_exp_f32_e32 v85, v85
	v_exp_f32_e32 v86, v86
	v_exp_f32_e32 v87, v87
	ds_read_b128 v[172:175], v80 offset:6144
	ds_read_b128 v[116:119], v80 offset:6656
	v_mfma_f32_32x32x16_bf16 v[20:35], v[148:151], v[52:55], v[20:35]
	v_exp_f32_e32 v88, v88
	v_exp_f32_e32 v89, v89
	v_exp_f32_e32 v90, v90
	v_exp_f32_e32 v91, v91
	s_waitcnt lgkmcnt(8)
	v_mfma_f32_32x32x16_bf16 v[4:19], v[140:143], v[56:59], v[4:19]
	v_exp_f32_e32 v92, v92
	v_exp_f32_e32 v93, v93
	v_exp_f32_e32 v94, v94
	v_exp_f32_e32 v95, v95
	v_mfma_f32_32x32x16_bf16 v[20:35], v[140:143], v[60:63], v[20:35]
	v_exp_f32_e32 v96, v96
	v_exp_f32_e32 v97, v97
	v_exp_f32_e32 v98, v98
	v_exp_f32_e32 v99, v99
	s_add_i32 s16, s15, 0x2000
	s_cmpk_lg_i32 s15, 0x4000
	s_cselect_b32 s23, s16, 0
	v_add_u32_e32 v190, s22, v2
	s_waitcnt vmcnt(2) lgkmcnt(0)
	s_barrier
;   #define RESC() do{ if(resc){ asm volatile("s_waitcnt lgkmcnt(0)":::"memory"); \
;       _Pragma("unroll") for(int d_=0;d_<2;++d_) _Pragma("unroll") for(int r=0;r<16;++r)o[d_][r]*=wsf[crow(r,hi)]; } }while(0)
;   #define ROT() do{sl_prev=sl_cur;sl_cur=sl_next;sl_next=(sl_next==(NSLOT-1)*SLOTB)?0:sl_next+SLOTB;}while(0)
;   #define WAIT_STEADY() WAIT_BAR(3)
;   #define WAIT_STEADY() WAIT_BAR(2)
; template<int THRL,bool NOMAX> __device__ __forceinline__ void attn_unit(int b,int h,int qb,int t0,const bf16*Q,const bf16*__restrict__ KV,const bf16*__restrict__ GA,bf16*O,char*shm){
;     ...
;   for(;t+5<NT;t+=2){
;     STEP(pB0,pB1,pA0,pA1,t,true,true,true);     WAIT_STEADY(); RESC(); ROT();
;     STEP(pA0,pA1,pB0,pB1,t+1,true,true,true);   WAIT_STEADY(); RESC(); ROT();
;   }
	ds_read_b64_tr_b16 v[198:199], v190 offset:24576
	ds_read_b64_tr_b16 v[200:201], v190 offset:25088
	v_mfma_f32_32x32x16_bf16 v[68:83], v[64:67], v[152:155], v[36:51]
	v_add_f32_e32 v52, v100, v101
	v_add_f32_e32 v52, v102, v52
	v_add_f32_e32 v52, v103, v52
	v_add_f32_e32 v52, v104, v52
	v_add_f32_e32 v52, v105, v52
	v_cvt_pk_bf16_f32 v160, v100, v101
	v_cvt_pk_bf16_f32 v161, v102, v103
	ds_read_b64_tr_b16 v[202:203], v190 offset:28672
	ds_read_b64_tr_b16 v[204:205], v190 offset:29184
	v_add_f32_e32 v52, v106, v52
	v_add_f32_e32 v52, v107, v52
	v_add_f32_e32 v52, v108, v52
	v_add_f32_e32 v140, v109, v52
	v_mfma_f32_32x32x16_bf16 v[52:67], v[120:123], v[152:155], v[36:51]
	v_cvt_pk_bf16_f32 v162, v104, v105
	v_cvt_pk_bf16_f32 v163, v106, v107
	ds_read_b64_tr_b16 v[100:101], v190 offset:25600
	ds_read_b64_tr_b16 v[102:103], v190 offset:26112
	v_mfma_f32_32x32x16_bf16 v[68:83], v[124:127], v[144:147], v[68:83]
	v_add_f32_e32 v104, v110, v140
	v_add_f32_e32 v104, v111, v104
	v_add_f32_e32 v104, v112, v104
	v_add_f32_e32 v120, v113, v104
	v_cvt_pk_bf16_f32 v156, v108, v109
	v_cvt_pk_bf16_f32 v157, v110, v111
	ds_read_b64_tr_b16 v[104:105], v190 offset:29696
	ds_read_b64_tr_b16 v[106:107], v190 offset:30208
	v_mfma_f32_32x32x16_bf16 v[52:67], v[128:131], v[144:147], v[52:67]
	v_add_f32_e32 v108, v114, v120
	v_add_f32_e32 v108, v115, v108
	v_add_f32_e32 v108, v84, v108
	v_add_f32_e32 v120, v85, v108
	v_cvt_pk_bf16_f32 v158, v112, v113
	v_cvt_pk_bf16_f32 v159, v114, v115
	ds_read_b64_tr_b16 v[108:109], v190 offset:26624
	ds_read_b64_tr_b16 v[110:111], v190 offset:27136
	v_mfma_f32_32x32x16_bf16 v[68:83], v[164:167], v[136:139], v[68:83]
	v_add_f32_e32 v112, v86, v120
	v_add_f32_e32 v112, v87, v112
	v_add_f32_e32 v112, v88, v112
	v_add_f32_e32 v120, v89, v112
	v_cvt_pk_bf16_f32 v148, v84, v85
	v_cvt_pk_bf16_f32 v149, v86, v87
	ds_read_b64_tr_b16 v[112:113], v190 offset:30720
	ds_read_b64_tr_b16 v[114:115], v190 offset:31232
	v_mfma_f32_32x32x16_bf16 v[52:67], v[168:171], v[136:139], v[52:67]
	v_add_f32_e32 v84, v90, v120
	v_add_f32_e32 v84, v91, v84
	v_add_f32_e32 v84, v92, v84
	v_add_f32_e32 v84, v93, v84
	v_cvt_pk_bf16_f32 v150, v88, v89
	v_cvt_pk_bf16_f32 v151, v90, v91
	ds_read_b64_tr_b16 v[88:89], v190 offset:27648
	ds_read_b64_tr_b16 v[90:91], v190 offset:28160
	v_mfma_f32_32x32x16_bf16 v[68:83], v[172:175], v[132:135], v[68:83]
	v_add_f32_e32 v84, v94, v84
	v_add_f32_e32 v84, v95, v84
	v_add_f32_e32 v84, v96, v84
	v_add_f32_e32 v84, v97, v84
	v_cvt_pk_bf16_f32 v140, v92, v93
	v_cvt_pk_bf16_f32 v141, v94, v95
	ds_read_b64_tr_b16 v[92:93], v190 offset:31744
	ds_read_b64_tr_b16 v[94:95], v190 offset:32256
	v_mfma_f32_32x32x16_bf16 v[52:67], v[116:119], v[132:135], v[52:67]
	v_add_f32_e32 v84, v98, v84
	v_add_f32_e32 v84, v99, v84
	v_add_f32_e32 v190, 0, v84
	v_cvt_pk_bf16_f32 v142, v96, v97
	v_cvt_pk_bf16_f32 v143, v98, v99
	s_and_b32 s16, s20, 0xfc000
	s_lshl_b32 s16, s16, 1
	v_lshl_add_u64 v[84:85], v[182:183], 0, s[16:17]
	s_add_i32 m0, s15, s9
	s_and_b32 s16, s21, 0xfc000
	global_load_lds_dwordx4 v[84:85], off
	s_lshl_b32 s16, s16, 1
	v_lshl_add_u64 v[84:85], v[180:181], 0, s[16:17]
	s_add_i32 m0, s23, s8
	s_nop 0
	global_load_lds_dwordx4 v[84:85], off
	s_waitcnt lgkmcnt(4)
	v_mfma_f32_32x32x16_bf16 v[4:19], v[160:163], v[198:201], v[4:19]
	v_exp_f32_e32 v68, v68
	v_exp_f32_e32 v69, v69
	v_exp_f32_e32 v70, v70
	v_exp_f32_e32 v71, v71
	v_mfma_f32_32x32x16_bf16 v[20:35], v[160:163], v[202:205], v[20:35]
	v_exp_f32_e32 v72, v72
	v_exp_f32_e32 v73, v73
	v_exp_f32_e32 v74, v74
	v_exp_f32_e32 v75, v75
	v_add_u32_e32 v96, s23, v189
	ds_read_b128 v[84:87], v96
	ds_read_b128 v[168:171], v96 offset:512
	v_mfma_f32_32x32x16_bf16 v[4:19], v[156:159], v[100:103], v[4:19]
	v_exp_f32_e32 v76, v76
	v_exp_f32_e32 v77, v77
	v_exp_f32_e32 v78, v78
	v_exp_f32_e32 v79, v79
	ds_read_b128 v[172:175], v96 offset:2048
	ds_read_b128 v[164:167], v96 offset:2560
	v_mfma_f32_32x32x16_bf16 v[20:35], v[156:159], v[104:107], v[20:35]
	v_exp_f32_e32 v80, v80
	v_exp_f32_e32 v81, v81
	v_exp_f32_e32 v82, v82
	v_exp_f32_e32 v83, v83
	ds_read_b128 v[128:131], v96 offset:4096
	ds_read_b128 v[124:127], v96 offset:4608
	v_mfma_f32_32x32x16_bf16 v[4:19], v[148:151], v[108:111], v[4:19]
	v_exp_f32_e32 v52, v52
	v_exp_f32_e32 v53, v53
	v_exp_f32_e32 v54, v54
	v_exp_f32_e32 v55, v55
	ds_read_b128 v[120:123], v96 offset:6144
	ds_read_b128 v[116:119], v96 offset:6656
	v_mfma_f32_32x32x16_bf16 v[20:35], v[148:151], v[112:115], v[20:35]
	v_exp_f32_e32 v56, v56
	v_exp_f32_e32 v57, v57
	v_exp_f32_e32 v58, v58
	v_exp_f32_e32 v59, v59
	s_waitcnt lgkmcnt(8)
	v_mfma_f32_32x32x16_bf16 v[4:19], v[140:143], v[88:91], v[4:19]
	v_exp_f32_e32 v60, v60
	v_exp_f32_e32 v61, v61
	v_exp_f32_e32 v62, v62
	v_exp_f32_e32 v63, v63
	v_mfma_f32_32x32x16_bf16 v[20:35], v[140:143], v[92:95], v[20:35]
	v_exp_f32_e32 v64, v64
	v_exp_f32_e32 v65, v65
	v_exp_f32_e32 v66, v66
	v_exp_f32_e32 v67, v67
	s_add_i32 s26, s23, 0x2000
	s_cmpk_lg_i32 s23, 0x4000
	v_add_f32_e32 v88, v191, v179
	s_mov_b32 s16, s15
	s_cselect_b32 s15, s26, 0
	s_add_i32 s14, s14, 2
	s_add_i32 s21, s21, 0x8000
	s_add_i32 s20, s20, 0x8000
	s_mov_b32 s22, s23
	v_add_f32_e32 v191, v88, v190
	s_cmp_gt_u32 s14, 56
	s_waitcnt vmcnt(2) lgkmcnt(0)
	s_barrier
	s_cbranch_scc0 .LBB0_479
;   #define RESC() do{ if(resc){ asm volatile("s_waitcnt lgkmcnt(0)":::"memory"); \
;       _Pragma("unroll") for(int d_=0;d_<2;++d_) _Pragma("unroll") for(int r=0;r<16;++r)o[d_][r]*=wsf[crow(r,hi)]; } }while(0)
;   #define ROT() do{sl_prev=sl_cur;sl_cur=sl_next;sl_next=(sl_next==(NSLOT-1)*SLOTB)?0:sl_next+SLOTB;}while(0)
;   #define ENDW(tt) do{ if((tt)+3<NT){WAIT_BAR(2);} else if((tt)+2<NT){WAIT_BAR(1);} else {WAIT_BAR(0);} }while(0)
; template<int THRL,bool NOMAX> __device__ __forceinline__ void attn_unit(int b,int h,int qb,int t0,const bf16*Q,const bf16*__restrict__ KV,const bf16*__restrict__ GA,bf16*O,char*shm){
;     ...
;   for(;t+1<NT;t+=2){
;     STEP(pB0,pB1,pA0,pA1,t,(t+3<NT),(t+1<NT),(t+1<NT));       ENDW(t);   RESC(); ROT();
;     STEP(pA0,pA1,pB0,pB1,t+1,(t+4<NT),(t+2<NT),(t+2<NT));     ENDW(t+1); RESC(); ROT();
;   }
	s_and_b32 s12, s12, 0x3fffffc0
	s_cmp_lg_u32 0, -1
	s_cselect_b32 s14, 0, 0
	s_add_i32 s15, s14, 0x6000
	s_lshl_b32 s12, s12, 2
	v_add_u32_e32 v88, s15, v177
	s_add_i32 s12, s12, 0
	v_add3_u32 v190, v88, v176, v178
	ds_read_b64_tr_b16 v[198:199], v2 offset:32768
	ds_read_b64_tr_b16 v[200:201], v2 offset:33280
	v_add_f32_e32 v88, v68, v69
	v_add_f32_e32 v88, v70, v88
	v_add_f32_e32 v88, v71, v88
	v_add_f32_e32 v88, v72, v88
	v_add_f32_e32 v88, v73, v88
	v_cvt_pk_bf16_f32 v160, v68, v69
	v_cvt_pk_bf16_f32 v161, v70, v71
	s_waitcnt lgkmcnt(9)
	v_mfma_f32_32x32x16_bf16 v[100:115], v[84:87], v[152:155], v[36:51]
	ds_read_b64_tr_b16 v[176:177], v2 offset:36864
	ds_read_b64_tr_b16 v[178:179], v2 offset:37376
	v_add_f32_e32 v68, v74, v88
	v_add_f32_e32 v68, v75, v68
	v_add_f32_e32 v68, v76, v68
	v_add_f32_e32 v140, v77, v68
	v_cvt_pk_bf16_f32 v162, v72, v73
	v_cvt_pk_bf16_f32 v163, v74, v75
	s_waitcnt lgkmcnt(10)
	v_mfma_f32_32x32x16_bf16 v[84:99], v[168:171], v[152:155], v[36:51]
	ds_read_b64_tr_b16 v[68:69], v2 offset:33792
	ds_read_b64_tr_b16 v[70:71], v2 offset:34304
	v_add_f32_e32 v72, v78, v140
	v_add_f32_e32 v72, v79, v72
	v_add_f32_e32 v72, v80, v72
	v_add_f32_e32 v140, v81, v72
	v_cvt_pk_bf16_f32 v156, v76, v77
	v_cvt_pk_bf16_f32 v157, v78, v79
	s_waitcnt lgkmcnt(11)
	v_mfma_f32_32x32x16_bf16 v[100:115], v[172:175], v[144:147], v[100:115]
	ds_read_b64_tr_b16 v[72:73], v2 offset:37888
	ds_read_b64_tr_b16 v[74:75], v2 offset:38400
	v_add_f32_e32 v76, v82, v140
	v_add_f32_e32 v76, v83, v76
	v_add_f32_e32 v76, v52, v76
	v_add_f32_e32 v140, v53, v76
	v_cvt_pk_bf16_f32 v158, v80, v81
	v_cvt_pk_bf16_f32 v159, v82, v83
	s_waitcnt lgkmcnt(12)
	v_mfma_f32_32x32x16_bf16 v[84:99], v[164:167], v[144:147], v[84:99]
	ds_read_b64_tr_b16 v[76:77], v2 offset:34816
	ds_read_b64_tr_b16 v[78:79], v2 offset:35328
	v_add_f32_e32 v80, v54, v140
	v_add_f32_e32 v80, v55, v80
	v_add_f32_e32 v80, v56, v80
	v_add_f32_e32 v80, v57, v80
	v_cvt_pk_bf16_f32 v148, v52, v53
	v_cvt_pk_bf16_f32 v149, v54, v55
	s_waitcnt lgkmcnt(13)
	v_mfma_f32_32x32x16_bf16 v[100:115], v[128:131], v[136:139], v[100:115]
	ds_read_b64_tr_b16 v[52:53], v2 offset:38912
	ds_read_b64_tr_b16 v[54:55], v2 offset:39424
	v_add_f32_e32 v80, v58, v80
	v_add_f32_e32 v80, v59, v80
	v_add_f32_e32 v80, v60, v80
	v_add_f32_e32 v80, v61, v80
	v_cvt_pk_bf16_f32 v150, v56, v57
	v_cvt_pk_bf16_f32 v151, v58, v59
	s_waitcnt lgkmcnt(14)
	v_mfma_f32_32x32x16_bf16 v[84:99], v[124:127], v[136:139], v[84:99]
	ds_read_b64_tr_b16 v[56:57], v2 offset:35840
	ds_read_b64_tr_b16 v[58:59], v2 offset:36352
	v_add_f32_e32 v80, v62, v80
	v_add_f32_e32 v80, v63, v80
	v_add_f32_e32 v80, v64, v80
	v_add_f32_e32 v80, v65, v80
	v_cvt_pk_bf16_f32 v140, v60, v61
	v_cvt_pk_bf16_f32 v141, v62, v63
	s_waitcnt lgkmcnt(14)
	v_mfma_f32_32x32x16_bf16 v[100:115], v[120:123], v[132:135], v[100:115]
	ds_read_b64_tr_b16 v[60:61], v2 offset:39936
	ds_read_b64_tr_b16 v[62:63], v2 offset:40448
	v_add_f32_e32 v80, v66, v80
	v_add_f32_e32 v80, v67, v80
	v_add_f32_e32 v80, 0, v80
	v_cvt_pk_bf16_f32 v142, v64, v65
	v_cvt_pk_bf16_f32 v143, v66, v67
	v_mfma_f32_32x32x16_bf16 v[84:99], v[116:119], v[132:135], v[84:99]
	v_readlane_b32 s20, v254, 56
	v_readlane_b32 s21, v254, 57
	s_mov_b32 s21, s17
	s_add_i32 s13, s14, s13
	v_lshl_add_u64 v[64:65], v[182:183], 0, s[20:21]
	s_add_i32 s14, s13, 0x4000
	s_mov_b32 s15, m0
	s_mov_b32 m0, s14
	s_nop 0
	global_load_lds_dwordx4 v[64:65], off
	s_mov_b32 m0, s15
	v_add_f32_e32 v191, v191, v80
	v_readlane_b32 s14, v254, 58
	v_readlane_b32 s15, v254, 59
	s_mov_b32 s15, s17
	s_mov_b32 s16, s14
	v_lshl_add_u64 v[64:65], v[180:181], 0, s[14:15]
	s_mov_b32 s14, m0
	s_mov_b32 m0, s8
	s_nop 0
	global_load_lds_dwordx4 v[64:65], off
	s_mov_b32 m0, s14
	v_writelane_b32 v254, s16, 58
	s_nop 1
	v_writelane_b32 v254, s17, 59
	s_waitcnt lgkmcnt(14)
	v_mfma_f32_32x32x16_bf16 v[4:19], v[160:163], v[198:201], v[4:19]
	v_exp_f32_e32 v100, v100
	v_exp_f32_e32 v101, v101
	v_exp_f32_e32 v102, v102
	v_exp_f32_e32 v103, v103
	s_waitcnt lgkmcnt(12)
	v_mfma_f32_32x32x16_bf16 v[20:35], v[160:163], v[176:179], v[20:35]
	v_exp_f32_e32 v104, v104
	v_exp_f32_e32 v105, v105
	v_exp_f32_e32 v106, v106
	v_exp_f32_e32 v107, v107
	ds_read_b128 v[64:67], v189
	ds_read_b128 v[80:83], v189 offset:512
	s_waitcnt lgkmcnt(12)
	v_mfma_f32_32x32x16_bf16 v[4:19], v[156:159], v[68:71], v[4:19]
	v_exp_f32_e32 v108, v108
	v_exp_f32_e32 v109, v109
	v_exp_f32_e32 v110, v110
	v_exp_f32_e32 v111, v111
	ds_read_b128 v[164:167], v189 offset:2048
	ds_read_b128 v[168:171], v189 offset:2560
	s_waitcnt lgkmcnt(12)
	v_mfma_f32_32x32x16_bf16 v[20:35], v[156:159], v[72:75], v[20:35]
	v_exp_f32_e32 v112, v112
	v_exp_f32_e32 v113, v113
	v_exp_f32_e32 v114, v114
	v_exp_f32_e32 v115, v115
	ds_read_b128 v[172:175], v189 offset:4096
	ds_read_b128 v[176:179], v189 offset:4608
	s_waitcnt lgkmcnt(12)
	v_mfma_f32_32x32x16_bf16 v[4:19], v[148:151], v[76:79], v[4:19]
	v_exp_f32_e32 v84, v84
	v_exp_f32_e32 v85, v85
	v_exp_f32_e32 v86, v86
	v_exp_f32_e32 v87, v87
	ds_read_b128 v[198:201], v189 offset:6144
	ds_read_b128 v[72:75], v189 offset:6656
	s_waitcnt lgkmcnt(12)
	v_mfma_f32_32x32x16_bf16 v[20:35], v[148:151], v[52:55], v[20:35]
	v_exp_f32_e32 v88, v88
	v_exp_f32_e32 v89, v89
	v_exp_f32_e32 v90, v90
	v_exp_f32_e32 v91, v91
	s_waitcnt lgkmcnt(10)
	v_mfma_f32_32x32x16_bf16 v[4:19], v[140:143], v[56:59], v[4:19]
	v_exp_f32_e32 v92, v92
	v_exp_f32_e32 v93, v93
	v_exp_f32_e32 v94, v94
	v_exp_f32_e32 v95, v95
	s_waitcnt lgkmcnt(8)
	v_mfma_f32_32x32x16_bf16 v[20:35], v[140:143], v[60:63], v[20:35]
	v_exp_f32_e32 v96, v96
	v_exp_f32_e32 v97, v97
	v_exp_f32_e32 v98, v98
	v_exp_f32_e32 v99, v99
	s_waitcnt vmcnt(2) lgkmcnt(0)
	s_barrier
;   #define RESC() do{ if(resc){ asm volatile("s_waitcnt lgkmcnt(0)":::"memory"); \
;       _Pragma("unroll") for(int d_=0;d_<2;++d_) _Pragma("unroll") for(int r=0;r<16;++r)o[d_][r]*=wsf[crow(r,hi)]; } }while(0)
;   #define ROT() do{sl_prev=sl_cur;sl_cur=sl_next;sl_next=(sl_next==(NSLOT-1)*SLOTB)?0:sl_next+SLOTB;}while(0)
;   #define ENDW(tt) do{ if((tt)+3<NT){WAIT_BAR(2);} else if((tt)+2<NT){WAIT_BAR(1);} else {WAIT_BAR(0);} }while(0)
; template<int THRL,bool NOMAX> __device__ __forceinline__ void attn_unit(int b,int h,int qb,int t0,const bf16*Q,const bf16*__restrict__ KV,const bf16*__restrict__ GA,bf16*O,char*shm){
;     ...
;   for(;t+1<NT;t+=2){
;     STEP(pB0,pB1,pA0,pA1,t,(t+3<NT),(t+1<NT),(t+1<NT));       ENDW(t);   RESC(); ROT();
;     STEP(pA0,pA1,pB0,pB1,t+1,(t+4<NT),(t+2<NT),(t+2<NT));     ENDW(t+1); RESC(); ROT();
;   }
	ds_read_b64_tr_b16 v[202:203], v2 offset:40960
	ds_read_b64_tr_b16 v[204:205], v2 offset:41472
	v_add_f32_e32 v52, v100, v101
	v_add_f32_e32 v52, v102, v52
	v_add_f32_e32 v52, v103, v52
	v_add_f32_e32 v52, v104, v52
	v_add_f32_e32 v52, v105, v52
	v_cvt_pk_bf16_f32 v160, v100, v101
	v_cvt_pk_bf16_f32 v161, v102, v103
	s_waitcnt lgkmcnt(9)
	v_mfma_f32_32x32x16_bf16 v[116:131], v[64:67], v[152:155], v[36:51]
	ds_read_b64_tr_b16 v[100:101], v2 offset:45056
	ds_read_b64_tr_b16 v[102:103], v2 offset:45568
	v_add_f32_e32 v52, v106, v52
	v_add_f32_e32 v52, v107, v52
	v_add_f32_e32 v52, v108, v52
	v_add_f32_e32 v76, v109, v52
	v_cvt_pk_bf16_f32 v162, v104, v105
	v_cvt_pk_bf16_f32 v163, v106, v107
	s_waitcnt lgkmcnt(10)
	v_mfma_f32_32x32x16_bf16 v[52:67], v[80:83], v[152:155], v[36:51]
	ds_read_b64_tr_b16 v[68:69], v2 offset:41984
	ds_read_b64_tr_b16 v[70:71], v2 offset:42496
	v_add_f32_e32 v76, v110, v76
	v_add_f32_e32 v76, v111, v76
	v_add_f32_e32 v76, v112, v76
	v_add_f32_e32 v80, v113, v76
	v_cvt_pk_bf16_f32 v156, v108, v109
	v_cvt_pk_bf16_f32 v157, v110, v111
	s_waitcnt lgkmcnt(11)
	v_mfma_f32_32x32x16_bf16 v[116:131], v[164:167], v[144:147], v[116:131]
	ds_read_b64_tr_b16 v[76:77], v2 offset:46080
	ds_read_b64_tr_b16 v[78:79], v2 offset:46592
	v_add_f32_e32 v80, v114, v80
	v_add_f32_e32 v80, v115, v80
	v_add_f32_e32 v80, v84, v80
	v_add_f32_e32 v104, v85, v80
	v_cvt_pk_bf16_f32 v158, v112, v113
	v_cvt_pk_bf16_f32 v159, v114, v115
	s_waitcnt lgkmcnt(12)
	v_mfma_f32_32x32x16_bf16 v[52:67], v[168:171], v[144:147], v[52:67]
	ds_read_b64_tr_b16 v[80:81], v2 offset:43008
	ds_read_b64_tr_b16 v[82:83], v2 offset:43520
	v_add_f32_e32 v104, v86, v104
	v_add_f32_e32 v104, v87, v104
	v_add_f32_e32 v104, v88, v104
	v_add_f32_e32 v108, v89, v104
	v_cvt_pk_bf16_f32 v148, v84, v85
	v_cvt_pk_bf16_f32 v149, v86, v87
	s_waitcnt lgkmcnt(13)
	v_mfma_f32_32x32x16_bf16 v[116:131], v[172:175], v[136:139], v[116:131]
	ds_read_b64_tr_b16 v[104:105], v2 offset:47104
	ds_read_b64_tr_b16 v[106:107], v2 offset:47616
	v_add_f32_e32 v84, v90, v108
	v_add_f32_e32 v84, v91, v84
	v_add_f32_e32 v84, v92, v84
	v_add_f32_e32 v84, v93, v84
	v_cvt_pk_bf16_f32 v150, v88, v89
	v_cvt_pk_bf16_f32 v151, v90, v91
	s_waitcnt lgkmcnt(14)
	v_mfma_f32_32x32x16_bf16 v[52:67], v[176:179], v[136:139], v[52:67]
	ds_read_b64_tr_b16 v[88:89], v2 offset:44032
	ds_read_b64_tr_b16 v[90:91], v2 offset:44544
	v_add_f32_e32 v84, v94, v84
	v_add_f32_e32 v84, v95, v84
	v_add_f32_e32 v84, v96, v84
	v_add_f32_e32 v84, v97, v84
	v_cvt_pk_bf16_f32 v140, v92, v93
	v_cvt_pk_bf16_f32 v141, v94, v95
	s_waitcnt lgkmcnt(14)
	v_mfma_f32_32x32x16_bf16 v[116:131], v[198:201], v[132:135], v[116:131]
	ds_read_b64_tr_b16 v[92:93], v2 offset:48128
	ds_read_b64_tr_b16 v[94:95], v2 offset:48640
	v_mfma_f32_32x32x16_bf16 v[52:67], v[72:75], v[132:135], v[52:67]
	v_add_f32_e32 v72, v98, v84
	v_add_f32_e32 v72, v99, v72
	v_add_f32_e32 v72, 0, v72
	v_cvt_pk_bf16_f32 v142, v96, v97
	v_cvt_pk_bf16_f32 v143, v98, v99
	v_readlane_b32 s22, v254, 60
	v_readlane_b32 s23, v254, 61
	s_mov_b32 s23, s17
	v_add_f32_e32 v191, v191, v72
	v_lshl_add_u64 v[72:73], v[182:183], 0, s[22:23]
	s_mov_b32 s14, m0
	s_mov_b32 m0, s9
	s_nop 0
	global_load_lds_dwordx4 v[72:73], off
	s_mov_b32 m0, s14
	s_add_i32 s9, s13, 0x8000
	v_readlane_b32 s14, v254, 62
	v_readlane_b32 s15, v254, 63
	s_mov_b32 s15, s17
	s_mov_b32 s16, s14
	v_lshl_add_u64 v[72:73], v[180:181], 0, s[14:15]
	s_mov_b32 s14, m0
	s_mov_b32 m0, s9
	s_nop 0
	global_load_lds_dwordx4 v[72:73], off
	s_mov_b32 m0, s14
	v_writelane_b32 v254, s16, 62
	s_nop 1
	v_writelane_b32 v254, s17, 63
	s_waitcnt lgkmcnt(14)
	v_mfma_f32_32x32x16_bf16 v[4:19], v[160:163], v[202:205], v[4:19]
	v_exp_f32_e32 v116, v116
	v_exp_f32_e32 v117, v117
	v_exp_f32_e32 v118, v118
	v_exp_f32_e32 v119, v119
	s_waitcnt lgkmcnt(12)
	v_mfma_f32_32x32x16_bf16 v[20:35], v[160:163], v[100:103], v[20:35]
	v_exp_f32_e32 v120, v120
	v_exp_f32_e32 v121, v121
	v_exp_f32_e32 v122, v122
	v_exp_f32_e32 v123, v123
	ds_read_b128 v[72:75], v189 offset:8192
	ds_read_b128 v[96:99], v189 offset:8704
	s_waitcnt lgkmcnt(12)
	v_mfma_f32_32x32x16_bf16 v[4:19], v[156:159], v[68:71], v[4:19]
	v_exp_f32_e32 v124, v124
	v_exp_f32_e32 v125, v125
	v_exp_f32_e32 v126, v126
	v_exp_f32_e32 v127, v127
	ds_read_b128 v[164:167], v189 offset:10240
	ds_read_b128 v[168:171], v189 offset:10752
	s_waitcnt lgkmcnt(12)
	v_mfma_f32_32x32x16_bf16 v[20:35], v[156:159], v[76:79], v[20:35]
	v_exp_f32_e32 v128, v128
	v_exp_f32_e32 v129, v129
	v_exp_f32_e32 v130, v130
	v_exp_f32_e32 v131, v131
	ds_read_b128 v[172:175], v189 offset:12288
	ds_read_b128 v[176:179], v189 offset:12800
	s_waitcnt lgkmcnt(12)
	v_mfma_f32_32x32x16_bf16 v[4:19], v[148:151], v[80:83], v[4:19]
	v_exp_f32_e32 v52, v52
	v_exp_f32_e32 v53, v53
	v_exp_f32_e32 v54, v54
	v_exp_f32_e32 v55, v55
	ds_read_b128 v[198:201], v189 offset:14336
	ds_read_b128 v[84:87], v189 offset:14848
	s_waitcnt lgkmcnt(12)
	v_mfma_f32_32x32x16_bf16 v[20:35], v[148:151], v[104:107], v[20:35]
	v_exp_f32_e32 v56, v56
	v_exp_f32_e32 v57, v57
	v_exp_f32_e32 v58, v58
	v_exp_f32_e32 v59, v59
	s_waitcnt lgkmcnt(10)
	v_mfma_f32_32x32x16_bf16 v[4:19], v[140:143], v[88:91], v[4:19]
	v_exp_f32_e32 v60, v60
	v_exp_f32_e32 v61, v61
	v_exp_f32_e32 v62, v62
	v_exp_f32_e32 v63, v63
	s_waitcnt lgkmcnt(8)
	v_mfma_f32_32x32x16_bf16 v[20:35], v[140:143], v[92:95], v[20:35]
	v_exp_f32_e32 v64, v64
	v_exp_f32_e32 v65, v65
	v_exp_f32_e32 v66, v66
	v_exp_f32_e32 v67, v67
	s_waitcnt vmcnt(2) lgkmcnt(0)
	s_barrier
;   #define RESC() do{ if(resc){ asm volatile("s_waitcnt lgkmcnt(0)":::"memory"); \
;       _Pragma("unroll") for(int d_=0;d_<2;++d_) _Pragma("unroll") for(int r=0;r<16;++r)o[d_][r]*=wsf[crow(r,hi)]; } }while(0)
;   #define ROT() do{sl_prev=sl_cur;sl_cur=sl_next;sl_next=(sl_next==(NSLOT-1)*SLOTB)?0:sl_next+SLOTB;}while(0)
;   #define ENDW(tt) do{ if((tt)+3<NT){WAIT_BAR(2);} else if((tt)+2<NT){WAIT_BAR(1);} else {WAIT_BAR(0);} }while(0)
; template<int THRL,bool NOMAX> __device__ __forceinline__ void attn_unit(int b,int h,int qb,int t0,const bf16*Q,const bf16*__restrict__ KV,const bf16*__restrict__ GA,bf16*O,char*shm){
;     ...
;   for(;t+1<NT;t+=2){
;     STEP(pB0,pB1,pA0,pA1,t,(t+3<NT),(t+1<NT),(t+1<NT));       ENDW(t);   RESC(); ROT();
;     STEP(pA0,pA1,pB0,pB1,t+1,(t+4<NT),(t+2<NT),(t+2<NT));     ENDW(t+1); RESC(); ROT();
;   }
	ds_read_b64_tr_b16 v[88:89], v2 offset:24576
	ds_read_b64_tr_b16 v[90:91], v2 offset:25088
	v_add_f32_e32 v68, v116, v117
	v_add_f32_e32 v68, v118, v68
	v_add_f32_e32 v68, v119, v68
	v_add_f32_e32 v68, v120, v68
	v_add_f32_e32 v68, v121, v68
	v_cvt_pk_bf16_f32 v160, v116, v117
	v_cvt_pk_bf16_f32 v161, v118, v119
	s_waitcnt lgkmcnt(9)
	v_mfma_f32_32x32x16_bf16 v[100:115], v[72:75], v[152:155], v[36:51]
	ds_read_b64_tr_b16 v[92:93], v2 offset:28672
	ds_read_b64_tr_b16 v[94:95], v2 offset:29184
	v_add_f32_e32 v68, v122, v68
	v_add_f32_e32 v68, v123, v68
	v_add_f32_e32 v68, v124, v68
	v_add_f32_e32 v116, v125, v68
	v_cvt_pk_bf16_f32 v162, v120, v121
	v_cvt_pk_bf16_f32 v163, v122, v123
	s_waitcnt lgkmcnt(10)
	v_mfma_f32_32x32x16_bf16 v[68:83], v[96:99], v[152:155], v[36:51]
	ds_read_b64_tr_b16 v[96:97], v2 offset:25600
	ds_read_b64_tr_b16 v[98:99], v2 offset:26112
	v_add_f32_e32 v116, v126, v116
	v_add_f32_e32 v116, v127, v116
	v_add_f32_e32 v116, v128, v116
	v_add_f32_e32 v120, v129, v116
	v_cvt_pk_bf16_f32 v156, v124, v125
	v_cvt_pk_bf16_f32 v157, v126, v127
	s_waitcnt lgkmcnt(11)
	v_mfma_f32_32x32x16_bf16 v[100:115], v[164:167], v[144:147], v[100:115]
	ds_read_b64_tr_b16 v[116:117], v2 offset:29696
	ds_read_b64_tr_b16 v[118:119], v2 offset:30208
	v_add_f32_e32 v120, v130, v120
	v_add_f32_e32 v120, v131, v120
	v_add_f32_e32 v120, v52, v120
	v_add_f32_e32 v124, v53, v120
	v_cvt_pk_bf16_f32 v158, v128, v129
	v_cvt_pk_bf16_f32 v159, v130, v131
	s_waitcnt lgkmcnt(12)
	v_mfma_f32_32x32x16_bf16 v[68:83], v[168:171], v[144:147], v[68:83]
	ds_read_b64_tr_b16 v[120:121], v2 offset:26624
	ds_read_b64_tr_b16 v[122:123], v2 offset:27136
	v_add_f32_e32 v124, v54, v124
	v_add_f32_e32 v124, v55, v124
	v_add_f32_e32 v124, v56, v124
	v_add_f32_e32 v124, v57, v124
	v_cvt_pk_bf16_f32 v148, v52, v53
	v_cvt_pk_bf16_f32 v149, v54, v55
	s_waitcnt lgkmcnt(13)
	v_mfma_f32_32x32x16_bf16 v[100:115], v[172:175], v[136:139], v[100:115]
	ds_read_b64_tr_b16 v[52:53], v2 offset:30720
	ds_read_b64_tr_b16 v[54:55], v2 offset:31232
	v_add_f32_e32 v124, v58, v124
	v_add_f32_e32 v124, v59, v124
	v_add_f32_e32 v124, v60, v124
	v_add_f32_e32 v124, v61, v124
	v_cvt_pk_bf16_f32 v150, v56, v57
	v_cvt_pk_bf16_f32 v151, v58, v59
	s_waitcnt lgkmcnt(14)
	v_mfma_f32_32x32x16_bf16 v[68:83], v[176:179], v[136:139], v[68:83]
	ds_read_b64_tr_b16 v[56:57], v2 offset:27648
	ds_read_b64_tr_b16 v[58:59], v2 offset:28160
	v_add_f32_e32 v124, v62, v124
	v_add_f32_e32 v124, v63, v124
	v_add_f32_e32 v124, v64, v124
	v_add_f32_e32 v124, v65, v124
	v_cvt_pk_bf16_f32 v140, v60, v61
	v_cvt_pk_bf16_f32 v141, v62, v63
	s_waitcnt lgkmcnt(14)
	v_mfma_f32_32x32x16_bf16 v[100:115], v[198:201], v[132:135], v[100:115]
	ds_read_b64_tr_b16 v[60:61], v2 offset:31744
	ds_read_b64_tr_b16 v[62:63], v2 offset:32256
	v_mfma_f32_32x32x16_bf16 v[68:83], v[84:87], v[132:135], v[68:83]
	v_add_f32_e32 v84, v66, v124
	v_add_f32_e32 v84, v67, v84
	v_add_f32_e32 v84, 0, v84
	v_cvt_pk_bf16_f32 v142, v64, v65
	v_cvt_pk_bf16_f32 v143, v66, v67
	s_mov_b32 s14, s20
	v_lshl_add_u64 v[64:65], v[180:181], 0, s[20:21]
	s_add_i32 s13, s13, 0xa000
	s_mov_b32 s9, m0
	s_mov_b32 m0, s13
	s_nop 0
	global_load_lds_dwordx4 v[64:65], off
	s_mov_b32 m0, s9
	v_writelane_b32 v254, s14, 56
	v_add_f32_e32 v182, v191, v84
	s_nop 0
	v_writelane_b32 v254, s15, 57
	s_waitcnt lgkmcnt(14)
	v_mfma_f32_32x32x16_bf16 v[4:19], v[160:163], v[88:91], v[4:19]
	v_exp_f32_e32 v100, v100
	v_exp_f32_e32 v101, v101
	v_exp_f32_e32 v102, v102
	v_exp_f32_e32 v103, v103
	s_waitcnt lgkmcnt(12)
	v_mfma_f32_32x32x16_bf16 v[20:35], v[160:163], v[92:95], v[20:35]
	v_exp_f32_e32 v104, v104
	v_exp_f32_e32 v105, v105
	v_exp_f32_e32 v106, v106
	v_exp_f32_e32 v107, v107
	ds_read_b128 v[64:67], v189 offset:16384
	ds_read_b128 v[124:127], v189 offset:16896
	s_waitcnt lgkmcnt(12)
	v_mfma_f32_32x32x16_bf16 v[4:19], v[156:159], v[96:99], v[4:19]
	v_exp_f32_e32 v108, v108
	v_exp_f32_e32 v109, v109
	v_exp_f32_e32 v110, v110
	v_exp_f32_e32 v111, v111
	ds_read_b128 v[128:131], v189 offset:18432
	ds_read_b128 v[164:167], v189 offset:18944
	s_waitcnt lgkmcnt(12)
	v_mfma_f32_32x32x16_bf16 v[20:35], v[156:159], v[116:119], v[20:35]
	v_exp_f32_e32 v112, v112
	v_exp_f32_e32 v113, v113
	v_exp_f32_e32 v114, v114
	v_exp_f32_e32 v115, v115
	ds_read_b128 v[168:171], v189 offset:20480
	ds_read_b128 v[172:175], v189 offset:20992
	s_waitcnt lgkmcnt(12)
	v_mfma_f32_32x32x16_bf16 v[4:19], v[148:151], v[120:123], v[4:19]
	v_exp_f32_e32 v68, v68
	v_exp_f32_e32 v69, v69
	v_exp_f32_e32 v70, v70
	v_exp_f32_e32 v71, v71
	ds_read_b128 v[120:123], v189 offset:22528
	ds_read_b128 v[116:119], v189 offset:23040
	s_waitcnt lgkmcnt(12)
	v_mfma_f32_32x32x16_bf16 v[20:35], v[148:151], v[52:55], v[20:35]
	v_exp_f32_e32 v72, v72
	v_exp_f32_e32 v73, v73
	v_exp_f32_e32 v74, v74
	v_exp_f32_e32 v75, v75
	s_waitcnt lgkmcnt(10)
	v_mfma_f32_32x32x16_bf16 v[4:19], v[140:143], v[56:59], v[4:19]
	v_exp_f32_e32 v76, v76
	v_exp_f32_e32 v77, v77
	v_exp_f32_e32 v78, v78
	v_exp_f32_e32 v79, v79
	s_waitcnt lgkmcnt(8)
	v_mfma_f32_32x32x16_bf16 v[20:35], v[140:143], v[60:63], v[20:35]
	v_exp_f32_e32 v80, v80
	v_exp_f32_e32 v81, v81
	v_exp_f32_e32 v82, v82
	v_exp_f32_e32 v83, v83
	s_waitcnt vmcnt(1) lgkmcnt(0)
	s_barrier
;   #define RESC() do{ if(resc){ asm volatile("s_waitcnt lgkmcnt(0)":::"memory"); \
;       _Pragma("unroll") for(int d_=0;d_<2;++d_) _Pragma("unroll") for(int r=0;r<16;++r)o[d_][r]*=wsf[crow(r,hi)]; } }while(0)
;   #define ROT() do{sl_prev=sl_cur;sl_cur=sl_next;sl_next=(sl_next==(NSLOT-1)*SLOTB)?0:sl_next+SLOTB;}while(0)
;   #define ENDW(tt) do{ if((tt)+3<NT){WAIT_BAR(2);} else if((tt)+2<NT){WAIT_BAR(1);} else {WAIT_BAR(0);} }while(0)
; template<int THRL,bool NOMAX> __device__ __forceinline__ void attn_unit(int b,int h,int qb,int t0,const bf16*Q,const bf16*__restrict__ KV,const bf16*__restrict__ GA,bf16*O,char*shm){
;     ...
;   for(;t+1<NT;t+=2){
;     STEP(pB0,pB1,pA0,pA1,t,(t+3<NT),(t+1<NT),(t+1<NT));       ENDW(t);   RESC(); ROT();
;     STEP(pA0,pA1,pB0,pB1,t+1,(t+4<NT),(t+2<NT),(t+2<NT));     ENDW(t+1); RESC(); ROT();
;   }
	ds_read_b64_tr_b16 v[176:177], v2 offset:32768
	ds_read_b64_tr_b16 v[178:179], v2 offset:33280
	v_add_f32_e32 v52, v100, v101
	v_add_f32_e32 v52, v102, v52
	v_add_f32_e32 v52, v103, v52
	v_add_f32_e32 v52, v104, v52
	v_add_f32_e32 v52, v105, v52
	v_cvt_pk_bf16_f32 v160, v100, v101
	v_cvt_pk_bf16_f32 v161, v102, v103
	s_waitcnt lgkmcnt(9)
	v_mfma_f32_32x32x16_bf16 v[84:99], v[64:67], v[152:155], v[36:51]
	ds_read_b64_tr_b16 v[100:101], v2 offset:36864
	ds_read_b64_tr_b16 v[102:103], v2 offset:37376
	v_add_f32_e32 v52, v106, v52
	v_add_f32_e32 v52, v107, v52
	v_add_f32_e32 v52, v108, v52
	v_add_f32_e32 v140, v109, v52
	v_cvt_pk_bf16_f32 v162, v104, v105
	v_cvt_pk_bf16_f32 v163, v106, v107
	s_waitcnt lgkmcnt(10)
	v_mfma_f32_32x32x16_bf16 v[52:67], v[124:127], v[152:155], v[36:51]
	ds_read_b64_tr_b16 v[124:125], v2 offset:33792
	ds_read_b64_tr_b16 v[126:127], v2 offset:34304
	v_add_f32_e32 v104, v110, v140
	v_add_f32_e32 v104, v111, v104
	v_add_f32_e32 v104, v112, v104
	v_add_f32_e32 v104, v113, v104
	v_cvt_pk_bf16_f32 v156, v108, v109
	v_cvt_pk_bf16_f32 v157, v110, v111
	s_waitcnt lgkmcnt(11)
	v_mfma_f32_32x32x16_bf16 v[84:99], v[128:131], v[144:147], v[84:99]
	ds_read_b64_tr_b16 v[106:107], v2 offset:37888
	ds_read_b64_tr_b16 v[108:109], v2 offset:38400
	v_add_f32_e32 v104, v114, v104
	v_add_f32_e32 v104, v115, v104
	v_add_f32_e32 v104, v68, v104
	v_add_f32_e32 v104, v69, v104
	v_cvt_pk_bf16_f32 v158, v112, v113
	v_cvt_pk_bf16_f32 v159, v114, v115
	s_waitcnt lgkmcnt(12)
	v_mfma_f32_32x32x16_bf16 v[52:67], v[164:167], v[144:147], v[52:67]
	ds_read_b64_tr_b16 v[110:111], v2 offset:34816
	ds_read_b64_tr_b16 v[112:113], v2 offset:35328
	v_add_f32_e32 v104, v70, v104
	v_add_f32_e32 v104, v71, v104
	v_add_f32_e32 v104, v72, v104
	v_add_f32_e32 v104, v73, v104
	v_cvt_pk_bf16_f32 v148, v68, v69
	v_cvt_pk_bf16_f32 v149, v70, v71
	s_waitcnt lgkmcnt(13)
	v_mfma_f32_32x32x16_bf16 v[84:99], v[168:171], v[136:139], v[84:99]
	ds_read_b64_tr_b16 v[68:69], v2 offset:38912
	ds_read_b64_tr_b16 v[70:71], v2 offset:39424
	v_add_f32_e32 v104, v74, v104
	v_add_f32_e32 v104, v75, v104
	v_add_f32_e32 v104, v76, v104
	v_add_f32_e32 v104, v77, v104
	v_cvt_pk_bf16_f32 v150, v72, v73
	v_cvt_pk_bf16_f32 v151, v74, v75
	s_waitcnt lgkmcnt(14)
	v_mfma_f32_32x32x16_bf16 v[52:67], v[172:175], v[136:139], v[52:67]
	ds_read_b64_tr_b16 v[72:73], v2 offset:35840
	ds_read_b64_tr_b16 v[74:75], v2 offset:36352
	v_add_f32_e32 v104, v78, v104
	v_add_f32_e32 v104, v79, v104
	v_add_f32_e32 v104, v80, v104
	v_add_f32_e32 v104, v81, v104
	v_cvt_pk_bf16_f32 v140, v76, v77
	v_cvt_pk_bf16_f32 v141, v78, v79
	s_waitcnt lgkmcnt(14)
	v_mfma_f32_32x32x16_bf16 v[84:99], v[120:123], v[132:135], v[84:99]
	ds_read_b64_tr_b16 v[76:77], v2 offset:39936
	ds_read_b64_tr_b16 v[78:79], v2 offset:40448
	v_add_f32_e32 v104, v82, v104
	v_add_f32_e32 v104, v83, v104
	v_add_f32_e32 v104, 0, v104
	v_cvt_pk_bf16_f32 v142, v80, v81
	v_cvt_pk_bf16_f32 v143, v82, v83
	v_mfma_f32_32x32x16_bf16 v[52:67], v[116:119], v[132:135], v[52:67]
	s_mov_b32 s14, s22
	v_lshl_add_u64 v[80:81], v[180:181], 0, s[22:23]
	s_mov_b32 s9, m0
	s_mov_b32 m0, s8
	s_nop 0
	global_load_lds_dwordx4 v[80:81], off
	s_mov_b32 m0, s9
	v_writelane_b32 v254, s14, 60
	v_add_f32_e32 v104, v182, v104
	s_nop 0
	v_writelane_b32 v254, s15, 61
	s_waitcnt lgkmcnt(14)
	v_mfma_f32_32x32x16_bf16 v[4:19], v[160:163], v[176:179], v[4:19]
	v_exp_f32_e32 v84, v84
	v_exp_f32_e32 v85, v85
	v_exp_f32_e32 v86, v86
	v_exp_f32_e32 v87, v87
	s_waitcnt lgkmcnt(12)
	v_mfma_f32_32x32x16_bf16 v[20:35], v[160:163], v[100:103], v[20:35]
	v_exp_f32_e32 v88, v88
	v_exp_f32_e32 v89, v89
	v_exp_f32_e32 v90, v90
	v_exp_f32_e32 v91, v91
	ds_read_b128 v[114:117], v189
	ds_read_b128 v[118:121], v189 offset:512
	s_waitcnt lgkmcnt(12)
	v_mfma_f32_32x32x16_bf16 v[4:19], v[156:159], v[124:127], v[4:19]
	v_exp_f32_e32 v92, v92
	v_exp_f32_e32 v93, v93
	v_exp_f32_e32 v94, v94
	v_exp_f32_e32 v95, v95
	ds_read_b128 v[122:125], v189 offset:2048
	ds_read_b128 v[126:129], v189 offset:2560
	s_waitcnt lgkmcnt(12)
	v_mfma_f32_32x32x16_bf16 v[20:35], v[156:159], v[106:109], v[20:35]
	v_exp_f32_e32 v96, v96
	v_exp_f32_e32 v97, v97
	v_exp_f32_e32 v98, v98
	v_exp_f32_e32 v99, v99
	ds_read_b128 v[106:109], v189 offset:4096
	ds_read_b128 v[164:167], v189 offset:4608
	s_waitcnt lgkmcnt(12)
	v_mfma_f32_32x32x16_bf16 v[4:19], v[148:151], v[110:113], v[4:19]
	v_exp_f32_e32 v52, v52
	v_exp_f32_e32 v53, v53
	v_exp_f32_e32 v54, v54
	v_exp_f32_e32 v55, v55
	ds_read_b128 v[110:113], v189 offset:6144
	ds_read_b128 v[100:103], v189 offset:6656
	s_waitcnt lgkmcnt(12)
	v_mfma_f32_32x32x16_bf16 v[20:35], v[148:151], v[68:71], v[20:35]
	v_exp_f32_e32 v56, v56
	v_exp_f32_e32 v57, v57
	v_exp_f32_e32 v58, v58
	v_exp_f32_e32 v59, v59
	s_waitcnt lgkmcnt(10)
	v_mfma_f32_32x32x16_bf16 v[4:19], v[140:143], v[72:75], v[4:19]
	v_exp_f32_e32 v60, v60
	v_exp_f32_e32 v61, v61
	v_exp_f32_e32 v62, v62
	v_exp_f32_e32 v63, v63
	s_waitcnt lgkmcnt(8)
	v_mfma_f32_32x32x16_bf16 v[20:35], v[140:143], v[76:79], v[20:35]
	v_exp_f32_e32 v64, v64
	v_exp_f32_e32 v65, v65
	v_exp_f32_e32 v66, v66
	v_exp_f32_e32 v67, v67
	s_waitcnt vmcnt(0) lgkmcnt(0)
	s_barrier
;   #define RESC() do{ if(resc){ asm volatile("s_waitcnt lgkmcnt(0)":::"memory"); \
;       _Pragma("unroll") for(int d_=0;d_<2;++d_) _Pragma("unroll") for(int r=0;r<16;++r)o[d_][r]*=wsf[crow(r,hi)]; } }while(0)
; template<int THRL,bool NOMAX> __device__ __forceinline__ void attn_unit(int b,int h,int qb,int t0,const bf16*Q,const bf16*__restrict__ KV,const bf16*__restrict__ GA,bf16*O,char*shm){
;     ...
;   STEP(pB0,pB1,pA0,pA1,NT-1,false,false,false); RESC();
	ds_read_b64_tr_b16 v[168:169], v2 offset:40960
	ds_read_b64_tr_b16 v[170:171], v2 offset:41472
	v_add_f32_e32 v68, v84, v85
	v_add_f32_e32 v68, v86, v68
	v_add_f32_e32 v68, v87, v68
	v_add_f32_e32 v68, v88, v68
	v_add_f32_e32 v105, v89, v68
	v_cvt_pk_bf16_f32 v160, v84, v85
	v_cvt_pk_bf16_f32 v161, v86, v87
	s_waitcnt lgkmcnt(9)
	v_mfma_f32_32x32x16_bf16 v[68:83], v[114:117], v[152:155], v[36:51]
	ds_read_b64_tr_b16 v[84:85], v2 offset:45056
	ds_read_b64_tr_b16 v[86:87], v2 offset:45568
	s_waitcnt lgkmcnt(10)
	v_mfma_f32_32x32x16_bf16 v[36:51], v[118:121], v[152:155], v[36:51]
	v_add_f32_e32 v105, v90, v105
	v_add_f32_e32 v105, v91, v105
	v_add_f32_e32 v105, v92, v105
	v_add_f32_e32 v105, v93, v105
	v_cvt_pk_bf16_f32 v162, v88, v89
	v_cvt_pk_bf16_f32 v163, v90, v91
	ds_read_b64_tr_b16 v[88:89], v2 offset:41984
	ds_read_b64_tr_b16 v[90:91], v2 offset:42496
	v_add_f32_e32 v105, v94, v105
	v_add_f32_e32 v105, v95, v105
	v_add_f32_e32 v105, v96, v105
	v_add_f32_e32 v105, v97, v105
	v_cvt_pk_bf16_f32 v156, v92, v93
	v_cvt_pk_bf16_f32 v157, v94, v95
	s_waitcnt lgkmcnt(11)
	v_mfma_f32_32x32x16_bf16 v[68:83], v[122:125], v[144:147], v[68:83]
	ds_read_b64_tr_b16 v[92:93], v2 offset:46080
	ds_read_b64_tr_b16 v[94:95], v2 offset:46592
	s_waitcnt lgkmcnt(12)
	v_mfma_f32_32x32x16_bf16 v[36:51], v[126:129], v[144:147], v[36:51]
	v_add_f32_e32 v105, v98, v105
	v_add_f32_e32 v105, v99, v105
	v_add_f32_e32 v105, v52, v105
	v_add_f32_e32 v105, v53, v105
	v_cvt_pk_bf16_f32 v158, v96, v97
	v_cvt_pk_bf16_f32 v159, v98, v99
	ds_read_b64_tr_b16 v[96:97], v2 offset:43008
	ds_read_b64_tr_b16 v[98:99], v2 offset:43520
	v_add_f32_e32 v105, v54, v105
	v_add_f32_e32 v105, v55, v105
	v_add_f32_e32 v105, v56, v105
	v_add_f32_e32 v105, v57, v105
	v_cvt_pk_bf16_f32 v148, v52, v53
	v_cvt_pk_bf16_f32 v149, v54, v55
	s_waitcnt lgkmcnt(13)
	v_mfma_f32_32x32x16_bf16 v[68:83], v[106:109], v[136:139], v[68:83]
	ds_read_b64_tr_b16 v[52:53], v2 offset:47104
	ds_read_b64_tr_b16 v[54:55], v2 offset:47616
	s_waitcnt lgkmcnt(14)
	v_mfma_f32_32x32x16_bf16 v[36:51], v[164:167], v[136:139], v[36:51]
	v_add_f32_e32 v105, v58, v105
	v_add_f32_e32 v105, v59, v105
	v_add_f32_e32 v105, v60, v105
	v_add_f32_e32 v105, v61, v105
	v_cvt_pk_bf16_f32 v150, v56, v57
	v_cvt_pk_bf16_f32 v151, v58, v59
	ds_read_b64_tr_b16 v[56:57], v2 offset:44032
	ds_read_b64_tr_b16 v[58:59], v2 offset:44544
	v_add_f32_e32 v105, v62, v105
	v_add_f32_e32 v105, v63, v105
	v_add_f32_e32 v105, v64, v105
	v_add_f32_e32 v105, v65, v105
	v_cvt_pk_bf16_f32 v140, v60, v61
	v_cvt_pk_bf16_f32 v141, v62, v63
	s_waitcnt lgkmcnt(14)
	v_mfma_f32_32x32x16_bf16 v[68:83], v[110:113], v[132:135], v[68:83]
	ds_read_b64_tr_b16 v[60:61], v2 offset:48128
	ds_read_b64_tr_b16 v[62:63], v2 offset:48640
	v_mfma_f32_32x32x16_bf16 v[36:51], v[100:103], v[132:135], v[36:51]
	v_add_f32_e32 v2, v66, v105
	v_add_f32_e32 v2, v67, v2
	v_add_f32_e32 v2, 0, v2
	v_cvt_pk_bf16_f32 v142, v64, v65
	v_cvt_pk_bf16_f32 v143, v66, v67
	s_waitcnt lgkmcnt(14)
	v_mfma_f32_32x32x16_bf16 v[4:19], v[160:163], v[168:171], v[4:19]
	s_nop 1
	v_exp_f32_e32 v68, v68
	v_exp_f32_e32 v69, v69
	v_exp_f32_e32 v70, v70
	v_exp_f32_e32 v71, v71
	s_waitcnt lgkmcnt(12)
	v_mfma_f32_32x32x16_bf16 v[20:35], v[160:163], v[84:87], v[20:35]
	v_exp_f32_e32 v72, v72
	v_exp_f32_e32 v73, v73
	v_exp_f32_e32 v74, v74
	v_exp_f32_e32 v75, v75
	s_waitcnt lgkmcnt(10)
	v_mfma_f32_32x32x16_bf16 v[4:19], v[156:159], v[88:91], v[4:19]
	v_exp_f32_e32 v76, v76
	v_exp_f32_e32 v77, v77
	v_exp_f32_e32 v78, v78
	v_exp_f32_e32 v79, v79
	s_waitcnt lgkmcnt(8)
	v_mfma_f32_32x32x16_bf16 v[20:35], v[156:159], v[92:95], v[20:35]
	v_exp_f32_e32 v80, v80
	v_exp_f32_e32 v81, v81
	v_exp_f32_e32 v82, v82
	v_exp_f32_e32 v83, v83
	s_waitcnt lgkmcnt(6)
; #define SBAR() __builtin_amdgcn_sched_barrier(0)
;   #define RESC() do{ if(resc){ asm volatile("s_waitcnt lgkmcnt(0)":::"memory"); \
;       _Pragma("unroll") for(int d_=0;d_<2;++d_) _Pragma("unroll") for(int r=0;r<16;++r)o[d_][r]*=wsf[crow(r,hi)]; } }while(0)
;   #define PKW(P,B) cvtpk_s(P[B],P[B+1])
; __device__ __forceinline__ void pv(f32x16*o,int vb,bf16x8 pa0,bf16x8 pa1,bf16x8 pa2,bf16x8 pa3){
;   #pragma unroll
;   for(int d0=0;d0<2;++d0){s16x4 lo[4],hi[4];
;     #pragma unroll
;     for(int ks=0;ks<4;++ks){
;       asm volatile("ds_read_b64_tr_b16 %0,%1 offset:%c2":"=&v"(lo[ks]):"v"(vb),"i"(d0*4096+ks*1024):"memory");
;       asm volatile("ds_read_b64_tr_b16 %0,%1 offset:%c2":"=&v"(hi[ks]):"v"(vb),"i"(d0*4096+ks*1024+512):"memory");}
;     asm volatile("s_waitcnt lgkmcnt(0)":::"memory");SBAR();
;     ...
;     o[d0]=__builtin_amdgcn_mfma_f32_32x32x16_bf16(pa0,PK(0),o[d0],0,0,0);
;     o[d0]=__builtin_amdgcn_mfma_f32_32x32x16_bf16(pa1,PK(1),o[d0],0,0,0);
;     o[d0]=__builtin_amdgcn_mfma_f32_32x32x16_bf16(pa2,PK(2),o[d0],0,0,0);
;     o[d0]=__builtin_amdgcn_mfma_f32_32x32x16_bf16(pa3,PK(3),o[d0],0,0,0);
;     ...
;   }
; }
; template<int THRL,bool NOMAX> __device__ __forceinline__ void attn_unit(int b,int h,int qb,int t0,const bf16*Q,const bf16*__restrict__ KV,const bf16*__restrict__ GA,bf16*O,char*shm){
;     ...
;   STEP(pB0,pB1,pA0,pA1,NT-1,false,false,false); RESC();
;   { float sacc=pB0[0]+pB0[1]; _Pragma("unroll") for(int r=2;r<16;++r)sacc+=pB0[r]; _Pragma("unroll") for(int r=0;r<16;++r)sacc+=pB1[r]; l_reg+=sacc;
;     pw0=(u32x4){PKW(pB0,0),PKW(pB0,2),PKW(pB0,4),PKW(pB0,6)};pw1=(u32x4){PKW(pB0,8),PKW(pB0,10),PKW(pB0,12),PKW(pB0,14)};pw2=(u32x4){PKW(pB1,0),PKW(pB1,2),PKW(pB1,4),PKW(pB1,6)};pw3=(u32x4){PKW(pB1,8),PKW(pB1,10),PKW(pB1,12),PKW(pB1,14)};
;     SBAR(); pv(o,vb0+sl_cur,PAF(0),PAF(1),PAF(2),PAF(3)); }
;     ...
;   {auto rr=__builtin_amdgcn_permlane32_swap(__float_as_uint(l_reg),__float_as_uint(l_reg),false,false);l_reg=__uint_as_float(rr[0])+__uint_as_float(rr[1]);}
;   if(hi==0)wsf[32+r32]=l_reg;asm volatile("s_waitcnt lgkmcnt(0)":::"memory");
	v_mfma_f32_32x32x16_bf16 v[4:19], v[148:151], v[96:99], v[4:19]
	v_exp_f32_e32 v36, v36
	v_exp_f32_e32 v37, v37
	v_exp_f32_e32 v38, v38
	v_exp_f32_e32 v39, v39
	s_waitcnt lgkmcnt(4)
	v_mfma_f32_32x32x16_bf16 v[20:35], v[148:151], v[52:55], v[20:35]
	v_exp_f32_e32 v40, v40
	v_exp_f32_e32 v41, v41
	v_exp_f32_e32 v42, v42
	v_exp_f32_e32 v43, v43
	s_waitcnt lgkmcnt(2)
	v_mfma_f32_32x32x16_bf16 v[4:19], v[140:143], v[56:59], v[4:19]
	v_exp_f32_e32 v44, v44
	v_exp_f32_e32 v45, v45
	v_exp_f32_e32 v46, v46
	v_exp_f32_e32 v47, v47
	s_waitcnt lgkmcnt(0)
	v_mfma_f32_32x32x16_bf16 v[20:35], v[140:143], v[60:63], v[20:35]
	v_exp_f32_e32 v48, v48
	v_exp_f32_e32 v49, v49
	v_exp_f32_e32 v50, v50
	v_exp_f32_e32 v51, v51
	v_add_f32_e32 v52, v68, v69
	v_add_f32_e32 v52, v70, v52
	v_add_f32_e32 v52, v71, v52
	v_add_f32_e32 v52, v72, v52
	v_add_f32_e32 v52, v73, v52
	v_add_f32_e32 v52, v74, v52
	v_add_f32_e32 v52, v75, v52
	v_add_f32_e32 v52, v76, v52
	v_add_f32_e32 v52, v77, v52
	v_add_f32_e32 v52, v78, v52
	v_add_f32_e32 v52, v79, v52
	v_add_f32_e32 v52, v80, v52
	v_add_f32_e32 v52, v81, v52
	v_add_f32_e32 v52, v82, v52
	v_add_f32_e32 v52, v83, v52
	v_add_f32_e32 v52, v36, v52
	v_add_f32_e32 v52, v37, v52
	v_add_f32_e32 v52, v38, v52
	v_add_f32_e32 v52, v39, v52
	v_add_f32_e32 v52, v40, v52
	v_add_f32_e32 v52, v41, v52
	v_add_f32_e32 v52, v42, v52
	v_add_f32_e32 v52, v43, v52
	v_add_f32_e32 v52, v44, v52
	v_add_f32_e32 v52, v45, v52
	v_add_f32_e32 v52, v46, v52
	v_add_f32_e32 v52, v47, v52
	v_add_f32_e32 v52, v48, v52
	v_add_f32_e32 v52, v49, v52
	v_add_f32_e32 v52, v50, v52
	v_add_f32_e32 v52, v51, v52
	v_add_f32_e32 v2, v104, v2
	v_add_f32_e32 v2, v2, v52
	v_cvt_pk_bf16_f32 v36, v36, v37
	v_cvt_pk_bf16_f32 v52, v68, v69
	v_cvt_pk_bf16_f32 v53, v70, v71
	v_cvt_pk_bf16_f32 v54, v72, v73
	v_cvt_pk_bf16_f32 v55, v74, v75
	v_cvt_pk_bf16_f32 v56, v76, v77
	v_cvt_pk_bf16_f32 v57, v78, v79
	v_cvt_pk_bf16_f32 v58, v80, v81
	v_cvt_pk_bf16_f32 v59, v82, v83
	v_cvt_pk_bf16_f32 v37, v38, v39
	v_cvt_pk_bf16_f32 v38, v40, v41
	v_cvt_pk_bf16_f32 v39, v42, v43
	v_cvt_pk_bf16_f32 v40, v44, v45
	v_cvt_pk_bf16_f32 v41, v46, v47
	v_cvt_pk_bf16_f32 v42, v48, v49
	v_cvt_pk_bf16_f32 v43, v50, v51
	ds_read_b64_tr_b16 v[44:45],v190 offset:0
	ds_read_b64_tr_b16 v[46:47],v190 offset:512
	ds_read_b64_tr_b16 v[48:49],v190 offset:1024
	ds_read_b64_tr_b16 v[50:51],v190 offset:1536
	ds_read_b64_tr_b16 v[60:61],v190 offset:2048
	ds_read_b64_tr_b16 v[62:63],v190 offset:2560
	ds_read_b64_tr_b16 v[64:65],v190 offset:3072
	ds_read_b64_tr_b16 v[66:67],v190 offset:3584
	s_waitcnt lgkmcnt(0)
	s_nop 0
	v_mfma_f32_32x32x16_bf16 v[4:19], v[52:55], v[44:47], v[4:19]
	ds_read_b64_tr_b16 v[44:45],v190 offset:4096
	ds_read_b64_tr_b16 v[46:47],v190 offset:4608
	v_mfma_f32_32x32x16_bf16 v[4:19], v[56:59], v[48:51], v[4:19]
	ds_read_b64_tr_b16 v[48:49],v190 offset:5120
	ds_read_b64_tr_b16 v[50:51],v190 offset:5632
	v_mfma_f32_32x32x16_bf16 v[4:19], v[36:39], v[60:63], v[4:19]
	ds_read_b64_tr_b16 v[60:61],v190 offset:6144
	ds_read_b64_tr_b16 v[62:63],v190 offset:6656
	v_mfma_f32_32x32x16_bf16 v[4:19], v[40:43], v[64:67], v[4:19]
	ds_read_b64_tr_b16 v[64:65],v190 offset:7168
	ds_read_b64_tr_b16 v[66:67],v190 offset:7680
	s_waitcnt lgkmcnt(0)
	v_mfma_f32_32x32x16_bf16 v[20:35], v[52:55], v[44:47], v[20:35]
	v_cmp_gt_u32_e32 vcc, 32, v184
	v_mfma_f32_32x32x16_bf16 v[20:35], v[56:59], v[48:51], v[20:35]
	v_mfma_f32_32x32x16_bf16 v[20:35], v[36:39], v[60:63], v[20:35]
	v_mov_b32_e32 v36, v2
	s_nop 1
	v_permlane32_swap_b32_e32 v2, v36
	v_mfma_f32_32x32x16_bf16 v[20:35], v[40:43], v[64:67], v[20:35]
	s_and_saveexec_b64 s[8:9], vcc
	s_cbranch_execz .LBB0_470
	v_lshl_add_u32 v37, v185, 2, s12
	v_add_f32_e32 v2, v2, v36
	ds_write_b32 v37, v2 offset:49280
	s_branch .LBB0_470

; #define RLAS __attribute__((address_space(3)))
; #define LBAR() do { asm volatile("s_waitcnt lgkmcnt(0)" ::: "memory"); __builtin_amdgcn_s_barrier(); asm volatile("" ::: "memory"); } while (0)
; __device__ __forceinline__ void out_unit(RLAS unsigned char* L, int b, int h, int c, const bf16_t* QR, bf16_t* PR, const bf16_t* KR, const bf16_t* VR, const bf16_t* GR, const bf16_t* ST, size_t stbatch, const float* gnw, float lgf, float lgb, OutRegs& PF, bool is_first, bool has_next, int nb, int nh ...
;     int tid_ = threadIdx.x; asm volatile("" : "+v"(tid_));
;     const int tid = tid_, lane = tid & 63, w = __builtin_amdgcn_readfirstlane(tid >> 6), r = lane & 31, h2 = lane >> 5;
;     const int ib = w >> 1, dvh = w & 1;
;     const int q = (lane & 15) >> 2, p = lane & 3, gq = (lane >> 4) & 1;
;     RLAS unsigned char* R0 = L; RLAS unsigned char* R1 = L + REG1;
;     const size_t tok0 = (size_t)b * SEQ + (size_t)c * 128;
;     const int srow = tid >> 2, sqt = tid & 3;
;     const int grow = (tid >> 6) * 16 + ((tid >> 4) & 3), gch = tid & 15;
;     RLAS unsigned char* R2 = L + REG1 + REGV;
; #pragma unroll
;     for (int i = 0; i < 4; ++i) { *(RLAS u32x4*)(R2 + (grow + 4 * i) * RS + gch * 16) = PF.q[i]; *(RLAS u32x4*)(R0 + (grow + 4 * i) * RS + gch * 16) = PF.k[i]; *(RLAS u32x4*)(R1 + (grow + 4 * i) * RSV + gch * 16) = PF.v[i]; }
;     asm volatile("" ::: "memory"); __builtin_amdgcn_sched_barrier(0);
;     u32x4 sfr[4], sbr[4];
;     { const bf16_t* sf = ST + (size_t)b * stbatch + ((size_t)(0 * 4 + h) * 32 + c) * 16384 + (size_t)grow * 128 + gch * 8;
;       const bf16_t* sb = ST + (size_t)b * stbatch + ((size_t)(1 * 4 + h) * 32 + c) * 16384 + (size_t)grow * 128 + gch * 8;
; #pragma unroll
;       for (int i = 0; i < 4; ++i) { sfr[i] = *(const u32x4*)(sf + (size_t)(4 * i) * 128); sbr[i] = *(const u32x4*)(sb + (size_t)(4 * i) * 128); } }
;     LBAR();
; __global__ void __launch_bounds__(NWAVES * 64, 2) mega_fwd(Args args) {
;     ...
;                 const int b = U >> 7, h = (U >> 5) & 3, c = U & 31;
;                 const float lgf = -log2f(1.f + expf(-dec_f[l * 4 + h])), lgb = -log2f(1.f + expf(-dec_b[l * 4 + h]));
.LBB0_502:
	s_bfe_u32 s15, s6, 0x20005
	s_or_b32 s16, s15, s9
	v_readlane_b32 s52, v252, 10
	s_ashr_i32 s0, s6, 7
	s_and_b32 s20, s6, 31
	s_lshl_b64 s[6:7], s[16:17], 2
	v_readlane_b32 s62, v252, 20
	v_readlane_b32 s63, v252, 21
	s_add_u32 s22, s62, s6
	s_addc_u32 s23, s63, s7
	global_load_dword v2, v3, s[22:23]
	s_mov_b32 s5, 0xbfb8aa3b
	s_mov_b32 s16, 0x42ce8ed0
	s_mov_b32 s21, 0xc2b17218
	v_readlane_b32 s64, v252, 22
	v_readlane_b32 s65, v252, 23
	s_add_u32 s6, s64, s6
	s_addc_u32 s7, s65, s7
	global_load_dword v56, v3, s[6:7]
	v_mov_b32_e32 v140, v0
	v_readlane_b32 s37, v255, 0
	s_movk_i32 s33, 0x110
	v_readlane_b32 s53, v252, 11
	v_readlane_b32 s54, v252, 12
	v_readlane_b32 s55, v252, 13
	v_readlane_b32 s56, v252, 14
	v_readlane_b32 s57, v252, 15
	v_readlane_b32 s58, v252, 16
	v_readlane_b32 s59, v252, 17
	v_readlane_b32 s60, v252, 18
	v_readlane_b32 s61, v252, 19
	v_readlane_b32 s66, v252, 24
	v_readlane_b32 s67, v252, 25
	s_waitcnt vmcnt(1)
	v_mul_f32_e32 v52, 0xbfb8aa3b, v2
	v_fma_f32 v53, v2, s5, -v52
	v_rndne_f32_e32 v54, v52
	v_fmac_f32_e32 v53, 0xb2a5705f, v2
	v_sub_f32_e32 v52, v52, v54
	v_add_f32_e32 v52, v52, v53
	v_cvt_i32_f32_e32 v54, v54
	v_exp_f32_e32 v52, v52
	v_cmp_nlt_f32_e32 vcc, s16, v2
	v_ldexp_f32 v52, v52, v54
	s_nop 0
	v_cndmask_b32_e32 v52, 0, v52, vcc
	v_cmp_ngt_f32_e32 vcc, s21, v2
	s_nop 1
	v_cndmask_b32_e32 v2, v225, v52, vcc
	v_add_f32_e32 v2, 1.0, v2
	v_cmp_gt_f32_e32 vcc, s35, v2
	s_and_b64 s[22:23], vcc, exec
	s_cselect_b32 s1, 32, 0
	v_ldexp_f32 v2, v2, s1
	v_log_f32_e32 v54, v2
	v_cndmask_b32_e32 v53, 0, v226, vcc
	v_ashrrev_i32_e32 v2, 6, v140
	v_bfe_u32 v52, v140, 4, 2
	v_and_b32_e32 v148, 15, v140
	v_readfirstlane_b32 s14, v2
	v_lshl_or_b32 v144, v2, 4, v52
	v_lshlrev_b32_e32 v2, 4, v148
	v_add_u32_e32 v57, s37, v2
	v_mul_lo_u32 v58, v144, s33
	v_add_u32_e32 v52, 0, v2
	v_sub_f32_e32 v149, v54, v53
	v_add_u32_e32 v53, v57, v58
	s_movk_i32 s1, 0x140
	v_mad_u64_u32 v[54:55], s[6:7], v144, s1, v[52:53]
	v_add_u32_e32 v55, 0x440, v58
	v_add_u32_e32 v136, v52, v58
	v_add_u32_e32 v59, 0x880, v58
	ds_write_b128 v53, v[16:19]
	ds_write_b128 v136, v[4:7]
	ds_write_b128 v54, v[8:11] offset:34816
	v_add_u32_e32 v4, v57, v55
	v_add_u32_e32 v137, v52, v55
	v_add_u32_e32 v5, v57, v59
	v_add_u32_e32 v138, v52, v59
	ds_write_b128 v4, v[12:15]
	ds_write_b128 v137, v[20:23]
	ds_write_b128 v54, v[28:31] offset:36096
	ds_write_b128 v5, v[40:43]
	ds_write_b128 v138, v[32:35]
	ds_write_b128 v54, v[36:39] offset:37376
	v_add_u32_e32 v58, 0xcc0, v58
	v_add_u32_e32 v6, v57, v58
	v_add_u32_e32 v139, v52, v58
	ds_write_b128 v6, v[24:27]
	ds_write_b128 v139, v[48:51]
	ds_write_b128 v54, v[44:47] offset:38656
	v_bfe_u32 v147, v140, 5, 1
	v_lshrrev_b32_e32 v141, 2, v140
	s_waitcnt vmcnt(0)
	v_mul_f32_e32 v4, 0xbfb8aa3b, v56
	v_fma_f32 v5, v56, s5, -v4
	v_rndne_f32_e32 v7, v4
	v_fmac_f32_e32 v5, 0xb2a5705f, v56
	v_sub_f32_e32 v4, v4, v7
	v_add_f32_e32 v4, v4, v5
	v_cvt_i32_f32_e32 v7, v7
	v_exp_f32_e32 v4, v4
	v_cmp_nlt_f32_e32 vcc, s16, v56
	v_ldexp_f32 v4, v4, v7
	s_nop 0
	v_cndmask_b32_e32 v4, 0, v4, vcc
	v_cmp_ngt_f32_e32 vcc, s21, v56
	s_nop 1
	v_cndmask_b32_e32 v4, v225, v4, vcc
	v_add_f32_e32 v4, 1.0, v4
	v_cmp_gt_f32_e32 vcc, s35, v4
	s_and_b64 s[6:7], vcc, exec
	s_cselect_b32 s5, 32, 0
	s_ashr_i32 s1, s0, 31
	v_ldexp_f32 v4, v4, s5
	s_lshl_b64 s[4:5], s[0:1], s4
	s_ashr_i32 s21, s27, 7
	s_bfe_u32 s22, s27, 0x20005
	s_and_b32 s23, s27, 31
	s_lshl_b32 s16, s20, 7
	s_lshl_b64 s[6:7], s[0:1], 12
	s_lshl_b64 s[4:5], s[4:5], 1
	v_readlane_b32 s1, v253, 33
	s_add_u32 s1, s1, s4
	v_readlane_b32 s4, v253, 32
	s_addc_u32 s4, s4, s5
	s_lshl_b32 s5, s20, 15
	s_lshl_b32 s26, s15, 20
	s_or_b32 s5, s26, s5
	s_add_u32 s28, s1, s5
	s_addc_u32 s29, s4, 0
	s_lshl_b32 s1, s14, 6
	s_and_b32 s26, s1, 64
	v_log_f32_e32 v4, v4
	s_lshl_b32 s30, s14, 4
	s_lshl_b32 s1, s26, 2
	s_or_b32 s6, s6, s16
	s_lshl_b32 s16, s15, 8
	s_lshl_b32 s4, s15, 9
	s_and_b32 s14, s30, 0xffffffe0
	s_add_i32 s1, s1, 0
	s_add_u32 s4, s10, s4
	v_cndmask_b32_e32 v5, 0, v226, vcc
	s_addc_u32 s5, s11, 0
	v_sub_f32_e32 v150, v4, v5
	s_cmp_gt_i32 s27, -1
	v_ashrrev_i32_e32 v145, 31, v144
	v_lshlrev_b64 v[4:5], 8, v[144:145]
	v_lshl_add_u64 v[4:5], s[28:29], 0, v[4:5]
	v_lshl_add_u64 v[4:5], v[4:5], 0, v[2:3]
	s_mov_b32 s27, 0x400000
	v_add_co_u32_e32 v8, vcc, s27, v4
	s_mov_b64 s[28:29], 0x400000
	s_nop 0
	v_addc_co_u32_e32 v9, vcc, 0, v5, vcc
	v_lshl_add_u64 v[6:7], v[4:5], 0, s[28:29]
	global_load_dwordx4 v[72:75], v[4:5], off
	global_load_dwordx4 v[76:79], v[8:9], off
	global_load_dwordx4 v[80:83], v[4:5], off offset:1024
	global_load_dwordx4 v[84:87], v[6:7], off offset:1024
	global_load_dwordx4 v[88:91], v[4:5], off offset:2048
	global_load_dwordx4 v[92:95], v[6:7], off offset:2048
	global_load_dwordx4 v[96:99], v[4:5], off offset:3072
	global_load_dwordx4 v[128:131], v[6:7], off offset:3072
	v_mov_b32_e32 v4, s30
	s_movk_i32 s27, 0xffe0
	v_bfi_b32 v154, s27, v4, v140
	v_mul_lo_u32 v4, v154, s33
	v_lshlrev_b32_e32 v5, 4, v147
	s_waitcnt lgkmcnt(0)
	s_barrier
; #define RLAS __attribute__((address_space(3)))
; #define RMFMA(a, b, c) __builtin_amdgcn_mfma_f32_32x32x16_bf16(a, b, c, 0, 0, 0)
; __device__ __forceinline__ void out_unit(RLAS unsigned char* L, int b, int h, int c, const bf16_t* QR, bf16_t* PR, const bf16_t* KR, const bf16_t* VR, const bf16_t* GR, const bf16_t* ST, size_t stbatch, const float* gnw, float lgf, float lgb, OutRegs& PF, bool is_first, bool has_next, int nb, int nh ...
;     ...
;     bf16x8 qf[8];
; #pragma unroll
;     for (int ks = 0; ks < 8; ++ks) qf[ks] = *(const RLAS bf16x8*)(R2 + (32 * ib + r) * RS + (16 * ks + 8 * h2) * 2);
;     bf16x8 P[4][2];
;     const int iq = 32 * ib + r;
;     float cfm[3], cbp[3];
; #pragma unroll
;     for (int e = 0; e < 3; ++e) { cfm[e] = __builtin_amdgcn_exp2f(-lgf * (float)(e + 1)); cbp[e] = __builtin_amdgcn_exp2f(lgb * (float)(e + 1)); }
;     { f32x16 X[4];
; #pragma unroll
;       for (int jb = 0; jb < 4; ++jb)
; #pragma unroll
;           for (int g = 0; g < 16; ++g) X[jb][g] = 0.f;
; #pragma unroll
;       for (int ks = 0; ks < 8; ++ks) { bf16x8 a[4];
; #pragma unroll
;           for (int jb = 0; jb < 4; ++jb) a[jb] = *(const RLAS bf16x8*)(R0 + (32 * jb + r) * RS + (16 * ks + 8 * h2) * 2);
; #pragma unroll
;           for (int jb = 0; jb < 4; ++jb) X[jb] = RMFMA(a[jb], qf[ks], X[jb]); }
; #pragma unroll
;       for (int jb = 0; jb < 4; ++jb) {
; #pragma unroll
;           for (int q4 = 0; q4 < 4; ++q4) {
;               const int d0 = iq - (32 * jb + 8 * q4 + 4 * h2); const float fd = (float)d0, Ff = __builtin_amdgcn_exp2f(lgf * fd), Fb = __builtin_amdgcn_exp2f(-lgb * fd);
;               X[jb][4 * q4 + 0] *= d0 >= 0 ? Ff : Fb;             X[jb][4 * q4 + 1] *= d0 >= 1 ? Ff * cfm[0] : Fb * cbp[0];
;               X[jb][4 * q4 + 2] *= d0 >= 2 ? Ff * cfm[1] : Fb * cbp[1]; X[jb][4 * q4 + 3] *= d0 >= 3 ? Ff * cfm[2] : Fb * cbp[2]; }
	v_add3_u32 v4, s37, v4, v5
	ds_read_b128 v[68:71], v4
	ds_read_b128 v[124:127], v4 offset:32
	ds_read_b128 v[120:123], v4 offset:64
	ds_read_b128 v[116:119], v4 offset:96
	ds_read_b128 v[112:115], v4 offset:128
	ds_read_b128 v[108:111], v4 offset:160
	ds_read_b128 v[104:107], v4 offset:192
	ds_read_b128 v[100:103], v4 offset:224
	v_add_f32_e32 v4, v149, v149
	v_exp_f32_e32 v132, v4
	v_mul_f32_e32 v4, -2.0, v150
	v_and_b32_e32 v151, 31, v140
	v_exp_f32_e32 v134, v4
	v_mul_f32_e32 v4, 0x40400000, v149
	v_add_u32_e32 v152, 0, v5
	v_exp_f32_e32 v133, v4
	v_mul_f32_e32 v4, 0xc0400000, v150
	v_mad_u32_u24 v153, v151, s33, v152
	v_exp_f32_e32 v135, v4
	ds_read_b128 v[4:7], v153 offset:8704
	ds_read_b128 v[8:11], v153 offset:17408
	ds_read_b128 v[12:15], v153 offset:26112
	ds_read_b128 v[16:19], v153
	ds_read_b128 v[156:159], v153 offset:32
	s_waitcnt lgkmcnt(1)
	v_mfma_f32_32x32x16_bf16 v[52:67], v[16:19], v[68:71], 0
	ds_read_b128 v[160:163], v153 offset:8736
	ds_read_b128 v[164:167], v153 offset:17440
	ds_read_b128 v[168:171], v153 offset:26144
	v_exp_f32_e32 v143, v149
	v_exp_f32_e64 v146, -v150
	v_and_b32_e32 v142, 16, v140
	s_movk_i32 s27, 0x6000
	v_mfma_f32_32x32x16_bf16 v[36:51], v[4:7], v[68:71], 0
	v_mfma_f32_32x32x16_bf16 v[20:35], v[8:11], v[68:71], 0
	v_mfma_f32_32x32x16_bf16 v[4:19], v[12:15], v[68:71], 0
	s_waitcnt lgkmcnt(3)
	v_mfma_f32_32x32x16_bf16 v[52:67], v[156:159], v[124:127], v[52:67]
	s_waitcnt lgkmcnt(2)
	v_mfma_f32_32x32x16_bf16 v[36:51], v[160:163], v[124:127], v[36:51]
	s_waitcnt lgkmcnt(1)
	v_mfma_f32_32x32x16_bf16 v[20:35], v[164:167], v[124:127], v[20:35]
	s_waitcnt lgkmcnt(0)
	v_mfma_f32_32x32x16_bf16 v[4:19], v[168:171], v[124:127], v[4:19]
	ds_read_b128 v[156:159], v153 offset:64
	ds_read_b128 v[160:163], v153 offset:8768
	ds_read_b128 v[164:167], v153 offset:17472
	ds_read_b128 v[168:171], v153 offset:26176
	s_waitcnt lgkmcnt(3)
	v_mfma_f32_32x32x16_bf16 v[52:67], v[156:159], v[120:123], v[52:67]
	s_waitcnt lgkmcnt(2)
	v_mfma_f32_32x32x16_bf16 v[36:51], v[160:163], v[120:123], v[36:51]
	s_waitcnt lgkmcnt(1)
	v_mfma_f32_32x32x16_bf16 v[20:35], v[164:167], v[120:123], v[20:35]
	s_waitcnt lgkmcnt(0)
	v_mfma_f32_32x32x16_bf16 v[4:19], v[168:171], v[120:123], v[4:19]
	ds_read_b128 v[156:159], v153 offset:96
	ds_read_b128 v[160:163], v153 offset:8800
	ds_read_b128 v[164:167], v153 offset:17504
	ds_read_b128 v[168:171], v153 offset:26208
	s_waitcnt lgkmcnt(3)
	v_mfma_f32_32x32x16_bf16 v[52:67], v[156:159], v[116:119], v[52:67]
	s_waitcnt lgkmcnt(2)
	v_mfma_f32_32x32x16_bf16 v[36:51], v[160:163], v[116:119], v[36:51]
	s_waitcnt lgkmcnt(1)
	v_mfma_f32_32x32x16_bf16 v[20:35], v[164:167], v[116:119], v[20:35]
	s_waitcnt lgkmcnt(0)
	v_mfma_f32_32x32x16_bf16 v[4:19], v[168:171], v[116:119], v[4:19]
	ds_read_b128 v[156:159], v153 offset:128
	ds_read_b128 v[160:163], v153 offset:8832
	ds_read_b128 v[164:167], v153 offset:17536
	ds_read_b128 v[168:171], v153 offset:26240
	s_waitcnt lgkmcnt(3)
	v_mfma_f32_32x32x16_bf16 v[52:67], v[156:159], v[112:115], v[52:67]
	s_waitcnt lgkmcnt(2)
	v_mfma_f32_32x32x16_bf16 v[36:51], v[160:163], v[112:115], v[36:51]
	s_waitcnt lgkmcnt(1)
	v_mfma_f32_32x32x16_bf16 v[20:35], v[164:167], v[112:115], v[20:35]
	s_waitcnt lgkmcnt(0)
	v_mfma_f32_32x32x16_bf16 v[4:19], v[168:171], v[112:115], v[4:19]
	ds_read_b128 v[156:159], v153 offset:160
	ds_read_b128 v[160:163], v153 offset:8864
	ds_read_b128 v[164:167], v153 offset:17568
	ds_read_b128 v[168:171], v153 offset:26272
	s_waitcnt lgkmcnt(3)
	v_mfma_f32_32x32x16_bf16 v[52:67], v[156:159], v[108:111], v[52:67]
	s_waitcnt lgkmcnt(2)
	v_mfma_f32_32x32x16_bf16 v[36:51], v[160:163], v[108:111], v[36:51]
	s_waitcnt lgkmcnt(1)
	v_mfma_f32_32x32x16_bf16 v[20:35], v[164:167], v[108:111], v[20:35]
	s_waitcnt lgkmcnt(0)
	v_mfma_f32_32x32x16_bf16 v[4:19], v[168:171], v[108:111], v[4:19]
	ds_read_b128 v[156:159], v153 offset:192
	ds_read_b128 v[160:163], v153 offset:8896
	ds_read_b128 v[164:167], v153 offset:17600
	ds_read_b128 v[168:171], v153 offset:26304
	s_waitcnt lgkmcnt(3)
	v_mfma_f32_32x32x16_bf16 v[52:67], v[156:159], v[104:107], v[52:67]
	s_waitcnt lgkmcnt(2)
	v_mfma_f32_32x32x16_bf16 v[36:51], v[160:163], v[104:107], v[36:51]
	s_waitcnt lgkmcnt(1)
	v_mfma_f32_32x32x16_bf16 v[20:35], v[164:167], v[104:107], v[20:35]
	s_waitcnt lgkmcnt(0)
	v_mfma_f32_32x32x16_bf16 v[4:19], v[168:171], v[104:107], v[4:19]
	ds_read_b128 v[156:159], v153 offset:224
	ds_read_b128 v[160:163], v153 offset:8928
	ds_read_b128 v[164:167], v153 offset:17632
	ds_read_b128 v[168:171], v153 offset:26336
	v_lshlrev_b32_e32 v153, 2, v147
	v_sub_u32_e32 v147, v154, v153
	v_cvt_f32_i32_e32 v155, v147
	v_cmp_gt_i32_e32 vcc, 0, v147
	v_cmp_lt_i32_e64 s[38:39], 0, v147
	v_mul_f32_e64 v154, -v149, v155
	s_waitcnt lgkmcnt(3)
	v_mfma_f32_32x32x16_bf16 v[52:67], v[156:159], v[100:103], v[52:67]
	v_mul_f32_e32 v155, v150, v155
	v_exp_f32_e32 v154, v154
	v_exp_f32_e32 v156, v155
	v_mul_f32_e32 v155, v143, v154
	v_mul_f32_e32 v157, v146, v156
	v_cndmask_b32_e64 v159, v157, v155, s[38:39]
	v_cndmask_b32_e32 v158, v154, v156, vcc
	v_cmp_lt_i32_e32 vcc, 1, v147
	v_cmp_lt_i32_e64 s[38:39], 2, v147
	v_pk_mul_f32 v[154:155], v[132:133], v[154:155] op_sel_hi:[1,0]
	v_pk_mul_f32 v[156:157], v[134:135], v[156:157] op_sel_hi:[1,0]
	s_nop 0
	v_pk_mul_f32 v[52:53], v[158:159], v[52:53]
	v_cndmask_b32_e64 v155, v157, v155, s[38:39]
	v_cndmask_b32_e32 v154, v156, v154, vcc
	v_pk_mul_f32 v[54:55], v[154:155], v[54:55]
	v_add_u32_e32 v155, -8, v147
	v_cvt_f32_i32_e32 v156, v155
	v_cmp_gt_i32_e32 vcc, 0, v155
	v_cmp_lt_i32_e64 s[38:39], 0, v155
	s_waitcnt lgkmcnt(2)
; __device__ __forceinline__ unsigned pkbf(float lo, float hi) { const f32x2r v = {lo, hi}; return __builtin_bit_cast(unsigned, __builtin_convertvector(v, bf16x2r)); }
; __device__ __forceinline__ void out_unit(RLAS unsigned char* L, int b, int h, int c, const bf16_t* QR, bf16_t* PR, const bf16_t* KR, const bf16_t* VR, const bf16_t* GR, const bf16_t* ST, size_t stbatch, const float* gnw, float lgf, float lgb, OutRegs& PF, bool is_first, bool has_next, int nb, int nh ...
;     ...
;       for (int jb = 0; jb < 4; ++jb) {
; #pragma unroll
;           for (int q4 = 0; q4 < 4; ++q4) {
;               const int d0 = iq - (32 * jb + 8 * q4 + 4 * h2); const float fd = (float)d0, Ff = __builtin_amdgcn_exp2f(lgf * fd), Fb = __builtin_amdgcn_exp2f(-lgb * fd);
;               X[jb][4 * q4 + 0] *= d0 >= 0 ? Ff : Fb;             X[jb][4 * q4 + 1] *= d0 >= 1 ? Ff * cfm[0] : Fb * cbp[0];
;               X[jb][4 * q4 + 2] *= d0 >= 2 ? Ff * cfm[1] : Fb * cbp[1]; X[jb][4 * q4 + 3] *= d0 >= 3 ? Ff * cfm[2] : Fb * cbp[2]; }
; #pragma unroll
;           for (int s = 0; s < 2; ++s) { u32x4 pw; pw.x = pkbf(X[jb][8 * s + 0], X[jb][8 * s + 1]); pw.y = pkbf(X[jb][8 * s + 2], X[jb][8 * s + 3]); pw.z = pkbf(X[jb][8 * s + 4], X[jb][8 * s + 5]); pw.w = pkbf(X[jb][8 * s + 6], X[jb][8 * s + 7]);
;               P[jb][s] = __builtin_bit_cast(bf16x8, pw); } } }
	v_mfma_f32_32x32x16_bf16 v[36:51], v[160:163], v[100:103], v[36:51]
	v_mul_f32_e64 v154, -v149, v156
	v_mul_f32_e32 v156, v150, v156
	v_exp_f32_e32 v154, v154
	v_exp_f32_e32 v156, v156
	v_mul_f32_e32 v157, v143, v154
	v_mul_f32_e32 v158, v146, v156
	v_cndmask_b32_e64 v159, v158, v157, s[38:39]
	v_cndmask_b32_e32 v158, v154, v156, vcc
	v_pk_mul_f32 v[158:159], v[158:159], v[56:57]
	v_cmp_lt_i32_e32 vcc, 1, v155
	v_cmp_lt_i32_e64 s[38:39], 2, v155
	v_pk_mul_f32 v[56:57], v[132:133], v[154:155] op_sel_hi:[1,0]
	v_pk_mul_f32 v[154:155], v[134:135], v[156:157] op_sel_hi:[1,0]
	s_waitcnt lgkmcnt(1)
	v_mfma_f32_32x32x16_bf16 v[20:35], v[164:167], v[100:103], v[20:35]
	v_cndmask_b32_e64 v57, v155, v57, s[38:39]
	v_cndmask_b32_e32 v56, v154, v56, vcc
	v_mul_f32_e64 v154, v56, v58
	v_mul_f32_e64 v155, v57, v59
	v_add_u32_e32 v57, -16, v147
	v_cvt_f32_i32_e32 v58, v57
	v_cmp_gt_i32_e32 vcc, 0, v57
	v_cmp_lt_i32_e64 s[38:39], 0, v57
	s_waitcnt lgkmcnt(0)
	v_mfma_f32_32x32x16_bf16 v[4:19], v[168:171], v[100:103], v[4:19]
	v_mul_f32_e64 v56, -v149, v58
	v_mul_f32_e32 v58, v150, v58
	v_exp_f32_e32 v56, v56
	v_exp_f32_e32 v58, v58
	v_mul_f32_e32 v59, v143, v56
	v_mul_f32_e32 v156, v146, v58
	v_cndmask_b32_e64 v157, v156, v59, s[38:39]
	v_cndmask_b32_e32 v156, v56, v58, vcc
	v_cmp_lt_i32_e32 vcc, 1, v57
	v_cmp_lt_i32_e64 s[38:39], 2, v57
	v_pk_mul_f32 v[56:57], v[132:133], v[56:57] op_sel_hi:[1,0]
	v_pk_mul_f32 v[58:59], v[134:135], v[58:59] op_sel_hi:[1,0]
	v_pk_mul_f32 v[60:61], v[156:157], v[60:61]
	v_cndmask_b32_e64 v57, v59, v57, s[38:39]
	v_cndmask_b32_e32 v56, v58, v56, vcc
	v_pk_mul_f32 v[62:63], v[56:57], v[62:63]
	v_subrev_u32_e32 v57, 24, v147
	v_cvt_f32_i32_e32 v58, v57
	v_cmp_gt_i32_e32 vcc, 0, v57
	v_cmp_lt_i32_e64 s[38:39], 0, v57
	v_mul_f32_e64 v56, -v149, v58
	v_mul_f32_e32 v58, v150, v58
	v_exp_f32_e32 v56, v56
	v_exp_f32_e32 v58, v58
	v_mul_f32_e32 v59, v143, v56
	v_mul_f32_e32 v156, v146, v58
	v_cndmask_b32_e64 v157, v156, v59, s[38:39]
	v_cndmask_b32_e32 v156, v56, v58, vcc
	v_cmp_lt_i32_e32 vcc, 1, v57
	v_cmp_lt_i32_e64 s[38:39], 2, v57
	v_pk_mul_f32 v[56:57], v[132:133], v[56:57] op_sel_hi:[1,0]
	v_pk_mul_f32 v[58:59], v[134:135], v[58:59] op_sel_hi:[1,0]
	v_pk_mul_f32 v[64:65], v[156:157], v[64:65]
	v_cndmask_b32_e64 v57, v59, v57, s[38:39]
	v_cndmask_b32_e32 v56, v58, v56, vcc
	v_pk_mul_f32 v[66:67], v[56:57], v[66:67]
	v_cvt_pk_bf16_f32 v56, v52, v53
	v_cvt_pk_bf16_f32 v52, v60, v61
	v_subrev_u32_e32 v61, 32, v147
	v_cvt_pk_bf16_f32 v53, v62, v63
	v_cvt_f32_i32_e32 v62, v61
	v_cvt_pk_bf16_f32 v57, v54, v55
	v_cvt_pk_bf16_f32 v54, v64, v65
	v_cmp_gt_i32_e32 vcc, 0, v61
	v_mul_f32_e64 v60, -v149, v62
	v_mul_f32_e32 v62, v150, v62
	v_exp_f32_e32 v60, v60
	v_exp_f32_e32 v62, v62
	v_cmp_lt_i32_e64 s[38:39], 0, v61
	v_cvt_pk_bf16_f32 v58, v158, v159
	v_mul_f32_e32 v63, v143, v60
	v_mul_f32_e32 v64, v146, v62
	v_cndmask_b32_e64 v65, v64, v63, s[38:39]
	v_cndmask_b32_e32 v64, v60, v62, vcc
	v_cmp_lt_i32_e32 vcc, 1, v61
	v_cmp_lt_i32_e64 s[38:39], 2, v61
	v_pk_mul_f32 v[60:61], v[132:133], v[60:61] op_sel_hi:[1,0]
	v_pk_mul_f32 v[62:63], v[134:135], v[62:63] op_sel_hi:[1,0]
	v_pk_mul_f32 v[36:37], v[64:65], v[36:37]
	v_cndmask_b32_e64 v61, v63, v61, s[38:39]
	v_cndmask_b32_e32 v60, v62, v60, vcc
	v_pk_mul_f32 v[38:39], v[60:61], v[38:39]
	v_subrev_u32_e32 v61, 40, v147
	v_cvt_f32_i32_e32 v62, v61
	v_cmp_gt_i32_e32 vcc, 0, v61
	v_cmp_lt_i32_e64 s[38:39], 0, v61
	v_cvt_pk_bf16_f32 v59, v154, v155
	v_mul_f32_e64 v60, -v149, v62
	v_mul_f32_e32 v62, v150, v62
	v_exp_f32_e32 v60, v60
	v_exp_f32_e32 v62, v62
	v_cvt_pk_bf16_f32 v55, v66, v67
	v_mul_f32_e32 v63, v143, v60
	v_mul_f32_e32 v64, v146, v62
	v_cndmask_b32_e64 v65, v64, v63, s[38:39]
	v_cndmask_b32_e32 v64, v60, v62, vcc
	v_pk_mul_f32 v[64:65], v[64:65], v[40:41]
	v_cmp_lt_i32_e32 vcc, 1, v61
	v_cmp_lt_i32_e64 s[38:39], 2, v61
	v_pk_mul_f32 v[40:41], v[132:133], v[60:61] op_sel_hi:[1,0]
	v_pk_mul_f32 v[60:61], v[134:135], v[62:63] op_sel_hi:[1,0]
	s_nop 0
	v_cndmask_b32_e64 v41, v61, v41, s[38:39]
	v_cndmask_b32_e32 v40, v60, v40, vcc
	v_pk_mul_f32 v[60:61], v[40:41], v[42:43]
	v_subrev_u32_e32 v41, 48, v147
	v_cvt_f32_i32_e32 v42, v41
	v_cmp_gt_i32_e32 vcc, 0, v41
	v_cmp_lt_i32_e64 s[38:39], 0, v41
	v_mul_f32_e64 v40, -v149, v42
	v_mul_f32_e32 v42, v150, v42
	v_exp_f32_e32 v40, v40
	v_exp_f32_e32 v42, v42
	v_mul_f32_e32 v43, v143, v40
	v_mul_f32_e32 v62, v146, v42
	v_cndmask_b32_e64 v63, v62, v43, s[38:39]
	v_cndmask_b32_e32 v62, v40, v42, vcc
	v_cmp_lt_i32_e32 vcc, 1, v41
	v_cmp_lt_i32_e64 s[38:39], 2, v41
	v_pk_mul_f32 v[40:41], v[132:133], v[40:41] op_sel_hi:[1,0]
	v_pk_mul_f32 v[42:43], v[134:135], v[42:43] op_sel_hi:[1,0]
	v_pk_mul_f32 v[44:45], v[62:63], v[44:45]
	v_cndmask_b32_e64 v41, v43, v41, s[38:39]
	v_cndmask_b32_e32 v40, v42, v40, vcc
	v_pk_mul_f32 v[46:47], v[40:41], v[46:47]
	v_subrev_u32_e32 v41, 56, v147
	v_cvt_f32_i32_e32 v42, v41
	v_cmp_gt_i32_e32 vcc, 0, v41
	v_cmp_lt_i32_e64 s[38:39], 0, v41
	v_mul_f32_e64 v40, -v149, v42
	v_mul_f32_e32 v42, v150, v42
	v_exp_f32_e32 v40, v40
	v_exp_f32_e32 v42, v42
	v_mul_f32_e32 v43, v143, v40
	v_mul_f32_e32 v62, v146, v42
	v_cndmask_b32_e64 v63, v62, v43, s[38:39]
	v_cndmask_b32_e32 v62, v40, v42, vcc
	v_cmp_lt_i32_e32 vcc, 1, v41
	v_cmp_lt_i32_e64 s[38:39], 2, v41
	v_pk_mul_f32 v[40:41], v[132:133], v[40:41] op_sel_hi:[1,0]
	v_pk_mul_f32 v[42:43], v[134:135], v[42:43] op_sel_hi:[1,0]
	v_pk_mul_f32 v[48:49], v[62:63], v[48:49]
	v_cndmask_b32_e64 v41, v43, v41, s[38:39]
	v_cndmask_b32_e32 v40, v42, v40, vcc
	v_pk_mul_f32 v[50:51], v[40:41], v[50:51]
	v_cvt_pk_bf16_f32 v40, v36, v37
	v_cvt_pk_bf16_f32 v36, v44, v45
; __device__ __forceinline__ unsigned pkbf(float lo, float hi) { const f32x2r v = {lo, hi}; return __builtin_bit_cast(unsigned, __builtin_convertvector(v, bf16x2r)); }
; #define RMFMA(a, b, c) __builtin_amdgcn_mfma_f32_32x32x16_bf16(a, b, c, 0, 0, 0)
; __device__ __forceinline__ void out_unit(RLAS unsigned char* L, int b, int h, int c, const bf16_t* QR, bf16_t* PR, const bf16_t* KR, const bf16_t* VR, const bf16_t* GR, const bf16_t* ST, size_t stbatch, const float* gnw, float lgf, float lgb, OutRegs& PF, bool is_first, bool has_next, int nb, int nh ...
;     ...
;       for (int jb = 0; jb < 4; ++jb) {
; #pragma unroll
;           for (int q4 = 0; q4 < 4; ++q4) {
;               const int d0 = iq - (32 * jb + 8 * q4 + 4 * h2); const float fd = (float)d0, Ff = __builtin_amdgcn_exp2f(lgf * fd), Fb = __builtin_amdgcn_exp2f(-lgb * fd);
;               X[jb][4 * q4 + 0] *= d0 >= 0 ? Ff : Fb;             X[jb][4 * q4 + 1] *= d0 >= 1 ? Ff * cfm[0] : Fb * cbp[0];
;               X[jb][4 * q4 + 2] *= d0 >= 2 ? Ff * cfm[1] : Fb * cbp[1]; X[jb][4 * q4 + 3] *= d0 >= 3 ? Ff * cfm[2] : Fb * cbp[2]; }
; #pragma unroll
;           for (int s = 0; s < 2; ++s) { u32x4 pw; pw.x = pkbf(X[jb][8 * s + 0], X[jb][8 * s + 1]); pw.y = pkbf(X[jb][8 * s + 2], X[jb][8 * s + 3]); pw.z = pkbf(X[jb][8 * s + 4], X[jb][8 * s + 5]); pw.w = pkbf(X[jb][8 * s + 6], X[jb][8 * s + 7]);
;               P[jb][s] = __builtin_bit_cast(bf16x8, pw); } } }
;     f32x16 Z[2];
; #pragma unroll
;     for (int t = 0; t < 2; ++t)
; #pragma unroll
;         for (int g = 0; g < 16; ++g) Z[t][g] = 0.f;
;     { const int cb0 = (64 * dvh + 16 * gq + 4 * p) * 2;
; #pragma unroll
;       for (int jb = 0; jb < 4; ++jb)
; #pragma unroll
;           for (int s = 0; s < 2; ++s) { const bf16x8 v0 = trfragv(R1, 32 * jb + 16 * s + 4 * h2 + q, 8, cb0), v1 = trfragv(R1, 32 * jb + 16 * s + 4 * h2 + q, 8, cb0 + 64);
;               Z[0] = RMFMA(P[jb][s], v0, Z[0]); Z[1] = RMFMA(P[jb][s], v1, Z[1]); } }
	v_subrev_u32_e32 v45, 64, v147
	v_cvt_pk_bf16_f32 v37, v46, v47
	v_cvt_f32_i32_e32 v46, v45
	v_cvt_pk_bf16_f32 v41, v38, v39
	v_cvt_pk_bf16_f32 v38, v48, v49
	v_cmp_gt_i32_e32 vcc, 0, v45
	v_mul_f32_e64 v44, -v149, v46
	v_mul_f32_e32 v46, v150, v46
	v_exp_f32_e32 v44, v44
	v_exp_f32_e32 v46, v46
	v_cmp_lt_i32_e64 s[38:39], 0, v45
	v_cvt_pk_bf16_f32 v43, v60, v61
	v_mul_f32_e32 v47, v143, v44
	v_mul_f32_e32 v48, v146, v46
	v_cndmask_b32_e64 v49, v48, v47, s[38:39]
	v_cndmask_b32_e32 v48, v44, v46, vcc
	v_cmp_lt_i32_e32 vcc, 1, v45
	v_cmp_lt_i32_e64 s[38:39], 2, v45
	v_pk_mul_f32 v[44:45], v[132:133], v[44:45] op_sel_hi:[1,0]
	v_pk_mul_f32 v[46:47], v[134:135], v[46:47] op_sel_hi:[1,0]
	v_pk_mul_f32 v[20:21], v[48:49], v[20:21]
	v_cndmask_b32_e64 v45, v47, v45, s[38:39]
	v_cndmask_b32_e32 v44, v46, v44, vcc
	v_pk_mul_f32 v[22:23], v[44:45], v[22:23]
	v_add_u32_e32 v45, 0xffffffb8, v147
	v_cvt_f32_i32_e32 v46, v45
	v_cmp_gt_i32_e32 vcc, 0, v45
	v_cmp_lt_i32_e64 s[38:39], 0, v45
	v_cvt_pk_bf16_f32 v60, v20, v21
	v_mul_f32_e64 v44, -v149, v46
	v_mul_f32_e32 v46, v150, v46
	v_exp_f32_e32 v44, v44
	v_exp_f32_e32 v46, v46
	v_add_u32_e32 v21, 0xffffffa0, v147
	v_cvt_pk_bf16_f32 v61, v22, v23
	v_mul_f32_e32 v47, v143, v44
	v_mul_f32_e32 v48, v146, v46
	v_cndmask_b32_e64 v49, v48, v47, s[38:39]
	v_cndmask_b32_e32 v48, v44, v46, vcc
	v_cmp_lt_i32_e32 vcc, 1, v45
	v_cmp_lt_i32_e64 s[38:39], 2, v45
	v_pk_mul_f32 v[44:45], v[132:133], v[44:45] op_sel_hi:[1,0]
	v_pk_mul_f32 v[46:47], v[134:135], v[46:47] op_sel_hi:[1,0]
	v_pk_mul_f32 v[24:25], v[48:49], v[24:25]
	v_cndmask_b32_e64 v45, v47, v45, s[38:39]
	v_cndmask_b32_e32 v44, v46, v44, vcc
	v_pk_mul_f32 v[26:27], v[44:45], v[26:27]
	v_add_u32_e32 v45, 0xffffffb0, v147
	v_cvt_f32_i32_e32 v46, v45
	v_cmp_gt_i32_e32 vcc, 0, v45
	v_cmp_lt_i32_e64 s[38:39], 0, v45
	v_cvt_f32_i32_e32 v22, v21
	v_mul_f32_e64 v44, -v149, v46
	v_mul_f32_e32 v46, v150, v46
	v_exp_f32_e32 v44, v44
	v_exp_f32_e32 v46, v46
	v_mul_f32_e64 v20, -v149, v22
	v_mul_f32_e32 v22, v150, v22
	v_mul_f32_e32 v47, v143, v44
	v_mul_f32_e32 v48, v146, v46
	v_cndmask_b32_e64 v49, v48, v47, s[38:39]
	v_cndmask_b32_e32 v48, v44, v46, vcc
	v_cmp_lt_i32_e32 vcc, 1, v45
	v_cmp_lt_i32_e64 s[38:39], 2, v45
	v_pk_mul_f32 v[44:45], v[132:133], v[44:45] op_sel_hi:[1,0]
	v_pk_mul_f32 v[46:47], v[134:135], v[46:47] op_sel_hi:[1,0]
	v_exp_f32_e32 v20, v20
	v_cndmask_b32_e64 v45, v47, v45, s[38:39]
	v_cndmask_b32_e32 v44, v46, v44, vcc
	v_pk_mul_f32 v[30:31], v[44:45], v[30:31]
	v_add_u32_e32 v45, 0xffffffa8, v147
	v_cvt_f32_i32_e32 v46, v45
	v_exp_f32_e32 v22, v22
	v_pk_mul_f32 v[28:29], v[48:49], v[28:29]
	v_cmp_gt_i32_e32 vcc, 0, v45
	v_mul_f32_e64 v44, -v149, v46
	v_mul_f32_e32 v46, v150, v46
	v_exp_f32_e32 v44, v44
	v_exp_f32_e32 v46, v46
	v_cmp_lt_i32_e64 s[38:39], 0, v45
	v_cvt_pk_bf16_f32 v62, v24, v25
	v_mul_f32_e32 v47, v143, v44
	v_mul_f32_e32 v48, v146, v46
	v_cndmask_b32_e64 v49, v48, v47, s[38:39]
	v_cndmask_b32_e32 v48, v44, v46, vcc
	v_cmp_lt_i32_e32 vcc, 1, v45
	v_cmp_lt_i32_e64 s[38:39], 2, v45
	v_pk_mul_f32 v[44:45], v[132:133], v[44:45] op_sel_hi:[1,0]
	v_pk_mul_f32 v[46:47], v[134:135], v[46:47] op_sel_hi:[1,0]
	v_mul_f32_e32 v23, v143, v20
	v_cndmask_b32_e64 v45, v47, v45, s[38:39]
	v_cndmask_b32_e32 v44, v46, v44, vcc
	v_mul_f32_e32 v24, v146, v22
	v_cmp_gt_i32_e32 vcc, 0, v21
	v_cmp_lt_i32_e64 s[38:39], 0, v21
	v_cvt_pk_bf16_f32 v42, v64, v65
	v_cvt_pk_bf16_f32 v39, v50, v51
	v_cndmask_b32_e64 v25, v24, v23, s[38:39]
	v_cndmask_b32_e32 v24, v20, v22, vcc
	v_cmp_lt_i32_e32 vcc, 1, v21
	v_cmp_lt_i32_e64 s[38:39], 2, v21
	v_pk_mul_f32 v[20:21], v[132:133], v[20:21] op_sel_hi:[1,0]
	v_pk_mul_f32 v[22:23], v[134:135], v[22:23] op_sel_hi:[1,0]
	v_pk_mul_f32 v[4:5], v[24:25], v[4:5]
	v_cndmask_b32_e64 v21, v23, v21, s[38:39]
	v_cndmask_b32_e32 v20, v22, v20, vcc
	v_pk_mul_f32 v[6:7], v[20:21], v[6:7]
	v_add_u32_e32 v21, 0xffffff98, v147
	v_cvt_f32_i32_e32 v22, v21
	v_cmp_gt_i32_e32 vcc, 0, v21
	v_cmp_lt_i32_e64 s[38:39], 0, v21
	v_cvt_pk_bf16_f32 v64, v4, v5
	v_mul_f32_e64 v20, -v149, v22
	v_mul_f32_e32 v22, v150, v22
	v_exp_f32_e32 v20, v20
	v_exp_f32_e32 v22, v22
	v_lshlrev_b32_e32 v4, 2, v140
	v_and_b32_e32 v4, 12, v4
	v_mul_f32_e32 v23, v143, v20
	v_mul_f32_e32 v24, v146, v22
	v_cndmask_b32_e64 v25, v24, v23, s[38:39]
	v_cndmask_b32_e32 v24, v20, v22, vcc
	v_cmp_lt_i32_e32 vcc, 1, v21
	v_cmp_lt_i32_e64 s[38:39], 2, v21
	v_pk_mul_f32 v[20:21], v[132:133], v[20:21] op_sel_hi:[1,0]
	v_pk_mul_f32 v[22:23], v[134:135], v[22:23] op_sel_hi:[1,0]
	v_pk_mul_f32 v[8:9], v[24:25], v[8:9]
	v_cndmask_b32_e64 v21, v23, v21, s[38:39]
	v_cndmask_b32_e32 v20, v22, v20, vcc
	v_pk_mul_f32 v[10:11], v[20:21], v[10:11]
	v_add_u32_e32 v21, 0xffffff90, v147
	v_cvt_f32_i32_e32 v22, v21
	v_cmp_gt_i32_e32 vcc, 0, v21
	v_cmp_lt_i32_e64 s[38:39], 0, v21
	v_or3_b32 v4, v4, v142, s26
	v_mul_f32_e64 v20, -v149, v22
	v_mul_f32_e32 v22, v150, v22
	v_exp_f32_e32 v20, v20
	v_exp_f32_e32 v22, v22
	v_and_or_b32 v5, v141, 3, v153
	v_lshlrev_b32_e32 v4, 1, v4
	v_mul_f32_e32 v23, v143, v20
	v_mul_f32_e32 v24, v146, v22
	v_cndmask_b32_e64 v25, v24, v23, s[38:39]
	v_cndmask_b32_e32 v24, v20, v22, vcc
	v_cmp_lt_i32_e32 vcc, 1, v21
	v_cmp_lt_i32_e64 s[38:39], 2, v21
	v_pk_mul_f32 v[20:21], v[132:133], v[20:21] op_sel_hi:[1,0]
	v_pk_mul_f32 v[22:23], v[134:135], v[22:23] op_sel_hi:[1,0]
	v_pk_mul_f32 v[12:13], v[24:25], v[12:13]
	v_cndmask_b32_e64 v21, v23, v21, s[38:39]
	v_cndmask_b32_e32 v20, v22, v20, vcc
	v_pk_mul_f32 v[14:15], v[20:21], v[14:15]
	v_add_u32_e32 v21, 0xffffff88, v147
	v_cvt_f32_i32_e32 v22, v21
	v_cmp_gt_i32_e32 vcc, 0, v21
	v_cmp_lt_i32_e64 s[38:39], 0, v21
	v_mul_u32_u24_e32 v5, 0x140, v5
	v_mul_f32_e64 v20, -v149, v22
	v_mul_f32_e32 v22, v150, v22
	v_exp_f32_e32 v20, v20
	v_exp_f32_e32 v22, v22
	v_add3_u32 v140, 0, v5, v4
	v_cvt_pk_bf16_f32 v65, v6, v7
	v_mul_f32_e32 v23, v143, v20
	v_mul_f32_e32 v24, v146, v22
	v_cndmask_b32_e64 v25, v24, v23, s[38:39]
	v_cndmask_b32_e32 v24, v20, v22, vcc
	v_cmp_lt_i32_e32 vcc, 1, v21
	v_cmp_lt_i32_e64 s[38:39], 2, v21
	v_pk_mul_f32 v[20:21], v[132:133], v[20:21] op_sel_hi:[1,0]
	v_pk_mul_f32 v[22:23], v[134:135], v[22:23] op_sel_hi:[1,0]
	v_pk_mul_f32 v[16:17], v[24:25], v[16:17]
	v_cndmask_b32_e64 v21, v23, v21, s[38:39]
	v_cndmask_b32_e32 v20, v22, v20, vcc
	v_pk_mul_f32 v[18:19], v[20:21], v[18:19]
	ds_read_b64_tr_b16 v[4:5], v140 offset:34816
	ds_read_b64_tr_b16 v[6:7], v140 offset:37376
	ds_read_b64_tr_b16 v[20:21], v140 offset:34880
	ds_read_b64_tr_b16 v[22:23], v140 offset:37440
	v_pk_mul_f32 v[32:33], v[48:49], v[32:33]
	v_cvt_pk_bf16_f32 v66, v8, v9
	v_cvt_pk_bf16_f32 v67, v10, v11
	v_cvt_pk_bf16_f32 v48, v12, v13
	v_cvt_pk_bf16_f32 v49, v14, v15
	v_cvt_pk_bf16_f32 v50, v16, v17
	v_cvt_pk_bf16_f32 v51, v18, v19
	s_waitcnt lgkmcnt(2)
; #define RLAS __attribute__((address_space(3)))
; #define LBAR() do { asm volatile("s_waitcnt lgkmcnt(0)" ::: "memory"); __builtin_amdgcn_s_barrier(); asm volatile("" ::: "memory"); } while (0)
; #define RMFMA(a, b, c) __builtin_amdgcn_mfma_f32_32x32x16_bf16(a, b, c, 0, 0, 0)
; __device__ __forceinline__ void out_unit(RLAS unsigned char* L, int b, int h, int c, const bf16_t* QR, bf16_t* PR, const bf16_t* KR, const bf16_t* VR, const bf16_t* GR, const bf16_t* ST, size_t stbatch, const float* gnw, float lgf, float lgb, OutRegs& PF, bool is_first, bool has_next, int nb, int nh ...
;     ...
;     { const int cb0 = (64 * dvh + 16 * gq + 4 * p) * 2;
; #pragma unroll
;       for (int jb = 0; jb < 4; ++jb)
; #pragma unroll
;           for (int s = 0; s < 2; ++s) { const bf16x8 v0 = trfragv(R1, 32 * jb + 16 * s + 4 * h2 + q, 8, cb0), v1 = trfragv(R1, 32 * jb + 16 * s + 4 * h2 + q, 8, cb0 + 64);
;               Z[0] = RMFMA(P[jb][s], v0, Z[0]); Z[1] = RMFMA(P[jb][s], v1, Z[1]); } }
;     LBAR();
; #pragma unroll
;     for (int i = 0; i < 4; ++i) { *(RLAS u32x4*)(R0 + (grow + 4 * i) * RS + gch * 16) = sfr[i]; *(RLAS u32x4*)(R1 + (grow + 4 * i) * RS + gch * 16) = sbr[i]; }
;     LBAR();
;     u32x4 gwr[4];
;     { const bf16_t* gp0 = GR + (tok0 + grow) * GRP + h * 128 + gch * 8;
; #pragma unroll
;       for (int i = 0; i < 4; ++i) gwr[i] = *(const u32x4*)(gp0 + (size_t)(4 * i) * GRP); }
;     { f32x16 Yf[2], Yb[2];
; #pragma unroll
;       for (int t = 0; t < 2; ++t)
; #pragma unroll
;           for (int g = 0; g < 16; ++g) { Yf[t][g] = 0.f; Yb[t][g] = 0.f; }
;       const int rb0 = (64 * dvh + r) * RS + 16 * h2;
; #pragma unroll
;       for (int ks = 0; ks < 8; ++ks) {
;           const bf16x8 f0 = *(const RLAS bf16x8*)(R0 + rb0 + 32 * ks), f1 = *(const RLAS bf16x8*)(R0 + rb0 + 32 * RS + 32 * ks), b0 = *(const RLAS bf16x8*)(R1 + rb0 + 32 * ks), b1 = *(const RLAS bf16x8*)(R1 + rb0 + 32 * RS + 32 * ks);
;           Yf[0] = RMFMA(qf[ks], f0, Yf[0]); Yf[1] = RMFMA(qf[ks], f1, Yf[1]); Yb[0] = RMFMA(qf[ks], b0, Yb[0]); Yb[1] = RMFMA(qf[ks], b1, Yb[1]); }
;     ...
;     f32x4 w0 = *(const f32x4*)(gnw + h * 128 + gch * 8), w1 = *(const f32x4*)(gnw + h * 128 + gch * 8 + 4);
	v_mfma_f32_32x32x16_bf16 v[4:19], v[56:59], v[4:7], 0
	v_mul_f32_e64 v34, v44, v34
	v_mul_f32_e64 v35, v45, v35
	v_cvt_pk_bf16_f32 v63, v26, v27
	v_cvt_pk_bf16_f32 v44, v28, v29
	v_cvt_pk_bf16_f32 v45, v30, v31
	v_cvt_pk_bf16_f32 v46, v32, v33
	v_cvt_pk_bf16_f32 v47, v34, v35
	v_add_u32_e32 v141, 0x8800, v140
	s_waitcnt lgkmcnt(0)
	v_mfma_f32_32x32x16_bf16 v[20:35], v[56:59], v[20:23], 0
	ds_read_b64_tr_b16 v[56:57], v140 offset:39936
	ds_read_b64_tr_b16 v[58:59], v140 offset:42496
	ds_read_b64_tr_b16 v[132:133], v140 offset:40000
	ds_read_b64_tr_b16 v[134:135], v140 offset:42560
	s_waitcnt lgkmcnt(2)
	v_mfma_f32_32x32x16_bf16 v[4:19], v[52:55], v[56:59], v[4:19]
	s_waitcnt lgkmcnt(0)
	v_mfma_f32_32x32x16_bf16 v[20:35], v[52:55], v[132:135], v[20:35]
	ds_read_b64_tr_b16 v[52:53], v140 offset:45056
	ds_read_b64_tr_b16 v[54:55], v140 offset:47616
	ds_read_b64_tr_b16 v[56:57], v140 offset:45120
	ds_read_b64_tr_b16 v[58:59], v140 offset:47680
	s_waitcnt lgkmcnt(2)
	v_mfma_f32_32x32x16_bf16 v[4:19], v[40:43], v[52:55], v[4:19]
	s_waitcnt lgkmcnt(0)
	v_mfma_f32_32x32x16_bf16 v[20:35], v[40:43], v[56:59], v[20:35]
	ds_read_b64_tr_b16 v[40:41], v140 offset:50176
	ds_read_b64_tr_b16 v[42:43], v140 offset:52736
	ds_read_b64_tr_b16 v[52:53], v140 offset:50240
	ds_read_b64_tr_b16 v[54:55], v140 offset:52800
	s_waitcnt lgkmcnt(2)
	v_mfma_f32_32x32x16_bf16 v[4:19], v[36:39], v[40:43], v[4:19]
	s_waitcnt lgkmcnt(0)
	v_mfma_f32_32x32x16_bf16 v[20:35], v[36:39], v[52:55], v[20:35]
	ds_read_b64_tr_b16 v[36:37], v140 offset:55296
	ds_read_b64_tr_b16 v[38:39], v140 offset:57856
	ds_read_b64_tr_b16 v[40:41], v140 offset:55360
	ds_read_b64_tr_b16 v[42:43], v140 offset:57920
	s_waitcnt lgkmcnt(2)
	v_mfma_f32_32x32x16_bf16 v[4:19], v[60:63], v[36:39], v[4:19]
	s_waitcnt lgkmcnt(0)
	v_mfma_f32_32x32x16_bf16 v[20:35], v[60:63], v[40:43], v[20:35]
	ds_read_b64_tr_b16 v[36:37], v140 offset:60416
	ds_read_b64_tr_b16 v[38:39], v140 offset:62976
	ds_read_b64_tr_b16 v[40:41], v140 offset:60480
	ds_read_b64_tr_b16 v[42:43], v140 offset:63040
	s_waitcnt lgkmcnt(2)
	v_mfma_f32_32x32x16_bf16 v[4:19], v[44:47], v[36:39], v[4:19]
	s_waitcnt lgkmcnt(0)
	v_mfma_f32_32x32x16_bf16 v[20:35], v[44:47], v[40:43], v[20:35]
	ds_read_b64_tr_b16 v[36:37], v141 offset:30720
	ds_read_b64_tr_b16 v[38:39], v141 offset:33280
	ds_read_b64_tr_b16 v[40:41], v141 offset:30784
	ds_read_b64_tr_b16 v[42:43], v141 offset:33344
	s_waitcnt lgkmcnt(2)
	v_mfma_f32_32x32x16_bf16 v[4:19], v[64:67], v[36:39], v[4:19]
	s_waitcnt lgkmcnt(0)
	v_mfma_f32_32x32x16_bf16 v[20:35], v[64:67], v[40:43], v[20:35]
	ds_read_b64_tr_b16 v[36:37], v141 offset:35840
	ds_read_b64_tr_b16 v[38:39], v141 offset:38400
	ds_read_b64_tr_b16 v[40:41], v141 offset:35904
	ds_read_b64_tr_b16 v[42:43], v141 offset:38464
	s_waitcnt lgkmcnt(0)
	s_barrier
	s_waitcnt vmcnt(7)
	ds_write_b128 v136, v[72:75]
	s_waitcnt vmcnt(6)
	ds_write_b128 v136, v[76:79] offset:34816
	s_waitcnt vmcnt(5)
	ds_write_b128 v137, v[80:83]
	s_waitcnt vmcnt(4)
	ds_write_b128 v137, v[84:87] offset:34816
	s_waitcnt vmcnt(3)
	ds_write_b128 v138, v[88:91]
	s_waitcnt vmcnt(2)
	ds_write_b128 v138, v[92:95] offset:34816
	s_waitcnt vmcnt(1)
	ds_write_b128 v139, v[96:99]
	s_waitcnt vmcnt(0)
	ds_write_b128 v139, v[128:131] offset:34816
	s_waitcnt lgkmcnt(0)
	s_barrier
	s_waitcnt lgkmcnt(10)
	v_mfma_f32_32x32x16_bf16 v[4:19], v[48:51], v[36:39], v[4:19]
	v_lshl_add_u64 v[36:37], s[6:7], 0, v[144:145]
	v_readlane_b32 s6, v252, 32
	v_lshlrev_b64 v[146:147], 11, v[36:37]
	v_readlane_b32 s7, v252, 33
	s_nop 1
	v_lshl_add_u64 v[36:37], s[6:7], 0, v[146:147]
	v_lshl_add_u64 v[36:37], v[36:37], 0, s[16:17]
	v_lshl_add_u64 v[36:37], v[36:37], 0, v[2:3]
	s_movk_i32 s7, 0x2000
	v_add_co_u32_e32 v38, vcc, s7, v36
	s_movk_i32 s6, 0x4000
	s_nop 0
	v_addc_co_u32_e32 v39, vcc, 0, v37, vcc
	global_load_dwordx4 v[140:143], v[36:37], off
	global_load_dwordx4 v[136:139], v[38:39], off
	v_add_co_u32_e32 v38, vcc, s6, v36
	s_waitcnt lgkmcnt(8)
	v_mfma_f32_32x32x16_bf16 v[20:35], v[48:51], v[40:43], v[20:35]
	v_addc_co_u32_e32 v39, vcc, 0, v37, vcc
	v_add_co_u32_e32 v36, vcc, s27, v36
	global_load_dwordx4 v[132:135], v[38:39], off
	s_nop 0
	v_addc_co_u32_e32 v37, vcc, 0, v37, vcc
	global_load_dwordx4 v[128:131], v[36:37], off
	v_lshlrev_b32_e32 v180, 5, v148
	global_load_dwordx4 v[172:175], v180, s[4:5] offset:16
	global_load_dwordx4 v[176:179], v180, s[4:5]
	v_or_b32_e32 v36, s26, v151
	v_mad_u32_u24 v145, v36, s33, v152
	ds_read_b128 v[36:39], v145 offset:8704
	ds_read_b128 v[72:75], v145 offset:34816
	ds_read_b128 v[76:79], v145 offset:43520
	ds_read_b128 v[40:43], v145
	ds_read_b128 v[154:157], v145 offset:32
	s_waitcnt lgkmcnt(1)
	v_mfma_f32_32x32x16_bf16 v[52:67], v[68:71], v[40:43], 0
	ds_read_b128 v[158:161], v145 offset:8736
	ds_read_b128 v[162:165], v145 offset:34848
	ds_read_b128 v[166:169], v145 offset:43552
	v_mfma_f32_32x32x16_bf16 v[36:51], v[68:71], v[36:39], 0
	v_mfma_f32_32x32x16_bf16 v[84:99], v[68:71], v[72:75], 0
	v_mfma_f32_32x32x16_bf16 v[68:83], v[68:71], v[76:79], 0
	s_waitcnt lgkmcnt(3)
	v_mfma_f32_32x32x16_bf16 v[52:67], v[124:127], v[154:157], v[52:67]
	s_waitcnt lgkmcnt(2)
	v_mfma_f32_32x32x16_bf16 v[36:51], v[124:127], v[158:161], v[36:51]
	s_waitcnt lgkmcnt(1)
	v_mfma_f32_32x32x16_bf16 v[84:99], v[124:127], v[162:165], v[84:99]
	s_waitcnt lgkmcnt(0)
	v_mfma_f32_32x32x16_bf16 v[68:83], v[124:127], v[166:169], v[68:83]
	ds_read_b128 v[124:127], v145 offset:64
	ds_read_b128 v[154:157], v145 offset:8768
	ds_read_b128 v[158:161], v145 offset:34880
	ds_read_b128 v[162:165], v145 offset:43584
	s_waitcnt lgkmcnt(3)
	v_mfma_f32_32x32x16_bf16 v[52:67], v[120:123], v[124:127], v[52:67]
	s_waitcnt lgkmcnt(2)
; #define RLAS __attribute__((address_space(3)))
; #define RMFMA(a, b, c) __builtin_amdgcn_mfma_f32_32x32x16_bf16(a, b, c, 0, 0, 0)
; __device__ __forceinline__ void out_unit(RLAS unsigned char* L, int b, int h, int c, const bf16_t* QR, bf16_t* PR, const bf16_t* KR, const bf16_t* VR, const bf16_t* GR, const bf16_t* ST, size_t stbatch, const float* gnw, float lgf, float lgb, OutRegs& PF, bool is_first, bool has_next, int nb, int nh ...
;     ...
;       for (int ks = 0; ks < 8; ++ks) {
;           const bf16x8 f0 = *(const RLAS bf16x8*)(R0 + rb0 + 32 * ks), f1 = *(const RLAS bf16x8*)(R0 + rb0 + 32 * RS + 32 * ks), b0 = *(const RLAS bf16x8*)(R1 + rb0 + 32 * ks), b1 = *(const RLAS bf16x8*)(R1 + rb0 + 32 * RS + 32 * ks);
;           Yf[0] = RMFMA(qf[ks], f0, Yf[0]); Yf[1] = RMFMA(qf[ks], f1, Yf[1]); Yb[0] = RMFMA(qf[ks], b0, Yb[0]); Yb[1] = RMFMA(qf[ks], b1, Yb[1]); }
; #pragma unroll
;       for (int q4 = 0; q4 < 4; ++q4) { const int il0 = 32 * ib + 8 * q4 + 4 * h2;
;           const float sf0 = __builtin_amdgcn_exp2f(lgf * (float)(il0 + 1)), sb0 = __builtin_amdgcn_exp2f(lgb * (float)(128 - il0));
; #pragma unroll
;           for (int e = 0; e < 4; ++e) { const float sf = e ? sf0 * __builtin_amdgcn_exp2f(lgf * (float)e) : sf0, sb = e ? sb0 * __builtin_amdgcn_exp2f(-lgb * (float)e) : sb0; const int g = 4 * q4 + e;
; #pragma unroll
;               for (int t = 0; t < 2; ++t) Z[t][g] += sf * Yf[t][g] + sb * Yb[t][g]; } } }
	v_mfma_f32_32x32x16_bf16 v[36:51], v[120:123], v[154:157], v[36:51]
	s_waitcnt lgkmcnt(1)
	v_mfma_f32_32x32x16_bf16 v[84:99], v[120:123], v[158:161], v[84:99]
	s_waitcnt lgkmcnt(0)
	v_mfma_f32_32x32x16_bf16 v[68:83], v[120:123], v[162:165], v[68:83]
	ds_read_b128 v[120:123], v145 offset:96
	ds_read_b128 v[124:127], v145 offset:8800
	ds_read_b128 v[154:157], v145 offset:34912
	ds_read_b128 v[158:161], v145 offset:43616
	s_waitcnt lgkmcnt(3)
	v_mfma_f32_32x32x16_bf16 v[52:67], v[116:119], v[120:123], v[52:67]
	s_waitcnt lgkmcnt(2)
	v_mfma_f32_32x32x16_bf16 v[36:51], v[116:119], v[124:127], v[36:51]
	s_waitcnt lgkmcnt(1)
	v_mfma_f32_32x32x16_bf16 v[84:99], v[116:119], v[154:157], v[84:99]
	s_waitcnt lgkmcnt(0)
	v_mfma_f32_32x32x16_bf16 v[68:83], v[116:119], v[158:161], v[68:83]
	ds_read_b128 v[116:119], v145 offset:128
	ds_read_b128 v[120:123], v145 offset:8832
	ds_read_b128 v[124:127], v145 offset:34944
	ds_read_b128 v[154:157], v145 offset:43648
	s_waitcnt lgkmcnt(3)
	v_mfma_f32_32x32x16_bf16 v[52:67], v[112:115], v[116:119], v[52:67]
	s_waitcnt lgkmcnt(2)
	v_mfma_f32_32x32x16_bf16 v[36:51], v[112:115], v[120:123], v[36:51]
	s_waitcnt lgkmcnt(1)
	v_mfma_f32_32x32x16_bf16 v[84:99], v[112:115], v[124:127], v[84:99]
	s_waitcnt lgkmcnt(0)
	v_mfma_f32_32x32x16_bf16 v[68:83], v[112:115], v[154:157], v[68:83]
	ds_read_b128 v[112:115], v145 offset:160
	ds_read_b128 v[116:119], v145 offset:8864
	ds_read_b128 v[120:123], v145 offset:34976
	ds_read_b128 v[124:127], v145 offset:43680
	s_waitcnt lgkmcnt(3)
	v_mfma_f32_32x32x16_bf16 v[52:67], v[108:111], v[112:115], v[52:67]
	s_waitcnt lgkmcnt(2)
	v_mfma_f32_32x32x16_bf16 v[36:51], v[108:111], v[116:119], v[36:51]
	s_waitcnt lgkmcnt(1)
	v_mfma_f32_32x32x16_bf16 v[84:99], v[108:111], v[120:123], v[84:99]
	s_waitcnt lgkmcnt(0)
	v_mfma_f32_32x32x16_bf16 v[68:83], v[108:111], v[124:127], v[68:83]
	ds_read_b128 v[108:111], v145 offset:192
	ds_read_b128 v[112:115], v145 offset:8896
	ds_read_b128 v[116:119], v145 offset:35008
	ds_read_b128 v[120:123], v145 offset:43712
	s_waitcnt lgkmcnt(3)
	v_mfma_f32_32x32x16_bf16 v[52:67], v[104:107], v[108:111], v[52:67]
	s_waitcnt lgkmcnt(2)
	v_mfma_f32_32x32x16_bf16 v[36:51], v[104:107], v[112:115], v[36:51]
	s_waitcnt lgkmcnt(1)
	v_mfma_f32_32x32x16_bf16 v[84:99], v[104:107], v[116:119], v[84:99]
	s_waitcnt lgkmcnt(0)
	v_mfma_f32_32x32x16_bf16 v[68:83], v[104:107], v[120:123], v[68:83]
	ds_read_b128 v[104:107], v145 offset:224
	ds_read_b128 v[108:111], v145 offset:8928
	ds_read_b128 v[112:115], v145 offset:35040
	ds_read_b128 v[116:119], v145 offset:43744
	s_waitcnt lgkmcnt(0)
	s_barrier
	s_waitcnt lgkmcnt(3)
	v_mfma_f32_32x32x16_bf16 v[52:67], v[100:103], v[104:107], v[52:67]
	s_waitcnt lgkmcnt(2)
	v_mfma_f32_32x32x16_bf16 v[36:51], v[100:103], v[108:111], v[36:51]
	s_waitcnt lgkmcnt(1)
	v_mfma_f32_32x32x16_bf16 v[84:99], v[100:103], v[112:115], v[84:99]
	s_waitcnt lgkmcnt(0)
	v_mfma_f32_32x32x16_bf16 v[68:83], v[100:103], v[116:119], v[68:83]
	v_or_b32_e32 v100, s14, v153
	v_sub_u32_e32 v102, 0x80, v100
	v_or_b32_e32 v101, 1, v100
	v_cvt_f32_i32_e32 v102, v102
	v_cvt_f32_i32_e32 v101, v101
	s_movk_i32 s14, 0x210
	v_mul_f32_e64 v102, -v150, v102
	v_mul_f32_e64 v101, -v149, v101
	v_exp_f32_e32 v102, v102
	v_exp_f32_e32 v101, v101
	v_mul_f32_e32 v84, v102, v84
	v_fmac_f32_e32 v84, v101, v52
	v_mul_f32_e32 v52, v102, v68
	v_exp_f32_e32 v68, v150
	v_fmac_f32_e32 v52, v101, v36
	v_exp_f32_e64 v36, -v149
	v_add_f32_e32 v4, v4, v84
	v_mul_f32_e32 v84, v68, v102
	v_add_f32_e32 v20, v20, v52
	v_mul_f32_e32 v52, v36, v101
	v_mul_f32_e32 v85, v84, v85
	v_fmac_f32_e32 v85, v52, v53
	v_mul_f32_e32 v53, v84, v69
	v_fmac_f32_e32 v53, v52, v37
	v_add_f32_e32 v21, v21, v53
	v_add_f32_e32 v53, v150, v150
	v_mul_f32_e32 v37, -2.0, v149
	v_exp_f32_e32 v53, v53
	v_exp_f32_e32 v37, v37
	v_add_f32_e32 v5, v5, v85
	v_mul_f32_e32 v69, v53, v102
	v_mul_f32_e32 v52, v37, v101
	v_mul_f32_e32 v84, v69, v86
	v_fmac_f32_e32 v84, v52, v54
	v_mul_f32_e32 v54, v69, v70
	v_fmac_f32_e32 v54, v52, v38
	v_add_f32_e32 v22, v22, v54
	v_mul_f32_e32 v54, 0x40400000, v150
	v_mul_f32_e32 v38, 0xc0400000, v149
	v_exp_f32_e32 v54, v54
	v_exp_f32_e32 v38, v38
	v_add_f32_e32 v6, v6, v84
	v_mul_f32_e32 v69, v54, v102
	v_mul_f32_e32 v52, v38, v101
	v_mul_f32_e32 v70, v69, v87
	v_fmac_f32_e32 v70, v52, v55
	v_mul_f32_e32 v55, v69, v71
	v_fmac_f32_e32 v55, v52, v39
	v_sub_u32_e32 v52, 0x78, v100
	v_or_b32_e32 v39, 9, v100
	v_cvt_f32_i32_e32 v52, v52
	v_cvt_f32_i32_e32 v39, v39
	v_add_f32_e32 v23, v23, v55
	v_add_f32_e32 v7, v7, v70
	v_mul_f32_e64 v52, -v150, v52
	v_mul_f32_e64 v39, -v149, v39
	v_exp_f32_e32 v52, v52
	v_exp_f32_e32 v39, v39
	v_mul_f32_e32 v55, v52, v88
	v_fmac_f32_e32 v55, v39, v56
	v_add_f32_e32 v8, v8, v55
	v_mul_f32_e32 v55, v52, v72
	v_fmac_f32_e32 v55, v39, v40
	v_add_f32_e32 v24, v24, v55
	v_mul_f32_e32 v55, v68, v52
	v_mul_f32_e32 v40, v36, v39
	v_mul_f32_e32 v56, v55, v89
	v_mul_f32_e32 v55, v55, v73
	v_fmac_f32_e32 v55, v40, v41
	v_mul_f32_e32 v41, v53, v52
	v_fmac_f32_e32 v56, v40, v57
	v_add_f32_e32 v25, v25, v55
	v_mul_f32_e32 v40, v37, v39
	v_mul_f32_e32 v55, v41, v90
	v_mul_f32_e32 v41, v41, v74
	v_fmac_f32_e32 v55, v40, v58
	v_fmac_f32_e32 v41, v40, v42
	v_mul_f32_e32 v40, v54, v52
	v_add_f32_e32 v26, v26, v41
	v_mul_f32_e32 v39, v38, v39
	v_mul_f32_e32 v41, v40, v91
	v_mul_f32_e32 v40, v40, v75
	v_fmac_f32_e32 v40, v39, v43
	v_add_f32_e32 v27, v27, v40
	v_sub_u32_e32 v40, 0x70, v100
	v_fmac_f32_e32 v41, v39, v59
	v_or_b32_e32 v39, 17, v100
	v_cvt_f32_i32_e32 v40, v40
	v_cvt_f32_i32_e32 v39, v39
	v_add_f32_e32 v11, v11, v41
	v_add_f32_e32 v9, v9, v56
	v_mul_f32_e64 v40, -v150, v40
; __device__ __forceinline__ int crow(int r,int hi){return (r&3)+8*(r>>2)+4*hi;}
; #define RLAS __attribute__((address_space(3)))
; __device__ __forceinline__ void out_prefetch(OutRegs& R, int b, int h, int c, const bf16_t* QR, const bf16_t* KR, const bf16_t* VR) {
;     int tid_ = threadIdx.x; asm volatile("" : "+v"(tid_));
;     const int grow = (tid_ >> 6) * 16 + ((tid_ >> 4) & 3), gch = tid_ & 15; const size_t tok0 = (size_t)b * SEQ + (size_t)c * 128;
;     const bf16_t* kp = KR + (tok0 + grow) * 512 + h * 128 + gch * 8; const bf16_t* vp = VR + (tok0 + grow) * 512 + h * 128 + gch * 8; const bf16_t* qp = QR + (tok0 + grow) * QRP + h * 128 + gch * 8;
; #pragma unroll
; __device__ __forceinline__ void out_unit(RLAS unsigned char* L, int b, int h, int c, const bf16_t* QR, bf16_t* PR, const bf16_t* KR, const bf16_t* VR, const bf16_t* GR, const bf16_t* ST, size_t stbatch, const float* gnw, float lgf, float lgb, OutRegs& PF, bool is_first, bool has_next, int nb, int nh ...
;     ...
;       for (int q4 = 0; q4 < 4; ++q4) { const int il0 = 32 * ib + 8 * q4 + 4 * h2;
;           const float sf0 = __builtin_amdgcn_exp2f(lgf * (float)(il0 + 1)), sb0 = __builtin_amdgcn_exp2f(lgb * (float)(128 - il0));
; #pragma unroll
;           for (int e = 0; e < 4; ++e) { const float sf = e ? sf0 * __builtin_amdgcn_exp2f(lgf * (float)e) : sf0, sb = e ? sb0 * __builtin_amdgcn_exp2f(-lgb * (float)e) : sb0; const int g = 4 * q4 + e;
; #pragma unroll
;               for (int t = 0; t < 2; ++t) Z[t][g] += sf * Yf[t][g] + sb * Yb[t][g]; } } }
;     LBAR();
;     { RLAS float* Os = (RLAS float*)L;
; #pragma unroll
;       for (int t = 0; t < 2; ++t)
; #pragma unroll
;           for (int g = 0; g < 16; ++g) Os[(32 * ib + crow(g, h2)) * OS + 64 * dvh + 32 * t + r] = Z[t][g]; }
;     LBAR();
;     asm volatile("" ::: "memory"); __builtin_amdgcn_sched_barrier(0);
;     f32x4 w0 = *(const f32x4*)(gnw + h * 128 + gch * 8), w1 = *(const f32x4*)(gnw + h * 128 + gch * 8 + 4);
;     asm volatile("" : "+v"(w0), "+v"(w1));
;     out_prefetch(PF, has_next ? nb : b, has_next ? nh : h, has_next ? nc : c, QR, KR, VR);
;     { const int cb = h * 128 + gch * 8;
;       f32x4 o[4][2]; float sm[4], vq[4];
; #pragma unroll
;       for (int i = 0; i < 4; ++i) { const RLAS float* Os = (const RLAS float*)L + (grow + 4 * i) * OS + gch * 8; o[i][0] = *(const RLAS f32x4*)Os; o[i][1] = *(const RLAS f32x4*)(Os + 4);
	v_mul_f32_e64 v39, -v149, v39
	v_exp_f32_e32 v40, v40
	v_exp_f32_e32 v39, v39
	v_add_f32_e32 v10, v10, v55
	v_mul_f32_e32 v41, v40, v92
	v_fmac_f32_e32 v41, v39, v60
	v_add_f32_e32 v12, v12, v41
	v_mul_f32_e32 v41, v40, v76
	v_fmac_f32_e32 v41, v39, v44
	v_mul_f32_e32 v42, v68, v40
	v_add_f32_e32 v28, v28, v41
	v_mul_f32_e32 v41, v36, v39
	v_mul_f32_e32 v43, v42, v93
	v_mul_f32_e32 v42, v42, v77
	v_fmac_f32_e32 v42, v41, v45
	v_fmac_f32_e32 v43, v41, v61
	v_add_f32_e32 v29, v29, v42
	v_mul_f32_e32 v42, v53, v40
	v_add_f32_e32 v13, v13, v43
	v_mul_f32_e32 v41, v37, v39
	v_mul_f32_e32 v43, v42, v94
	v_mul_f32_e32 v42, v42, v78
	v_mul_f32_e32 v40, v54, v40
	v_fmac_f32_e32 v43, v41, v62
	v_fmac_f32_e32 v42, v41, v46
	v_mul_f32_e32 v39, v38, v39
	v_mul_f32_e32 v41, v40, v95
	v_mul_f32_e32 v40, v40, v79
	v_fmac_f32_e32 v40, v39, v47
	v_add_f32_e32 v31, v31, v40
	v_sub_u32_e32 v40, 0x68, v100
	v_fmac_f32_e32 v41, v39, v63
	v_or_b32_e32 v39, 25, v100
	v_cvt_f32_i32_e32 v40, v40
	v_cvt_f32_i32_e32 v39, v39
	v_add_f32_e32 v15, v15, v41
	v_add_f32_e32 v30, v30, v42
	v_mul_f32_e64 v40, -v150, v40
	v_mul_f32_e64 v39, -v149, v39
	v_exp_f32_e32 v40, v40
	v_exp_f32_e32 v39, v39
	v_add_f32_e32 v14, v14, v43
	v_mul_f32_e32 v41, v40, v96
	v_fmac_f32_e32 v41, v39, v64
	v_add_f32_e32 v16, v16, v41
	v_mul_f32_e32 v41, v40, v80
	v_fmac_f32_e32 v41, v39, v48
	v_add_f32_e32 v32, v32, v41
	v_mul_f32_e32 v41, v68, v40
	v_mul_f32_e32 v36, v36, v39
	v_mul_f32_e32 v42, v41, v97
	v_mul_f32_e32 v41, v41, v81
	v_fmac_f32_e32 v42, v36, v65
	v_fmac_f32_e32 v41, v36, v49
	v_mul_f32_e32 v36, v37, v39
	v_mul_f32_e32 v37, v53, v40
	v_add_f32_e32 v33, v33, v41
	v_mul_f32_e32 v41, v37, v98
	v_mul_f32_e32 v37, v37, v82
	v_fmac_f32_e32 v37, v36, v50
	v_add_f32_e32 v34, v34, v37
	v_mul_f32_e32 v37, v54, v40
	v_fmac_f32_e32 v41, v36, v66
	v_mul_f32_e32 v36, v38, v39
	v_mul_f32_e32 v38, v37, v99
	v_mul_f32_e32 v37, v37, v83
	v_fmac_f32_e32 v37, v36, v51
	v_fmac_f32_e32 v38, v36, v67
	v_add_f32_e32 v35, v35, v37
	v_lshlrev_b32_e32 v36, 2, v151
	v_mul_lo_u32 v37, v100, s14
	v_add3_u32 v36, s1, v36, v37
	ds_write2_b32 v36, v4, v20 offset1:32
	ds_write2_b32 v36, v5, v21 offset0:132 offset1:164
	v_add_u32_e32 v4, 0x400, v36
	ds_write2_b32 v4, v6, v22 offset0:8 offset1:40
	ds_write2_b32 v4, v7, v23 offset0:140 offset1:172
	v_add_u32_e32 v4, 0x1000, v36
	ds_write2_b32 v4, v8, v24 offset0:32 offset1:64
	ds_write2_b32 v4, v9, v25 offset0:164 offset1:196
	v_add_u32_e32 v4, 0x1400, v36
	ds_write2_b32 v4, v10, v26 offset0:40 offset1:72
	ds_write2_b32 v4, v11, v27 offset0:172 offset1:204
	v_add_u32_e32 v4, 0x2000, v36
	ds_write2_b32 v4, v12, v28 offset0:64 offset1:96
	ds_write2_b32 v4, v13, v29 offset0:196 offset1:228
	v_add_u32_e32 v4, 0x2400, v36
	ds_write2_b32 v4, v14, v30 offset0:72 offset1:104
	ds_write2_b32 v4, v15, v31 offset0:204 offset1:236
	v_add_u32_e32 v4, 0x3000, v36
	v_add_f32_e32 v17, v17, v42
	ds_write2_b32 v4, v16, v32 offset0:96 offset1:128
	v_add_u32_e32 v4, 0x3200, v36
	v_add_f32_e32 v18, v18, v41
	ds_write2_b32 v4, v17, v33 offset0:100 offset1:132
	v_add_u32_e32 v4, 0x3400, v36
	v_add_f32_e32 v19, v19, v38
	ds_write2_b32 v4, v18, v34 offset0:104 offset1:136
	v_add_u32_e32 v4, 0x3600, v36
	ds_write2_b32 v4, v19, v35 offset0:108 offset1:140
	s_waitcnt lgkmcnt(0)
	s_barrier
	v_lshlrev_b32_e32 v60, 5, v148
	s_cselect_b32 s0, s21, s0
	v_mov_b32_e32 v10, v0
	s_cselect_b32 s4, s22, s15
	s_cselect_b32 s5, s23, s20
	s_ashr_i32 s1, s0, 31
	s_lshl_b64 s[0:1], s[0:1], 12
	s_lshl_b32 s5, s5, 7
	s_or_b32 s0, s0, s5
	v_mov_b32_e32 v11, v3
	v_mul_lo_u32 v61, v144, s14
	v_add3_u32 v92, 0, v60, v61
	v_or_b32_e32 v2, s16, v2
	s_add_i32 s12, s12, 1
	s_add_i32 s13, s13, s3
	s_waitcnt vmcnt(0)
	v_mov_b64_e32 v[52:53], v[172:173]
	v_mov_b64_e32 v[54:55], v[174:175]
	v_mov_b64_e32 v[56:57], v[176:177]
	v_mov_b64_e32 v[58:59], v[178:179]
	s_nop 0
	v_ashrrev_i32_e32 v4, 2, v10
	v_bfe_u32 v5, v10, 4, 2
	v_and_or_b32 v4, v4, -16, v5
	v_ashrrev_i32_e32 v5, 31, v4
	v_lshl_add_u64 v[4:5], s[0:1], 0, v[4:5]
	v_lshlrev_b64 v[6:7], 10, v[4:5]
	v_lshlrev_b64 v[4:5], 11, v[4:5]
	s_lshl_b32 s0, s4, 8
	s_mov_b32 s1, s17
	v_lshlrev_b32_e32 v10, 4, v10
	v_lshl_add_u64 v[4:5], s[82:83], 0, v[4:5]
	v_and_b32_e32 v10, 0xf0, v10
	v_lshl_add_u64 v[4:5], v[4:5], 0, s[0:1]
	v_lshl_add_u64 v[8:9], s[92:93], 0, v[6:7]
	v_readlane_b32 s4, v252, 30
	v_lshl_add_u64 v[24:25], v[4:5], 0, v[10:11]
	v_lshl_add_u64 v[8:9], v[8:9], 0, s[0:1]
	v_readlane_b32 s5, v252, 31
	v_add_co_u32_e32 v12, vcc, s7, v24
	v_lshl_add_u64 v[44:45], v[8:9], 0, v[10:11]
	v_lshl_add_u64 v[6:7], s[4:5], 0, v[6:7]
	v_addc_co_u32_e32 v13, vcc, 0, v25, vcc
	v_lshl_add_u64 v[6:7], v[6:7], 0, s[0:1]
	v_add_co_u32_e32 v26, vcc, s7, v44
	v_lshl_add_u64 v[46:47], v[6:7], 0, v[10:11]
	s_nop 0
	v_addc_co_u32_e32 v27, vcc, 0, v45, vcc
	v_add_co_u32_e32 v36, vcc, s7, v46
	global_load_dwordx4 v[16:19], v[24:25], off
	global_load_dwordx4 v[4:7], v[44:45], off
	global_load_dwordx4 v[8:11], v[46:47], off
	v_addc_co_u32_e32 v37, vcc, 0, v47, vcc
	v_add_co_u32_e32 v32, vcc, s6, v24
	s_movk_i32 s0, 0x3000
	s_nop 0
	v_addc_co_u32_e32 v33, vcc, 0, v25, vcc
	v_add_co_u32_e32 v24, vcc, s27, v24
	global_load_dwordx4 v[12:15], v[12:13], off
	s_nop 0
	v_addc_co_u32_e32 v25, vcc, 0, v25, vcc
	v_add_co_u32_e32 v44, vcc, s0, v44
	global_load_dwordx4 v[20:23], v[26:27], off offset:-4096
	s_nop 0
	v_addc_co_u32_e32 v45, vcc, 0, v45, vcc
	global_load_dwordx4 v[28:31], v[36:37], off offset:-4096
	global_load_dwordx4 v[40:43], v[32:33], off
	s_nop 0
	global_load_dwordx4 v[32:35], v[26:27], off
	s_nop 0
	global_load_dwordx4 v[36:39], v[36:37], off
	s_nop 0
	global_load_dwordx4 v[24:27], v[24:25], off
	s_nop 0
	global_load_dwordx4 v[48:51], v[44:45], off
	v_add_co_u32_e32 v44, vcc, s0, v46
	s_mov_b32 s0, 0x358637bd
	s_nop 0
	v_addc_co_u32_e32 v45, vcc, 0, v47, vcc
	global_load_dwordx4 v[44:47], v[44:45], off
	ds_read_b128 v[80:83], v92
	ds_read_b128 v[76:79], v92 offset:16
	ds_read_b128 v[88:91], v92 offset:2112
	ds_read_b128 v[84:87], v92 offset:2128
	ds_read_b128 v[72:75], v92 offset:4224
	ds_read_b128 v[68:71], v92 offset:4240
	s_waitcnt lgkmcnt(5)
; #define RLAS __attribute__((address_space(3)))
; __device__ __forceinline__ void out_unit(RLAS unsigned char* L, int b, int h, int c, const bf16_t* QR, bf16_t* PR, const bf16_t* KR, const bf16_t* VR, const bf16_t* GR, const bf16_t* ST, size_t stbatch, const float* gnw, float lgf, float lgb, OutRegs& PF, bool is_first, bool has_next, int nb, int nh ...
;     ...
;     { const int cb = h * 128 + gch * 8;
;       f32x4 o[4][2]; float sm[4], vq[4];
; #pragma unroll
;       for (int i = 0; i < 4; ++i) { const RLAS float* Os = (const RLAS float*)L + (grow + 4 * i) * OS + gch * 8; o[i][0] = *(const RLAS f32x4*)Os; o[i][1] = *(const RLAS f32x4*)(Os + 4);
;           sm[i] = ((o[i][0][0] + o[i][0][1]) + (o[i][0][2] + o[i][0][3])) + ((o[i][1][0] + o[i][1][1]) + (o[i][1][2] + o[i][1][3])); }
; #pragma unroll
;       for (int i = 0; i < 4; ++i) sm[i] = row16_sum(sm[i]);
; #pragma unroll
;       for (int i = 0; i < 4; ++i) { const float mean = sm[i] * (1.f / 128.f); o[i][0] = o[i][0] - mean; o[i][1] = o[i][1] - mean;
;           vq[i] = ((o[i][0][0] * o[i][0][0] + o[i][0][1] * o[i][0][1]) + (o[i][0][2] * o[i][0][2] + o[i][0][3] * o[i][0][3])) + ((o[i][1][0] * o[i][1][0] + o[i][1][1] * o[i][1][1]) + (o[i][1][2] * o[i][1][2] + o[i][1][3] * o[i][1][3])); }
; #pragma unroll
;       for (int i = 0; i < 4; ++i) vq[i] = row16_sum(vq[i]);
	v_mov_b32_e32 v60, v80
	s_waitcnt lgkmcnt(4)
	v_mov_b32_e32 v61, v76
	v_mov_b32_e32 v62, v81
	v_mov_b32_e32 v63, v77
	v_pk_add_f32 v[60:61], v[60:61], v[62:63]
	v_mov_b32_e32 v62, v82
	v_mov_b32_e32 v63, v78
	v_mov_b32_e32 v64, v83
	v_mov_b32_e32 v65, v79
	v_pk_add_f32 v[62:63], v[62:63], v[64:65]
	s_waitcnt lgkmcnt(3)
	v_mov_b32_e32 v64, v91
	v_pk_add_f32 v[60:61], v[60:61], v[62:63]
	v_mov_b32_e32 v62, v89
	v_add_f32_e32 v98, v60, v61
	v_mov_b32_e32 v60, v88
	s_waitcnt lgkmcnt(2)
	v_mov_b32_e32 v61, v84
	v_mov_b32_e32 v63, v85
	v_pk_add_f32 v[60:61], v[60:61], v[62:63]
	v_mov_b32_e32 v62, v90
	v_mov_b32_e32 v63, v86
	v_mov_b32_e32 v65, v87
	v_pk_add_f32 v[62:63], v[62:63], v[64:65]
	s_waitcnt lgkmcnt(1)
	v_mov_b32_e32 v64, v75
	v_pk_add_f32 v[60:61], v[60:61], v[62:63]
	v_mov_b32_e32 v62, v73
	v_add_f32_e32 v99, v60, v61
	v_mov_b32_e32 v60, v72
	s_waitcnt lgkmcnt(0)
	v_mov_b32_e32 v61, v68
	v_mov_b32_e32 v63, v69
	v_pk_add_f32 v[60:61], v[60:61], v[62:63]
	v_mov_b32_e32 v62, v74
	v_mov_b32_e32 v63, v70
	v_mov_b32_e32 v65, v71
	v_pk_add_f32 v[62:63], v[62:63], v[64:65]
	s_nop 0
	v_pk_add_f32 v[60:61], v[60:61], v[62:63]
	s_nop 0
	v_add_f32_e32 v100, v60, v61
	ds_read_b128 v[64:67], v92 offset:6336
	ds_read_b128 v[60:63], v92 offset:6352
	s_waitcnt lgkmcnt(1)
	v_mov_b32_e32 v92, v64
	s_waitcnt lgkmcnt(0)
	v_mov_b32_e32 v93, v60
	v_mov_b32_e32 v94, v65
	v_mov_b32_e32 v95, v61
	v_pk_add_f32 v[92:93], v[92:93], v[94:95]
	v_mov_b32_e32 v94, v66
	v_mov_b32_e32 v95, v62
	v_mov_b32_e32 v96, v67
	v_mov_b32_e32 v97, v63
	v_pk_add_f32 v[94:95], v[94:95], v[96:97]
	s_nop 0
	v_pk_add_f32 v[92:93], v[92:93], v[94:95]
	v_add_f32_dpp v94, v99, v99 quad_perm:[1,0,3,2] row_mask:0xf bank_mask:0xf bound_ctrl:1
	v_add_f32_e32 v92, v92, v93
	v_add_f32_dpp v93, v98, v98 quad_perm:[1,0,3,2] row_mask:0xf bank_mask:0xf bound_ctrl:1
	v_add_f32_dpp v94, v94, v94 quad_perm:[2,3,0,1] row_mask:0xf bank_mask:0xf bound_ctrl:1
	v_add_f32_dpp v92, v92, v92 quad_perm:[1,0,3,2] row_mask:0xf bank_mask:0xf bound_ctrl:1
	v_add_f32_dpp v93, v93, v93 quad_perm:[2,3,0,1] row_mask:0xf bank_mask:0xf bound_ctrl:1
	v_add_f32_dpp v94, v94, v94 row_half_mirror row_mask:0xf bank_mask:0xf bound_ctrl:1
	v_add_f32_dpp v92, v92, v92 quad_perm:[2,3,0,1] row_mask:0xf bank_mask:0xf bound_ctrl:1
	v_add_f32_dpp v93, v93, v93 row_half_mirror row_mask:0xf bank_mask:0xf bound_ctrl:1
	v_add_f32_dpp v102, v94, v94 row_mirror row_mask:0xf bank_mask:0xf bound_ctrl:1
	v_add_f32_dpp v92, v92, v92 row_half_mirror row_mask:0xf bank_mask:0xf bound_ctrl:1
	v_add_f32_dpp v93, v93, v93 row_mirror row_mask:0xf bank_mask:0xf bound_ctrl:1
	v_fmamk_f32 v81, v93, 0xbc000000, v81
	v_fmamk_f32 v77, v93, 0xbc000000, v77
	v_fmamk_f32 v99, v93, 0xbc000000, v83
	v_fmamk_f32 v98, v93, 0xbc000000, v82
	v_fmac_f32_e32 v80, 0xbc000000, v93
	v_fmamk_f32 v97, v93, 0xbc000000, v79
	v_fmac_f32_e32 v76, 0xbc000000, v93
	v_mov_b32_e32 v82, v81
	v_mov_b32_e32 v83, v77
	v_add_f32_dpp v104, v92, v92 row_mirror row_mask:0xf bank_mask:0xf bound_ctrl:1
	v_fmamk_f32 v96, v93, 0xbc000000, v78
	v_mov_b32_e32 v78, v80
	v_mov_b32_e32 v79, v76
	v_pk_mul_f32 v[82:83], v[82:83], v[82:83]
	v_mov_b32_e32 v92, v99
	v_mov_b32_e32 v93, v97
	v_add_f32_dpp v94, v100, v100 quad_perm:[1,0,3,2] row_mask:0xf bank_mask:0xf bound_ctrl:1
	v_pk_fma_f32 v[78:79], v[78:79], v[78:79], v[82:83]
	v_mov_b32_e32 v82, v98
	v_mov_b32_e32 v83, v96
	v_pk_mul_f32 v[92:93], v[92:93], v[92:93]
	v_add_f32_dpp v94, v94, v94 quad_perm:[2,3,0,1] row_mask:0xf bank_mask:0xf bound_ctrl:1
	v_pk_fma_f32 v[82:83], v[82:83], v[82:83], v[92:93]
	v_fmamk_f32 v89, v102, 0xbc000000, v89
	v_fmamk_f32 v85, v102, 0xbc000000, v85
	v_add_f32_dpp v94, v94, v94 row_half_mirror row_mask:0xf bank_mask:0xf bound_ctrl:1
	v_pk_add_f32 v[100:101], v[78:79], v[82:83]
	v_fmamk_f32 v93, v102, 0xbc000000, v91
	v_fmac_f32_e32 v88, 0xbc000000, v102
	v_fmamk_f32 v95, v102, 0xbc000000, v87
	v_fmac_f32_e32 v84, 0xbc000000, v102
	v_mov_b32_e32 v82, v89
	v_mov_b32_e32 v83, v85
	v_add_f32_dpp v103, v94, v94 row_mirror row_mask:0xf bank_mask:0xf bound_ctrl:1
	v_fmamk_f32 v92, v102, 0xbc000000, v90
	v_fmamk_f32 v94, v102, 0xbc000000, v86
	v_mov_b32_e32 v78, v88
	v_mov_b32_e32 v79, v84
	v_pk_mul_f32 v[82:83], v[82:83], v[82:83]
	v_mov_b32_e32 v86, v93
	v_mov_b32_e32 v87, v95
	v_pk_fma_f32 v[78:79], v[78:79], v[78:79], v[82:83]
	v_mov_b32_e32 v82, v92
	v_mov_b32_e32 v83, v94
	v_pk_mul_f32 v[86:87], v[86:87], v[86:87]
	v_fmamk_f32 v73, v103, 0xbc000000, v73
	v_pk_fma_f32 v[82:83], v[82:83], v[82:83], v[86:87]
	v_fmamk_f32 v69, v103, 0xbc000000, v69
	v_pk_add_f32 v[90:91], v[78:79], v[82:83]
	v_fmamk_f32 v75, v103, 0xbc000000, v75
	v_fmac_f32_e32 v72, 0xbc000000, v103
	v_fmamk_f32 v79, v103, 0xbc000000, v71
	v_fmac_f32_e32 v68, 0xbc000000, v103
	v_mov_b32_e32 v82, v73
	v_mov_b32_e32 v83, v69
	v_fmamk_f32 v74, v103, 0xbc000000, v74
	v_fmamk_f32 v78, v103, 0xbc000000, v70
	v_mov_b32_e32 v70, v72
	v_mov_b32_e32 v71, v68
	v_pk_mul_f32 v[82:83], v[82:83], v[82:83]
	v_mov_b32_e32 v86, v75
	v_mov_b32_e32 v87, v79
	v_pk_fma_f32 v[70:71], v[70:71], v[70:71], v[82:83]
	v_mov_b32_e32 v82, v74
	v_mov_b32_e32 v83, v78
	v_pk_mul_f32 v[86:87], v[86:87], v[86:87]
	v_fmamk_f32 v65, v104, 0xbc000000, v65
	v_pk_fma_f32 v[82:83], v[82:83], v[82:83], v[86:87]
	v_fmamk_f32 v61, v104, 0xbc000000, v61
	v_pk_add_f32 v[82:83], v[70:71], v[82:83]
	v_fmamk_f32 v67, v104, 0xbc000000, v67
	v_fmac_f32_e32 v64, 0xbc000000, v104
	v_fmamk_f32 v71, v104, 0xbc000000, v63
	v_fmac_f32_e32 v60, 0xbc000000, v104
	v_mov_b32_e32 v86, v65
	v_mov_b32_e32 v87, v61
	v_fmamk_f32 v66, v104, 0xbc000000, v66
	v_fmamk_f32 v70, v104, 0xbc000000, v62
	v_mov_b32_e32 v62, v64
;       #define SILU_(x) ((x)*__builtin_amdgcn_rcpf(1.f+__builtin_amdgcn_exp2f(-1.4426950408889634f*(x))))
; __device__ __forceinline__ unsigned pkbf(float lo, float hi) { const f32x2r v = {lo, hi}; return __builtin_bit_cast(unsigned, __builtin_convertvector(v, bf16x2r)); }
; #define SILU_(x) ((x) * __builtin_amdgcn_rcpf(1.f + __builtin_amdgcn_exp2f(-1.4426950408889634f * (x))))
; __device__ __forceinline__ void out_unit(RLAS unsigned char* L, int b, int h, int c, const bf16_t* QR, bf16_t* PR, const bf16_t* KR, const bf16_t* VR, const bf16_t* GR, const bf16_t* ST, size_t stbatch, const float* gnw, float lgf, float lgb, OutRegs& PF, bool is_first, bool has_next, int nb, int nh ...
;     ...
;       for (int i = 0; i < 4; ++i) sm[i] = row16_sum(sm[i]);
; #pragma unroll
;       for (int i = 0; i < 4; ++i) { const float mean = sm[i] * (1.f / 128.f); o[i][0] = o[i][0] - mean; o[i][1] = o[i][1] - mean;
;           vq[i] = ((o[i][0][0] * o[i][0][0] + o[i][0][1] * o[i][0][1]) + (o[i][0][2] * o[i][0][2] + o[i][0][3] * o[i][0][3])) + ((o[i][1][0] * o[i][1][0] + o[i][1][1] * o[i][1][1]) + (o[i][1][2] * o[i][1][2] + o[i][1][3] * o[i][1][3])); }
; #pragma unroll
;       for (int i = 0; i < 4; ++i) vq[i] = row16_sum(vq[i]);
;       bf16_t* op = PR + (tok0 + grow) * QRP + cb;
; #pragma unroll
;       for (int i = 0; i < 4; ++i) { const float rstd = rsqrtf(vq[i] * (1.f / 128.f) + EPS); const u32x4 gw = gwr[i];
;           const f32x4 a0 = o[i][0] * rstd * w0, a1 = o[i][1] * rstd * w1; u32x4 ow;
;     ...
;           const float g0 = __uint_as_float(gw.x << 16), g1 = __uint_as_float(gw.x & 0xffff0000u), g2 = __uint_as_float(gw.y << 16), g3 = __uint_as_float(gw.y & 0xffff0000u), g4 = __uint_as_float(gw.z << 16), g5 = __uint_as_float(gw.z & 0xffff0000u), g6 = __uint_as_float(gw.w << 16), g7 = __uint_as_float(gw.w & 0xffff0000u);
;           ow.x = pkbf(a0[0] * SILU_(g0), a0[1] * SILU_(g1)); ow.y = pkbf(a0[2] * SILU_(g2), a0[3] * SILU_(g3));
;           ow.z = pkbf(a1[0] * SILU_(g4), a1[1] * SILU_(g5)); ow.w = pkbf(a1[2] * SILU_(g6), a1[3] * SILU_(g7));
;     ...
;           *(u32x4*)(op + (size_t)(4 * i) * QRP) = ow; } }
	v_mov_b32_e32 v63, v60
	v_pk_mul_f32 v[86:87], v[86:87], v[86:87]
	v_mov_b32_e32 v102, v67
	v_mov_b32_e32 v103, v71
	v_pk_fma_f32 v[62:63], v[62:63], v[62:63], v[86:87]
	v_mov_b32_e32 v86, v66
	v_mov_b32_e32 v87, v70
	v_pk_mul_f32 v[102:103], v[102:103], v[102:103]
	s_nop 0
	v_pk_fma_f32 v[86:87], v[86:87], v[86:87], v[102:103]
	v_lshlrev_b32_e32 v102, 16, v140
	v_pk_add_f32 v[86:87], v[62:63], v[86:87]
	v_lshl_add_u64 v[62:63], s[82:83], 0, v[146:147]
	v_lshl_add_u64 v[62:63], v[62:63], 0, v[2:3]
	v_mul_f32_e32 v2, 0xbfb8aa3b, v102
	v_exp_f32_e32 v2, v2
	v_and_b32_e32 v103, 0xffff0000, v140
	v_add_f32_e32 v2, 1.0, v2
	v_rcp_f32_e32 v104, v2
	v_mul_f32_e32 v2, 0xbfb8aa3b, v103
	v_exp_f32_e32 v2, v2
	s_nop 0
	v_add_f32_e32 v2, 1.0, v2
	v_rcp_f32_e32 v105, v2
	s_nop 0
	v_pk_mul_f32 v[102:103], v[104:105], v[102:103]
	v_lshlrev_b32_e32 v104, 16, v141
	v_mul_f32_e32 v2, 0xbfb8aa3b, v104
	v_exp_f32_e32 v2, v2
	v_and_b32_e32 v105, 0xffff0000, v141
	v_add_f32_e32 v2, 1.0, v2
	v_rcp_f32_e32 v106, v2
	v_mul_f32_e32 v2, 0xbfb8aa3b, v105
	v_exp_f32_e32 v2, v2
	s_nop 0
	v_add_f32_e32 v2, 1.0, v2
	v_rcp_f32_e32 v107, v2
	s_nop 0
	v_pk_mul_f32 v[104:105], v[106:107], v[104:105]
	v_lshlrev_b32_e32 v106, 16, v142
	v_mul_f32_e32 v2, 0xbfb8aa3b, v106
	v_exp_f32_e32 v2, v2
	v_and_b32_e32 v107, 0xffff0000, v142
	v_add_f32_e32 v2, 1.0, v2
	v_rcp_f32_e32 v108, v2
	v_mul_f32_e32 v2, 0xbfb8aa3b, v107
	v_exp_f32_e32 v2, v2
	s_nop 0
	v_add_f32_e32 v2, 1.0, v2
	v_rcp_f32_e32 v109, v2
	s_nop 0
	v_pk_mul_f32 v[106:107], v[108:109], v[106:107]
	v_lshlrev_b32_e32 v108, 16, v143
	v_mul_f32_e32 v2, 0xbfb8aa3b, v108
	v_exp_f32_e32 v2, v2
	v_and_b32_e32 v109, 0xffff0000, v143
	v_add_f32_e32 v2, 1.0, v2
	v_rcp_f32_e32 v110, v2
	v_mul_f32_e32 v2, 0xbfb8aa3b, v109
	v_exp_f32_e32 v2, v2
	s_nop 0
	v_add_f32_e32 v2, 1.0, v2
	v_rcp_f32_e32 v111, v2
	s_nop 0
	v_pk_mul_f32 v[108:109], v[110:111], v[108:109]
	v_mov_b32_e32 v110, v90
	v_mov_b32_e32 v111, v100
	v_mov_b32_e32 v100, v91
	v_pk_add_f32 v[90:91], v[110:111], v[100:101]
	s_nop 1
	v_mov_b32_dpp v101, v91 quad_perm:[1,0,3,2] row_mask:0xf bank_mask:0xf bound_ctrl:1
	v_mov_b32_dpp v100, v90 quad_perm:[1,0,3,2] row_mask:0xf bank_mask:0xf bound_ctrl:1
	v_pk_add_f32 v[90:91], v[90:91], v[100:101]
	s_nop 1
	v_mov_b32_dpp v101, v91 quad_perm:[2,3,0,1] row_mask:0xf bank_mask:0xf bound_ctrl:1
	v_mov_b32_dpp v100, v90 quad_perm:[2,3,0,1] row_mask:0xf bank_mask:0xf bound_ctrl:1
	v_pk_add_f32 v[90:91], v[90:91], v[100:101]
	s_nop 1
	v_mov_b32_dpp v101, v91 row_half_mirror row_mask:0xf bank_mask:0xf bound_ctrl:1
	v_mov_b32_dpp v100, v90 row_half_mirror row_mask:0xf bank_mask:0xf bound_ctrl:1
	v_pk_add_f32 v[90:91], v[90:91], v[100:101]
	s_nop 1
	v_mov_b32_dpp v101, v91 row_mirror row_mask:0xf bank_mask:0xf bound_ctrl:1
	v_mov_b32_dpp v100, v90 row_mirror row_mask:0xf bank_mask:0xf bound_ctrl:1
	v_pk_add_f32 v[100:101], v[90:91], v[100:101]
	v_mov_b64_e32 v[90:91], s[0:1]
	s_brev_b32 s0, 60
	v_pk_fma_f32 v[100:101], v[100:101], s[0:1], v[90:91] op_sel_hi:[1,0,0]
	s_nop 0
	v_mul_f32_e32 v2, 0x4b800000, v101
	v_cmp_gt_f32_e64 s[38:39], s35, v101
	v_cmp_gt_f32_e32 vcc, s35, v100
	s_nop 0
	v_cndmask_b32_e64 v2, v101, v2, s[38:39]
	v_rsq_f32_e32 v2, v2
	s_nop 0
	v_mul_f32_e32 v101, 0x45800000, v2
	v_cndmask_b32_e64 v2, v2, v101, s[38:39]
	v_pk_mul_f32 v[80:81], v[80:81], v[2:3] op_sel_hi:[1,0]
	v_pk_mul_f32 v[98:99], v[98:99], v[2:3] op_sel_hi:[1,0]
	v_pk_mul_f32 v[76:77], v[76:77], v[2:3] op_sel_hi:[1,0]
	v_pk_mul_f32 v[96:97], v[96:97], v[2:3] op_sel_hi:[1,0]
	v_mul_f32_e32 v2, 0x4b800000, v100
	v_cndmask_b32_e32 v2, v100, v2, vcc
	v_rsq_f32_e32 v2, v2
	v_pk_mul_f32 v[80:81], v[56:57], v[80:81]
	v_pk_mul_f32 v[76:77], v[52:53], v[76:77]
	v_pk_mul_f32 v[98:99], v[58:59], v[98:99]
	v_pk_mul_f32 v[110:111], v[54:55], v[96:97]
	v_pk_mul_f32 v[80:81], v[102:103], v[80:81]
	v_pk_mul_f32 v[76:77], v[106:107], v[76:77]
	v_cvt_pk_bf16_f32 v96, v80, v81
	v_pk_mul_f32 v[80:81], v[104:105], v[98:99]
	v_cvt_pk_bf16_f32 v98, v76, v77
	v_pk_mul_f32 v[76:77], v[108:109], v[110:111]
	v_cvt_pk_bf16_f32 v97, v80, v81
	v_cvt_pk_bf16_f32 v99, v76, v77
	v_mul_f32_e32 v76, 0x45800000, v2
	v_cndmask_b32_e32 v2, v2, v76, vcc
	v_pk_mul_f32 v[80:81], v[92:93], v[2:3] op_sel_hi:[1,0]
	v_lshlrev_b32_e32 v92, 16, v136
	v_pk_mul_f32 v[76:77], v[88:89], v[2:3] op_sel_hi:[1,0]
	v_pk_mul_f32 v[84:85], v[84:85], v[2:3] op_sel_hi:[1,0]
	v_pk_mul_f32 v[88:89], v[94:95], v[2:3] op_sel_hi:[1,0]
	v_mul_f32_e32 v2, 0xbfb8aa3b, v92
	v_exp_f32_e32 v2, v2
	v_and_b32_e32 v93, 0xffff0000, v136
	v_pk_mul_f32 v[76:77], v[56:57], v[76:77]
	v_pk_mul_f32 v[80:81], v[58:59], v[80:81]
	v_add_f32_e32 v2, 1.0, v2
	v_rcp_f32_e32 v94, v2
	v_mul_f32_e32 v2, 0xbfb8aa3b, v93
	v_exp_f32_e32 v2, v2
	v_pk_mul_f32 v[84:85], v[52:53], v[84:85]
	v_pk_mul_f32 v[88:89], v[54:55], v[88:89]
	global_store_dwordx4 v[62:63], v[96:99], off
	v_add_f32_e32 v2, 1.0, v2
	v_rcp_f32_e32 v95, v2
	s_nop 0
	v_pk_mul_f32 v[92:93], v[94:95], v[92:93]
	s_nop 0
	v_pk_mul_f32 v[76:77], v[92:93], v[76:77]
	s_nop 0
	v_cvt_pk_bf16_f32 v92, v76, v77
	v_lshlrev_b32_e32 v76, 16, v137
	v_mul_f32_e32 v2, 0xbfb8aa3b, v76
	v_exp_f32_e32 v2, v2
	v_and_b32_e32 v77, 0xffff0000, v137
	v_add_f32_e32 v2, 1.0, v2
	v_rcp_f32_e32 v94, v2
	v_mul_f32_e32 v2, 0xbfb8aa3b, v77
	v_exp_f32_e32 v2, v2
	s_nop 0
	v_add_f32_e32 v2, 1.0, v2
	v_rcp_f32_e32 v95, v2
	s_nop 0
	v_pk_mul_f32 v[76:77], v[94:95], v[76:77]
	s_nop 0
	v_pk_mul_f32 v[76:77], v[76:77], v[80:81]
	s_nop 0
	v_cvt_pk_bf16_f32 v93, v76, v77
	v_lshlrev_b32_e32 v76, 16, v138
	v_mul_f32_e32 v2, 0xbfb8aa3b, v76
	v_exp_f32_e32 v2, v2
	v_and_b32_e32 v77, 0xffff0000, v138
	v_add_f32_e32 v2, 1.0, v2
;       #define SILU_(x) ((x)*__builtin_amdgcn_rcpf(1.f+__builtin_amdgcn_exp2f(-1.4426950408889634f*(x))))
; __device__ __forceinline__ unsigned pkbf(float lo, float hi) { const f32x2r v = {lo, hi}; return __builtin_bit_cast(unsigned, __builtin_convertvector(v, bf16x2r)); }
; #define LBAR() do { asm volatile("s_waitcnt lgkmcnt(0)" ::: "memory"); __builtin_amdgcn_s_barrier(); asm volatile("" ::: "memory"); } while (0)
; #define SILU_(x) ((x) * __builtin_amdgcn_rcpf(1.f + __builtin_amdgcn_exp2f(-1.4426950408889634f * (x))))
; __device__ __forceinline__ void out_unit(RLAS unsigned char* L, int b, int h, int c, const bf16_t* QR, bf16_t* PR, const bf16_t* KR, const bf16_t* VR, const bf16_t* GR, const bf16_t* ST, size_t stbatch, const float* gnw, float lgf, float lgb, OutRegs& PF, bool is_first, bool has_next, int nb, int nh ...
;     ...
;       for (int i = 0; i < 4; ++i) vq[i] = row16_sum(vq[i]);
;       bf16_t* op = PR + (tok0 + grow) * QRP + cb;
; #pragma unroll
;       for (int i = 0; i < 4; ++i) { const float rstd = rsqrtf(vq[i] * (1.f / 128.f) + EPS); const u32x4 gw = gwr[i];
;           const f32x4 a0 = o[i][0] * rstd * w0, a1 = o[i][1] * rstd * w1; u32x4 ow;
;     ...
;           const float g0 = __uint_as_float(gw.x << 16), g1 = __uint_as_float(gw.x & 0xffff0000u), g2 = __uint_as_float(gw.y << 16), g3 = __uint_as_float(gw.y & 0xffff0000u), g4 = __uint_as_float(gw.z << 16), g5 = __uint_as_float(gw.z & 0xffff0000u), g6 = __uint_as_float(gw.w << 16), g7 = __uint_as_float(gw.w & 0xffff0000u);
;           ow.x = pkbf(a0[0] * SILU_(g0), a0[1] * SILU_(g1)); ow.y = pkbf(a0[2] * SILU_(g2), a0[3] * SILU_(g3));
;           ow.z = pkbf(a1[0] * SILU_(g4), a1[1] * SILU_(g5)); ow.w = pkbf(a1[2] * SILU_(g6), a1[3] * SILU_(g7));
;     ...
;           *(u32x4*)(op + (size_t)(4 * i) * QRP) = ow; } }
;     LBAR();
	v_rcp_f32_e32 v80, v2
	v_mul_f32_e32 v2, 0xbfb8aa3b, v77
	v_exp_f32_e32 v2, v2
	s_nop 0
	v_add_f32_e32 v2, 1.0, v2
	v_rcp_f32_e32 v81, v2
	s_nop 0
	v_pk_mul_f32 v[76:77], v[80:81], v[76:77]
	s_nop 0
	v_pk_mul_f32 v[76:77], v[76:77], v[84:85]
	s_nop 0
	v_cvt_pk_bf16_f32 v94, v76, v77
	v_lshlrev_b32_e32 v76, 16, v139
	v_mul_f32_e32 v2, 0xbfb8aa3b, v76
	v_exp_f32_e32 v2, v2
	v_and_b32_e32 v77, 0xffff0000, v139
	v_add_f32_e32 v2, 1.0, v2
	v_rcp_f32_e32 v80, v2
	v_mul_f32_e32 v2, 0xbfb8aa3b, v77
	v_exp_f32_e32 v2, v2
	s_nop 0
	v_add_f32_e32 v2, 1.0, v2
	v_rcp_f32_e32 v81, v2
	s_nop 0
	v_pk_mul_f32 v[76:77], v[80:81], v[76:77]
	s_nop 0
	v_pk_mul_f32 v[76:77], v[76:77], v[88:89]
	s_nop 0
	v_cvt_pk_bf16_f32 v95, v76, v77
	v_add_co_u32_e32 v76, vcc, s7, v62
	s_nop 1
	v_addc_co_u32_e32 v77, vcc, 0, v63, vcc
	global_store_dwordx4 v[76:77], v[92:95], off
	v_lshlrev_b32_e32 v76, 16, v132
	v_mul_f32_e32 v2, 0xbfb8aa3b, v76
	v_exp_f32_e32 v2, v2
	v_and_b32_e32 v77, 0xffff0000, v132
	v_add_f32_e32 v2, 1.0, v2
	v_rcp_f32_e32 v80, v2
	v_mul_f32_e32 v2, 0xbfb8aa3b, v77
	v_exp_f32_e32 v2, v2
	s_nop 0
	v_add_f32_e32 v2, 1.0, v2
	v_rcp_f32_e32 v81, v2
	s_nop 0
	v_pk_mul_f32 v[76:77], v[80:81], v[76:77]
	v_lshlrev_b32_e32 v80, 16, v133
	v_mul_f32_e32 v2, 0xbfb8aa3b, v80
	v_exp_f32_e32 v2, v2
	v_and_b32_e32 v81, 0xffff0000, v133
	v_add_f32_e32 v2, 1.0, v2
	v_rcp_f32_e32 v84, v2
	v_mul_f32_e32 v2, 0xbfb8aa3b, v81
	v_exp_f32_e32 v2, v2
	s_nop 0
	v_add_f32_e32 v2, 1.0, v2
	v_rcp_f32_e32 v85, v2
	s_nop 0
	v_pk_mul_f32 v[80:81], v[84:85], v[80:81]
	v_lshlrev_b32_e32 v84, 16, v134
	v_mul_f32_e32 v2, 0xbfb8aa3b, v84
	v_exp_f32_e32 v2, v2
	v_and_b32_e32 v85, 0xffff0000, v134
	v_add_f32_e32 v2, 1.0, v2
	v_rcp_f32_e32 v88, v2
	v_mul_f32_e32 v2, 0xbfb8aa3b, v85
	v_exp_f32_e32 v2, v2
	s_nop 0
	v_add_f32_e32 v2, 1.0, v2
	v_rcp_f32_e32 v89, v2
	s_nop 0
	v_pk_mul_f32 v[84:85], v[88:89], v[84:85]
	v_lshlrev_b32_e32 v88, 16, v135
	v_mul_f32_e32 v2, 0xbfb8aa3b, v88
	v_exp_f32_e32 v2, v2
	v_and_b32_e32 v89, 0xffff0000, v135
	v_add_f32_e32 v2, 1.0, v2
	v_rcp_f32_e32 v92, v2
	v_mul_f32_e32 v2, 0xbfb8aa3b, v89
	v_exp_f32_e32 v2, v2
	s_nop 0
	v_add_f32_e32 v2, 1.0, v2
	v_rcp_f32_e32 v93, v2
	s_nop 0
	v_pk_mul_f32 v[88:89], v[92:93], v[88:89]
	v_mov_b32_e32 v92, v86
	v_mov_b32_e32 v93, v82
	v_mov_b32_e32 v82, v87
	v_pk_add_f32 v[82:83], v[92:93], v[82:83]
	s_nop 1
	v_mov_b32_dpp v87, v83 quad_perm:[1,0,3,2] row_mask:0xf bank_mask:0xf bound_ctrl:1
	v_mov_b32_dpp v86, v82 quad_perm:[1,0,3,2] row_mask:0xf bank_mask:0xf bound_ctrl:1
	v_pk_add_f32 v[82:83], v[82:83], v[86:87]
	s_nop 1
	v_mov_b32_dpp v87, v83 quad_perm:[2,3,0,1] row_mask:0xf bank_mask:0xf bound_ctrl:1
	v_mov_b32_dpp v86, v82 quad_perm:[2,3,0,1] row_mask:0xf bank_mask:0xf bound_ctrl:1
	v_pk_add_f32 v[82:83], v[82:83], v[86:87]
	s_nop 1
	v_mov_b32_dpp v87, v83 row_half_mirror row_mask:0xf bank_mask:0xf bound_ctrl:1
	v_mov_b32_dpp v86, v82 row_half_mirror row_mask:0xf bank_mask:0xf bound_ctrl:1
	v_pk_add_f32 v[82:83], v[82:83], v[86:87]
	s_nop 1
	v_mov_b32_dpp v87, v83 row_mirror row_mask:0xf bank_mask:0xf bound_ctrl:1
	v_mov_b32_dpp v86, v82 row_mirror row_mask:0xf bank_mask:0xf bound_ctrl:1
	v_pk_add_f32 v[82:83], v[82:83], v[86:87]
	s_nop 0
	v_pk_fma_f32 v[82:83], v[82:83], s[0:1], v[90:91] op_sel_hi:[1,0,0]
	s_mov_b64 s[0:1], 0
	v_mul_f32_e32 v2, 0x4b800000, v83
	v_cmp_gt_f32_e64 s[38:39], s35, v83
	v_cmp_gt_f32_e32 vcc, s35, v82
	s_nop 0
	v_cndmask_b32_e64 v2, v83, v2, s[38:39]
	v_rsq_f32_e32 v2, v2
	s_nop 0
	v_mul_f32_e32 v83, 0x45800000, v2
	v_cndmask_b32_e64 v2, v2, v83, s[38:39]
	v_pk_mul_f32 v[72:73], v[72:73], v[2:3] op_sel_hi:[1,0]
	v_pk_mul_f32 v[74:75], v[74:75], v[2:3] op_sel_hi:[1,0]
	v_pk_mul_f32 v[68:69], v[68:69], v[2:3] op_sel_hi:[1,0]
	v_pk_mul_f32 v[78:79], v[78:79], v[2:3] op_sel_hi:[1,0]
	v_mul_f32_e32 v2, 0x4b800000, v82
	v_pk_mul_f32 v[74:75], v[58:59], v[74:75]
	v_pk_mul_f32 v[72:73], v[56:57], v[72:73]
	v_pk_mul_f32 v[68:69], v[52:53], v[68:69]
	v_cndmask_b32_e32 v2, v82, v2, vcc
	v_pk_mul_f32 v[78:79], v[54:55], v[78:79]
	v_pk_mul_f32 v[72:73], v[76:77], v[72:73]
	v_pk_mul_f32 v[74:75], v[80:81], v[74:75]
	v_pk_mul_f32 v[68:69], v[84:85], v[68:69]
	v_rsq_f32_e32 v2, v2
	v_cvt_pk_bf16_f32 v72, v72, v73
	v_cvt_pk_bf16_f32 v73, v74, v75
	v_cvt_pk_bf16_f32 v74, v68, v69
	v_pk_mul_f32 v[68:69], v[88:89], v[78:79]
	s_nop 0
	v_cvt_pk_bf16_f32 v75, v68, v69
	v_add_co_u32_e64 v68, s[38:39], s6, v62
	s_nop 1
	v_addc_co_u32_e64 v69, s[38:39], 0, v63, s[38:39]
	global_store_dwordx4 v[68:69], v[72:75], off
	v_mul_f32_e32 v68, 0x45800000, v2
	v_cndmask_b32_e32 v2, v2, v68, vcc
	v_pk_mul_f32 v[64:65], v[64:65], v[2:3] op_sel_hi:[1,0]
	v_pk_mul_f32 v[60:61], v[60:61], v[2:3] op_sel_hi:[1,0]
	v_pk_mul_f32 v[56:57], v[56:57], v[64:65]
	v_pk_mul_f32 v[64:65], v[70:71], v[2:3] op_sel_hi:[1,0]
	v_pk_mul_f32 v[66:67], v[66:67], v[2:3] op_sel_hi:[1,0]
	v_pk_mul_f32 v[64:65], v[54:55], v[64:65]
	v_pk_mul_f32 v[54:55], v[52:53], v[60:61]
	v_lshlrev_b32_e32 v52, 16, v128
	v_mul_f32_e32 v2, 0xbfb8aa3b, v52
	v_exp_f32_e32 v2, v2
	v_and_b32_e32 v53, 0xffff0000, v128
	v_pk_mul_f32 v[58:59], v[58:59], v[66:67]
	v_add_f32_e32 v2, 1.0, v2
	v_rcp_f32_e32 v60, v2
	v_mul_f32_e32 v2, 0xbfb8aa3b, v53
	v_exp_f32_e32 v2, v2
	s_nop 0
	v_add_f32_e32 v2, 1.0, v2
	v_rcp_f32_e32 v61, v2
	s_nop 0
	v_pk_mul_f32 v[52:53], v[60:61], v[52:53]
	s_nop 0
	v_pk_mul_f32 v[52:53], v[52:53], v[56:57]
	v_lshlrev_b32_e32 v56, 16, v129
	v_mul_f32_e32 v2, 0xbfb8aa3b, v56
	v_exp_f32_e32 v2, v2
	v_and_b32_e32 v57, 0xffff0000, v129
	v_cvt_pk_bf16_f32 v52, v52, v53
	v_add_f32_e32 v2, 1.0, v2
	v_rcp_f32_e32 v60, v2
	v_mul_f32_e32 v2, 0xbfb8aa3b, v57
	v_exp_f32_e32 v2, v2
	s_nop 0
	v_add_f32_e32 v2, 1.0, v2
	v_rcp_f32_e32 v61, v2
	s_nop 0
	v_pk_mul_f32 v[56:57], v[60:61], v[56:57]
	s_nop 0
	v_pk_mul_f32 v[56:57], v[56:57], v[58:59]
	s_nop 0
	v_cvt_pk_bf16_f32 v53, v56, v57
	v_lshlrev_b32_e32 v56, 16, v130
	v_mul_f32_e32 v2, 0xbfb8aa3b, v56
	v_exp_f32_e32 v2, v2
	v_and_b32_e32 v57, 0xffff0000, v130
	v_add_f32_e32 v2, 1.0, v2
	v_rcp_f32_e32 v58, v2
	v_mul_f32_e32 v2, 0xbfb8aa3b, v57
	v_exp_f32_e32 v2, v2
	s_nop 0
	v_add_f32_e32 v2, 1.0, v2
	v_rcp_f32_e32 v59, v2
	s_nop 0
	v_pk_mul_f32 v[56:57], v[58:59], v[56:57]
	s_nop 0
	v_pk_mul_f32 v[54:55], v[56:57], v[54:55]
	v_lshlrev_b32_e32 v56, 16, v131
	v_mul_f32_e32 v2, 0xbfb8aa3b, v56
	v_exp_f32_e32 v2, v2
	v_and_b32_e32 v57, 0xffff0000, v131
	v_cvt_pk_bf16_f32 v54, v54, v55
	v_add_f32_e32 v2, 1.0, v2
	v_rcp_f32_e32 v58, v2
	v_mul_f32_e32 v2, 0xbfb8aa3b, v57
	v_exp_f32_e32 v2, v2
	s_nop 0
	v_add_f32_e32 v2, 1.0, v2
	v_rcp_f32_e32 v59, v2
	s_nop 0
	v_pk_mul_f32 v[56:57], v[58:59], v[56:57]
	s_nop 0
	v_pk_mul_f32 v[56:57], v[56:57], v[64:65]
	s_nop 0
	v_cvt_pk_bf16_f32 v55, v56, v57
	v_add_co_u32_e32 v56, vcc, 0x6000, v62
	s_nop 1
	v_addc_co_u32_e32 v57, vcc, 0, v63, vcc
	global_store_dwordx4 v[56:57], v[52:55], off
	s_waitcnt lgkmcnt(0)
	s_barrier
